# v71 with the once-read gate-row loads of the FFN-up epilogue marked non-temporal (prompt path, both layers)
# baseline (speedup 1.0000x reference)
;     __device__ __forceinline__ void operator()(const f32x4 (&acc)[2][2][4][2], const Unit& u, int wr, int wc, int fr, int fq) const {
;     ...
;             for (int m = 0; m < 4; ++m) rs8[ai][m] = rsqrtf(SS[u.rb + (u.half ? 0 : ai * HALF) + wr * 64 + fr + 16 * m] * (1.f / 1024.f) + 1e-6f);
;         if (u.pm < 128) {
; #pragma unroll
;           for (int bj = 0; bj < 2; ++bj) {
;             const int col8 = u.pn * BM + bj * HALF + wc * 32 + 8 * fq;
;             float w0[2][4], w1[2][4], w2[2][4], bb[2][4];
; #pragma unroll
;             for (int hv = 0; hv < 2; ++hv) { ld4f(cw + col8 + 4 * hv, w0[hv]); ld4f(cw + 2816 + col8 + 4 * hv, w1[hv]); ld4f(cw + 2 * 2816 + col8 + 4 * hv, w2[hv]); ld4f(cb + col8 + 4 * hv, bb[hv]); }
; #pragma unroll
;             for (int ai = 0; ai < 2; ++ai) { const int R0 = u.rb + ai * HALF + wr * 64; const bf16_t* gp = G + (size_t)(R0 + fr) * 2816 + col8;
;                 u32x4 gq[4], prv = (u32x4){0u, 0u, 0u, 0u};
; #pragma unroll
;                 for (int m = 0; m < 4; ++m) gq[m] = *(const u32x4*)(gp + (size_t)m * 16 * 2816);
;                 if ((R0 & 8191) != 0) prv = *(const u32x4*)(gp - (size_t)16 * 2816);
.LBB0_1009:
	s_andn2_b64 vcc, exec, s[0:1]
	s_cbranch_vccnz .LBB0_1021
	s_and_b64 s[0:1], s[84:85], exec
	s_cselect_b32 s0, 0x80, 0
	v_add_u32_e32 v132, s0, v210
	v_add_u32_e32 v134, 16, v132
	v_ashrrev_i32_e32 v133, 31, v132
	v_ashrrev_i32_e32 v135, 31, v134
	v_lshl_add_u64 v[164:165], v[132:133], 2, s[12:13]
	v_lshl_add_u64 v[166:167], v[134:135], 2, s[12:13]
	v_add_u32_e32 v134, 32, v132
	v_add_u32_e32 v132, 48, v132
	s_lshl_b32 s0, s70, 8
	v_ashrrev_i32_e32 v133, 31, v132
	v_add_u32_e32 v212, s0, v3
	v_lshl_add_u64 v[132:133], v[132:133], 2, s[12:13]
	v_ashrrev_i32_e32 v213, 31, v212
	v_readlane_b32 s0, v240, 19
	global_load_dword v185, v[132:133], off
	v_lshlrev_b64 v[132:133], 2, v[212:213]
	v_readlane_b32 s1, v240, 20
	s_mov_b64 s[68:69], s[54:55]
	v_readlane_b32 s52, v240, 62
	v_lshl_add_u64 v[140:141], s[0:1], 0, v[132:133]
	v_readlane_b32 s0, v240, 21
	v_readlane_b32 s1, v240, 22
	v_readlane_b32 s66, v239, 12
	v_readlane_b32 s67, v239, 13
	v_lshl_add_u64 v[144:145], s[0:1], 0, v[132:133]
	v_readlane_b32 s0, v240, 12
	v_readlane_b32 s1, v240, 13
	v_ashrrev_i32_e32 v135, 31, v134
	v_lshl_add_u64 v[136:137], s[66:67], 0, v[132:133]
	v_mov_b64_e32 v[170:171], s[0:1]
	v_mad_i64_i32 v[214:215], s[0:1], v210, s91, v[170:171]
	v_lshl_add_u64 v[160:161], s[88:89], 0, v[132:133]
	v_lshl_add_u64 v[180:181], v[212:213], 1, v[214:215]
	s_mov_b32 s10, 0x16000
	v_lshl_add_u64 v[168:169], v[134:135], 2, s[12:13]
	global_load_dwordx4 v[132:135], v[136:137], off offset:16
	global_load_dwordx4 v[148:151], v[136:137], off
	s_nop 0
	global_load_dwordx4 v[136:139], v[140:141], off offset:16
	global_load_dwordx4 v[152:155], v[140:141], off
	s_nop 0
	global_load_dwordx4 v[140:143], v[144:145], off offset:16
	global_load_dwordx4 v[156:159], v[144:145], off
	s_nop 0
	global_load_dwordx4 v[144:147], v[160:161], off offset:16
	s_nop 0
	global_load_dwordx4 v[160:163], v[160:161], off
	s_nop 0
	global_load_dword v189, v[164:165], off
	global_load_dword v187, v[166:167], off
	global_load_dword v3, v[168:169], off
	global_load_dwordx4 v[176:179], v[180:181], off nt
	v_add_co_u32_e32 v164, vcc, s10, v180
	s_and_b32 s3, s2, 0x1fff
	s_nop 0
	v_addc_co_u32_e32 v165, vcc, 0, v181, vcc
	v_add_co_u32_e32 v166, vcc, 0x2c000, v180
	s_cmp_lg_u32 s3, 0
	s_nop 0
	v_addc_co_u32_e32 v167, vcc, 0, v181, vcc
	global_load_dwordx4 v[172:175], v[164:165], off nt
	global_load_dwordx4 v[168:171], v[166:167], off nt
	v_add_co_u32_e32 v164, vcc, 0x42000, v180
	s_cselect_b64 s[0:1], -1, 0
	s_nop 0
	v_addc_co_u32_e32 v165, vcc, 0, v181, vcc
	global_load_dwordx4 v[164:167], v[164:165], off nt
	s_cmp_eq_u32 s3, 0
	v_readlane_b32 s53, v240, 63
	v_readlane_b32 s54, v239, 0
	v_readlane_b32 s55, v239, 1
	v_readlane_b32 s56, v239, 2
	v_readlane_b32 s57, v239, 3
	v_readlane_b32 s58, v239, 4
	v_readlane_b32 s59, v239, 5
	v_readlane_b32 s60, v239, 6
	v_readlane_b32 s61, v239, 7
	v_readlane_b32 s62, v239, 8
	v_readlane_b32 s63, v239, 9
	v_readlane_b32 s64, v239, 10
	v_readlane_b32 s65, v239, 11
	s_cbranch_scc1 .LBB0_1012
	v_add_co_u32_e32 v180, vcc, 0xfffea000, v180
	s_nop 1
	v_addc_co_u32_e32 v181, vcc, -1, v181, vcc
	global_load_dwordx4 v[180:183], v[180:181], off nt
	s_branch .LBB0_1013

;     static __device__ __forceinline__ void unpk4(const u32x2 w, float (&o)[4]) { o[0] = bf_lo(w.x); o[1] = bf_hi(w.x); o[2] = bf_lo(w.y); o[3] = bf_hi(w.y); }
;     template <int N> static __device__ __forceinline__ u32x2 dpp_prev(const u32x2 pv, const u32x2 cur) { u32x2 r; r.x = dpp_prev1<N>(pv.x, cur.x); r.y = dpp_prev1<N>(pv.y, cur.y); return r; }
; __device__ __forceinline__ f32x2 gelu_pk(f32x2 v) {
;     f32x2 x = v * 0.70710678118f;
;     x.x = __builtin_amdgcn_fmed3f(x.x, -2.9f, 2.9f); x.y = __builtin_amdgcn_fmed3f(x.y, -2.9f, 2.9f);
;     const f32x2 t = x * x;
;     f32x2 p = t * (-4.953124630e-07f) + 1.987094038e-05f;
;     p = p * t + (-3.472001117e-04f); p = p * t + 3.517547622e-03f; p = p * t + (-2.333305031e-02f); p = p * t + 1.087993085e-01f; p = p * t + (-3.740358949e-01f); p = p * t + 1.128076553e+00f;
;     const f32x2 hv = v * 0.5f;
;     return hv * (x * p) + hv;
; }
;     __device__ __forceinline__ void operator()(const f32x4 (&acc)[2][2][4][2], const Unit& u, int wr, int wc, int fr, int fq) const {
;     ...
;                 for (int m = 0; m < 4; ++m) { const u32x4 cur = gq[m]; u32x4 hw;
; #pragma unroll
;                     for (int hv = 0; hv < 2; ++hv) { const u32x2 c2 = half2(cur, hv), p2 = half2(pv, hv);
;                         const u32x2 q1 = dpp_prev<1>(p2, c2), q2 = dpp_prev<2>(p2, c2);
;                         float g0[4], g1[4], g2[4]; unpk4(c2, g0); unpk4(q1, g1); unpk4(q2, g2);
;                         const u32x2 r = finish2(g0, g1, g2, w0[hv], w1[hv], w2[hv], bb[hv], acc[ai][bj][m][hv], rs8[ai][m]);
;                         if (hv == 0) { hw.x = r.x; hw.y = r.y; } else { hw.z = r.x; hw.w = r.y; } }
.LBB0_1013:
	s_waitcnt vmcnt(0)
	v_mov_b32_dpp v195, v180 row_ror:2 row_mask:0xf bank_mask:0xf bound_ctrl:1
	v_mov_b32_dpp v191, v180 row_ror:1 row_mask:0xf bank_mask:0xf bound_ctrl:1
	v_mad_i64_i32 v[230:231], s[8:9], v210, s91, 0
	v_mov_b32_dpp v195, v176 row_shr:2 row_mask:0xf bank_mask:0xf
	v_mov_b32_dpp v191, v176 row_shr:1 row_mask:0xf bank_mask:0xf
	v_lshlrev_b32_e32 v210, 16, v195
	v_and_b32_e32 v211, 0xffff0000, v195
	v_mov_b32_dpp v193, v181 row_ror:1 row_mask:0xf bank_mask:0xf bound_ctrl:1
	v_mov_b32_dpp v229, v181 row_ror:2 row_mask:0xf bank_mask:0xf bound_ctrl:1
	v_lshlrev_b32_e32 v180, 16, v191
	v_and_b32_e32 v181, 0xffff0000, v191
	v_pk_fma_f32 v[210:211], v[148:149], v[210:211], v[160:161]
	v_lshlrev_b32_e32 v232, 16, v176
	v_and_b32_e32 v233, 0xffff0000, v176
	v_pk_fma_f32 v[180:181], v[152:153], v[180:181], v[210:211]
	v_mov_b32_dpp v229, v177 row_shr:2 row_mask:0xf bank_mask:0xf
	v_pk_fma_f32 v[180:181], v[156:157], v[232:233], v[180:181]
	v_mov_b32_dpp v193, v177 row_shr:1 row_mask:0xf bank_mask:0xf
	v_pk_mul_f32 v[210:211], v[180:181], s[30:31] op_sel_hi:[1,0]
	v_lshlrev_b32_e32 v228, 16, v229
	v_med3_f32 v232, v210, s47, v225
	v_med3_f32 v233, v211, s47, v225
	v_pk_mul_f32 v[234:235], v[232:233], v[232:233]
	v_mov_b64_e32 v[210:211], s[36:37]
	v_pk_fma_f32 v[236:237], v[234:235], s[34:35], v[210:211] op_sel_hi:[1,0,0] neg_lo:[1,0,0] neg_hi:[1,0,0]
	v_and_b32_e32 v229, 0xffff0000, v229
	v_pk_fma_f32 v[236:237], v[234:235], v[236:237], s[38:39] op_sel_hi:[1,1,0]
	v_pk_mul_f32 v[180:181], v[180:181], 0.5 op_sel_hi:[1,0]
	v_pk_fma_f32 v[236:237], v[234:235], v[236:237], s[40:41] op_sel_hi:[1,1,0]
	v_lshlrev_b32_e32 v226, 16, v193
	v_pk_fma_f32 v[236:237], v[234:235], v[236:237], s[42:43] op_sel_hi:[1,1,0]
	v_and_b32_e32 v227, 0xffff0000, v193
	v_pk_fma_f32 v[236:237], v[234:235], v[236:237], s[44:45] op_sel_hi:[1,1,0]
	v_pk_mul_f32 v[128:129], v[128:129], v[188:189] op_sel_hi:[1,0]
	v_pk_fma_f32 v[236:237], v[234:235], v[236:237], s[46:47] op_sel_hi:[1,1,0]
	v_pk_fma_f32 v[228:229], v[150:151], v[228:229], v[162:163]
	v_pk_fma_f32 v[234:235], v[234:235], v[236:237], s[48:49] op_sel_hi:[1,1,0]
	v_pk_fma_f32 v[226:227], v[154:155], v[226:227], v[228:229]
	v_pk_mul_f32 v[232:233], v[232:233], v[234:235]
	v_pk_mul_f32 v[130:131], v[130:131], v[188:189] op_sel_hi:[1,0]
	v_pk_fma_f32 v[180:181], v[180:181], v[232:233], v[180:181]
	v_pk_mul_f32 v[124:125], v[124:125], v[188:189] op_sel_hi:[1,0]
	v_pk_mul_f32 v[128:129], v[128:129], v[180:181]
	v_lshlrev_b32_e32 v180, 16, v177
	v_and_b32_e32 v181, 0xffff0000, v177
	v_pk_fma_f32 v[180:181], v[158:159], v[180:181], v[226:227]
	v_readlane_b32 s8, v240, 58
	v_pk_mul_f32 v[226:227], v[180:181], s[30:31] op_sel_hi:[1,0]
	v_pk_mul_f32 v[180:181], v[180:181], 0.5 op_sel_hi:[1,0]
	v_med3_f32 v226, v226, s47, v225
	v_med3_f32 v227, v227, s47, v225
	v_pk_mul_f32 v[228:229], v[226:227], v[226:227]
	v_readlane_b32 s9, v240, 59
	v_pk_fma_f32 v[232:233], v[228:229], s[34:35], v[210:211] op_sel_hi:[1,0,0] neg_lo:[1,0,0] neg_hi:[1,0,0]
	v_pk_mul_f32 v[126:127], v[126:127], v[188:189] op_sel_hi:[1,0]
	v_pk_fma_f32 v[232:233], v[228:229], v[232:233], s[38:39] op_sel_hi:[1,1,0]
	v_pk_mul_f32 v[120:121], v[120:121], v[186:187] op_sel_hi:[1,0]
	v_pk_fma_f32 v[232:233], v[228:229], v[232:233], s[40:41] op_sel_hi:[1,1,0]
	v_pk_mul_f32 v[122:123], v[122:123], v[186:187] op_sel_hi:[1,0]
	v_pk_fma_f32 v[232:233], v[228:229], v[232:233], s[42:43] op_sel_hi:[1,1,0]
	v_pk_mul_f32 v[116:117], v[116:117], v[186:187] op_sel_hi:[1,0]
	v_pk_fma_f32 v[232:233], v[228:229], v[232:233], s[44:45] op_sel_hi:[1,1,0]
	v_pk_mul_f32 v[118:119], v[118:119], v[186:187] op_sel_hi:[1,0]
	v_pk_fma_f32 v[232:233], v[228:229], v[232:233], s[46:47] op_sel_hi:[1,1,0]
	v_pk_mul_f32 v[112:113], v[112:113], v[184:185] op_sel_hi:[1,0]
	v_pk_fma_f32 v[228:229], v[228:229], v[232:233], s[48:49] op_sel_hi:[1,1,0]
	v_pk_mul_f32 v[114:115], v[114:115], v[184:185] op_sel_hi:[1,0]
	v_pk_mul_f32 v[226:227], v[226:227], v[228:229]
	v_lshlrev_b32_e32 v228, 16, v178
	v_pk_fma_f32 v[180:181], v[180:181], v[226:227], v[180:181]
	v_cvt_pk_bf16_f32 v226, v128, v129
	v_mov_b32_dpp v129, v182 row_ror:1 row_mask:0xf bank_mask:0xf bound_ctrl:1
	v_pk_mul_f32 v[130:131], v[130:131], v[180:181]
	v_mov_b32_dpp v181, v182 row_ror:2 row_mask:0xf bank_mask:0xf bound_ctrl:1
	v_mov_b32_dpp v129, v178 row_shr:1 row_mask:0xf bank_mask:0xf
	v_lshlrev_b32_e32 v128, 16, v129
	v_mov_b32_dpp v181, v178 row_shr:2 row_mask:0xf bank_mask:0xf
	v_lshlrev_b32_e32 v180, 16, v181
	v_and_b32_e32 v181, 0xffff0000, v181
	v_and_b32_e32 v129, 0xffff0000, v129
	v_pk_fma_f32 v[180:181], v[132:133], v[180:181], v[144:145]
	v_and_b32_e32 v229, 0xffff0000, v178
	v_pk_fma_f32 v[128:129], v[136:137], v[128:129], v[180:181]
	v_cvt_pk_bf16_f32 v227, v130, v131
	v_mov_b32_dpp v131, v183 row_ror:1 row_mask:0xf bank_mask:0xf bound_ctrl:1
	v_pk_fma_f32 v[128:129], v[140:141], v[228:229], v[128:129]
	v_mov_b32_dpp v183, v183 row_ror:2 row_mask:0xf bank_mask:0xf bound_ctrl:1
	v_pk_mul_f32 v[180:181], v[128:129], s[30:31] op_sel_hi:[1,0]
	v_mov_b32_dpp v131, v179 row_shr:1 row_mask:0xf bank_mask:0xf
	v_med3_f32 v180, v180, s47, v225
	v_med3_f32 v181, v181, s47, v225
	v_pk_mul_f32 v[228:229], v[180:181], v[180:181]
	v_mov_b32_dpp v183, v179 row_shr:2 row_mask:0xf bank_mask:0xf
	v_pk_fma_f32 v[232:233], v[228:229], s[34:35], v[210:211] op_sel_hi:[1,0,0] neg_lo:[1,0,0] neg_hi:[1,0,0]
	v_lshlrev_b32_e32 v182, 16, v183
	v_pk_fma_f32 v[232:233], v[228:229], v[232:233], s[38:39] op_sel_hi:[1,1,0]
	v_and_b32_e32 v183, 0xffff0000, v183
	v_pk_fma_f32 v[232:233], v[228:229], v[232:233], s[40:41] op_sel_hi:[1,1,0]
;     static __device__ __forceinline__ void unpk4(const u32x2 w, float (&o)[4]) { o[0] = bf_lo(w.x); o[1] = bf_hi(w.x); o[2] = bf_lo(w.y); o[3] = bf_hi(w.y); }
;     template <int N> static __device__ __forceinline__ u32x2 dpp_prev(const u32x2 pv, const u32x2 cur) { u32x2 r; r.x = dpp_prev1<N>(pv.x, cur.x); r.y = dpp_prev1<N>(pv.y, cur.y); return r; }
;     __device__ __forceinline__ void operator()(const f32x4 (&acc)[2][2][4][2], const Unit& u, int wr, int wc, int fr, int fq) const {
;     ...
;                 for (int m = 0; m < 4; ++m) { const u32x4 cur = gq[m]; u32x4 hw;
; #pragma unroll
;                     for (int hv = 0; hv < 2; ++hv) { const u32x2 c2 = half2(cur, hv), p2 = half2(pv, hv);
;                         const u32x2 q1 = dpp_prev<1>(p2, c2), q2 = dpp_prev<2>(p2, c2);
;                         float g0[4], g1[4], g2[4]; unpk4(c2, g0); unpk4(q1, g1); unpk4(q2, g2);
;                         const u32x2 r = finish2(g0, g1, g2, w0[hv], w1[hv], w2[hv], bb[hv], acc[ai][bj][m][hv], rs8[ai][m]);
;                         if (hv == 0) { hw.x = r.x; hw.y = r.y; } else { hw.z = r.x; hw.w = r.y; } }
;                     *(u32x4*)(H + (size_t)(R0 + fr + 16 * m) * 2816 + col8) = hw;
;                     pv = cur; } }
	v_pk_mul_f32 v[128:129], v[128:129], 0.5 op_sel_hi:[1,0]
	v_pk_fma_f32 v[232:233], v[228:229], v[232:233], s[42:43] op_sel_hi:[1,1,0]
	v_lshlrev_b32_e32 v130, 16, v131
	v_pk_fma_f32 v[232:233], v[228:229], v[232:233], s[44:45] op_sel_hi:[1,1,0]
	v_and_b32_e32 v131, 0xffff0000, v131
	v_pk_fma_f32 v[232:233], v[228:229], v[232:233], s[46:47] op_sel_hi:[1,1,0]
	v_pk_mul_f32 v[108:109], v[108:109], v[184:185] op_sel_hi:[1,0]
	v_pk_fma_f32 v[228:229], v[228:229], v[232:233], s[48:49] op_sel_hi:[1,1,0]
	v_pk_mul_f32 v[110:111], v[110:111], v[184:185] op_sel_hi:[1,0]
	v_pk_mul_f32 v[180:181], v[180:181], v[228:229]
	v_pk_mul_f32 v[104:105], v[104:105], v[2:3] op_sel_hi:[1,0]
	v_pk_fma_f32 v[128:129], v[128:129], v[180:181], v[128:129]
	v_pk_fma_f32 v[180:181], v[134:135], v[182:183], v[146:147]
	v_pk_mul_f32 v[124:125], v[124:125], v[128:129]
	v_lshlrev_b32_e32 v128, 16, v179
	v_and_b32_e32 v129, 0xffff0000, v179
	v_pk_fma_f32 v[130:131], v[138:139], v[130:131], v[180:181]
	v_cvt_pk_bf16_f32 v228, v124, v125
	v_pk_mul_f32 v[106:107], v[106:107], v[2:3] op_sel_hi:[1,0]
	v_pk_fma_f32 v[128:129], v[142:143], v[128:129], v[130:131]
	v_pk_mul_f32 v[100:101], v[100:101], v[2:3] op_sel_hi:[1,0]
	v_pk_mul_f32 v[130:131], v[128:129], s[30:31] op_sel_hi:[1,0]
	v_pk_mul_f32 v[128:129], v[128:129], 0.5 op_sel_hi:[1,0]
	v_med3_f32 v130, v130, s47, v225
	v_med3_f32 v131, v131, s47, v225
	v_pk_mul_f32 v[180:181], v[130:131], v[130:131]
	s_add_i32 s7, s2, 0x80
	v_pk_fma_f32 v[182:183], v[180:181], s[34:35], v[210:211] op_sel_hi:[1,0,0] neg_lo:[1,0,0] neg_hi:[1,0,0]
	v_readlane_b32 s2, v240, 12
	v_pk_fma_f32 v[182:183], v[180:181], v[182:183], s[38:39] op_sel_hi:[1,1,0]
	v_readlane_b32 s3, v240, 13
	v_pk_fma_f32 v[182:183], v[180:181], v[182:183], s[40:41] op_sel_hi:[1,1,0]
	v_add_u32_e32 v1, s7, v1
	v_pk_fma_f32 v[182:183], v[180:181], v[182:183], s[42:43] op_sel_hi:[1,1,0]
	v_pk_mul_f32 v[102:103], v[102:103], v[2:3] op_sel_hi:[1,0]
	v_pk_fma_f32 v[182:183], v[180:181], v[182:183], s[44:45] op_sel_hi:[1,1,0]
	s_and_b32 s7, s7, 0x1fff
	v_pk_fma_f32 v[182:183], v[180:181], v[182:183], s[46:47] op_sel_hi:[1,1,0]
	s_cmp_lg_u32 s7, 0
	v_pk_fma_f32 v[180:181], v[180:181], v[182:183], s[48:49] op_sel_hi:[1,1,0]
	v_lshlrev_b32_e32 v182, 16, v172
	v_pk_mul_f32 v[130:131], v[130:131], v[180:181]
	v_lshlrev_b64 v[180:181], 1, v[212:213]
	v_pk_fma_f32 v[128:129], v[128:129], v[130:131], v[128:129]
	v_lshl_add_u64 v[130:131], s[8:9], 0, v[230:231]
	v_pk_mul_f32 v[126:127], v[126:127], v[128:129]
	v_lshl_add_u64 v[124:125], v[130:131], 0, v[180:181]
	v_mov_b32_dpp v129, v176 row_ror:2 row_mask:0xf bank_mask:0xf bound_ctrl:1
	v_cvt_pk_bf16_f32 v229, v126, v127
	global_store_dwordx4 v[124:125], v[226:229], off
	v_mov_b32_dpp v125, v176 row_ror:1 row_mask:0xf bank_mask:0xf bound_ctrl:1
	v_mov_b32_dpp v129, v172 row_shr:2 row_mask:0xf bank_mask:0xf
	v_lshlrev_b32_e32 v128, 16, v129
	v_mov_b32_dpp v125, v172 row_shr:1 row_mask:0xf bank_mask:0xf
	v_and_b32_e32 v129, 0xffff0000, v129
	v_lshlrev_b32_e32 v124, 16, v125
	v_and_b32_e32 v125, 0xffff0000, v125
	v_pk_fma_f32 v[128:129], v[148:149], v[128:129], v[160:161]
	v_and_b32_e32 v183, 0xffff0000, v172
	v_pk_fma_f32 v[124:125], v[152:153], v[124:125], v[128:129]
	v_mov_b32_dpp v127, v177 row_ror:1 row_mask:0xf bank_mask:0xf bound_ctrl:1
	v_pk_fma_f32 v[124:125], v[156:157], v[182:183], v[124:125]
	v_mov_b32_dpp v177, v177 row_ror:2 row_mask:0xf bank_mask:0xf bound_ctrl:1
	v_pk_mul_f32 v[128:129], v[124:125], s[30:31] op_sel_hi:[1,0]
	v_mov_b32_dpp v127, v173 row_shr:1 row_mask:0xf bank_mask:0xf
	v_med3_f32 v128, v128, s47, v225
	v_med3_f32 v129, v129, s47, v225
	v_pk_mul_f32 v[182:183], v[128:129], v[128:129]
	v_mov_b32_dpp v177, v173 row_shr:2 row_mask:0xf bank_mask:0xf
	v_pk_fma_f32 v[226:227], v[182:183], s[34:35], v[210:211] op_sel_hi:[1,0,0] neg_lo:[1,0,0] neg_hi:[1,0,0]
	v_lshlrev_b32_e32 v176, 16, v177
	v_pk_fma_f32 v[226:227], v[182:183], v[226:227], s[38:39] op_sel_hi:[1,1,0]
	v_and_b32_e32 v177, 0xffff0000, v177
	v_pk_fma_f32 v[226:227], v[182:183], v[226:227], s[40:41] op_sel_hi:[1,1,0]
	v_pk_mul_f32 v[124:125], v[124:125], 0.5 op_sel_hi:[1,0]
	v_pk_fma_f32 v[226:227], v[182:183], v[226:227], s[42:43] op_sel_hi:[1,1,0]
	v_lshlrev_b32_e32 v126, 16, v127
	v_pk_fma_f32 v[226:227], v[182:183], v[226:227], s[44:45] op_sel_hi:[1,1,0]
	v_and_b32_e32 v127, 0xffff0000, v127
	v_pk_fma_f32 v[226:227], v[182:183], v[226:227], s[46:47] op_sel_hi:[1,1,0]
	s_nop 0
	v_pk_fma_f32 v[182:183], v[182:183], v[226:227], s[48:49] op_sel_hi:[1,1,0]
	s_nop 0
	v_pk_mul_f32 v[128:129], v[128:129], v[182:183]
	s_nop 0
	v_pk_fma_f32 v[124:125], v[124:125], v[128:129], v[124:125]
	v_pk_fma_f32 v[128:129], v[150:151], v[176:177], v[162:163]
	v_pk_mul_f32 v[120:121], v[120:121], v[124:125]
	v_lshlrev_b32_e32 v124, 16, v173
	v_and_b32_e32 v125, 0xffff0000, v173
	v_pk_fma_f32 v[126:127], v[154:155], v[126:127], v[128:129]
	v_cvt_pk_bf16_f32 v120, v120, v121
	s_nop 0
	v_pk_fma_f32 v[124:125], v[158:159], v[124:125], v[126:127]
	s_nop 0
	v_pk_mul_f32 v[126:127], v[124:125], s[30:31] op_sel_hi:[1,0]
	v_pk_mul_f32 v[124:125], v[124:125], 0.5 op_sel_hi:[1,0]
	v_med3_f32 v126, v126, s47, v225
	v_med3_f32 v127, v127, s47, v225
	v_pk_mul_f32 v[128:129], v[126:127], v[126:127]
	s_nop 0
	v_pk_fma_f32 v[176:177], v[128:129], s[34:35], v[210:211] op_sel_hi:[1,0,0] neg_lo:[1,0,0] neg_hi:[1,0,0]
	s_nop 0
	v_pk_fma_f32 v[176:177], v[128:129], v[176:177], s[38:39] op_sel_hi:[1,1,0]
	s_nop 0
	v_pk_fma_f32 v[176:177], v[128:129], v[176:177], s[40:41] op_sel_hi:[1,1,0]
	s_nop 0
	v_pk_fma_f32 v[176:177], v[128:129], v[176:177], s[42:43] op_sel_hi:[1,1,0]
	s_nop 0
;     static __device__ __forceinline__ void unpk4(const u32x2 w, float (&o)[4]) { o[0] = bf_lo(w.x); o[1] = bf_hi(w.x); o[2] = bf_lo(w.y); o[3] = bf_hi(w.y); }
;     template <int N> static __device__ __forceinline__ u32x2 dpp_prev(const u32x2 pv, const u32x2 cur) { u32x2 r; r.x = dpp_prev1<N>(pv.x, cur.x); r.y = dpp_prev1<N>(pv.y, cur.y); return r; }
;     __device__ __forceinline__ void operator()(const f32x4 (&acc)[2][2][4][2], const Unit& u, int wr, int wc, int fr, int fq) const {
;     ...
;                 for (int m = 0; m < 4; ++m) { const u32x4 cur = gq[m]; u32x4 hw;
; #pragma unroll
;                     for (int hv = 0; hv < 2; ++hv) { const u32x2 c2 = half2(cur, hv), p2 = half2(pv, hv);
;                         const u32x2 q1 = dpp_prev<1>(p2, c2), q2 = dpp_prev<2>(p2, c2);
;                         float g0[4], g1[4], g2[4]; unpk4(c2, g0); unpk4(q1, g1); unpk4(q2, g2);
;                         const u32x2 r = finish2(g0, g1, g2, w0[hv], w1[hv], w2[hv], bb[hv], acc[ai][bj][m][hv], rs8[ai][m]);
;                         if (hv == 0) { hw.x = r.x; hw.y = r.y; } else { hw.z = r.x; hw.w = r.y; } }
;                     *(u32x4*)(H + (size_t)(R0 + fr + 16 * m) * 2816 + col8) = hw;
;                     pv = cur; } }
	v_pk_fma_f32 v[176:177], v[128:129], v[176:177], s[44:45] op_sel_hi:[1,1,0]
	s_nop 0
	v_pk_fma_f32 v[176:177], v[128:129], v[176:177], s[46:47] op_sel_hi:[1,1,0]
	s_nop 0
	v_pk_fma_f32 v[128:129], v[128:129], v[176:177], s[48:49] op_sel_hi:[1,1,0]
	v_lshlrev_b32_e32 v176, 16, v174
	v_pk_mul_f32 v[126:127], v[126:127], v[128:129]
	v_and_b32_e32 v177, 0xffff0000, v174
	v_pk_fma_f32 v[124:125], v[124:125], v[126:127], v[124:125]
	v_mov_b32_dpp v127, v178 row_ror:2 row_mask:0xf bank_mask:0xf bound_ctrl:1
	v_pk_mul_f32 v[122:123], v[122:123], v[124:125]
	v_mov_b32_dpp v125, v179 row_ror:1 row_mask:0xf bank_mask:0xf bound_ctrl:1
	v_cvt_pk_bf16_f32 v121, v122, v123
	v_mov_b32_dpp v127, v174 row_shr:2 row_mask:0xf bank_mask:0xf
	v_mov_b32_dpp v123, v178 row_ror:1 row_mask:0xf bank_mask:0xf bound_ctrl:1
	v_lshlrev_b32_e32 v126, 16, v127
	v_and_b32_e32 v127, 0xffff0000, v127
	v_mov_b32_dpp v123, v174 row_shr:1 row_mask:0xf bank_mask:0xf
	v_lshlrev_b32_e32 v122, 16, v123
	v_and_b32_e32 v123, 0xffff0000, v123
	v_pk_fma_f32 v[126:127], v[132:133], v[126:127], v[144:145]
	v_mov_b32_dpp v129, v179 row_ror:2 row_mask:0xf bank_mask:0xf bound_ctrl:1
	v_pk_fma_f32 v[122:123], v[136:137], v[122:123], v[126:127]
	v_mov_b32_dpp v125, v175 row_shr:1 row_mask:0xf bank_mask:0xf
	v_pk_fma_f32 v[122:123], v[140:141], v[176:177], v[122:123]
	v_mov_b32_dpp v129, v175 row_shr:2 row_mask:0xf bank_mask:0xf
	v_pk_mul_f32 v[126:127], v[122:123], s[30:31] op_sel_hi:[1,0]
	v_lshlrev_b32_e32 v128, 16, v129
	v_med3_f32 v126, v126, s47, v225
	v_med3_f32 v127, v127, s47, v225
	v_pk_mul_f32 v[176:177], v[126:127], v[126:127]
	v_and_b32_e32 v129, 0xffff0000, v129
	v_pk_fma_f32 v[178:179], v[176:177], s[34:35], v[210:211] op_sel_hi:[1,0,0] neg_lo:[1,0,0] neg_hi:[1,0,0]
	v_pk_mul_f32 v[122:123], v[122:123], 0.5 op_sel_hi:[1,0]
	v_pk_fma_f32 v[178:179], v[176:177], v[178:179], s[38:39] op_sel_hi:[1,1,0]
	v_lshlrev_b32_e32 v124, 16, v125
	v_pk_fma_f32 v[178:179], v[176:177], v[178:179], s[40:41] op_sel_hi:[1,1,0]
	v_and_b32_e32 v125, 0xffff0000, v125
	v_pk_fma_f32 v[178:179], v[176:177], v[178:179], s[42:43] op_sel_hi:[1,1,0]
	s_nop 0
	v_pk_fma_f32 v[178:179], v[176:177], v[178:179], s[44:45] op_sel_hi:[1,1,0]
	s_nop 0
	v_pk_fma_f32 v[178:179], v[176:177], v[178:179], s[46:47] op_sel_hi:[1,1,0]
	s_nop 0
	v_pk_fma_f32 v[176:177], v[176:177], v[178:179], s[48:49] op_sel_hi:[1,1,0]
	s_nop 0
	v_pk_mul_f32 v[126:127], v[126:127], v[176:177]
	s_nop 0
	v_pk_fma_f32 v[122:123], v[122:123], v[126:127], v[122:123]
	v_pk_fma_f32 v[126:127], v[134:135], v[128:129], v[146:147]
	v_pk_mul_f32 v[116:117], v[116:117], v[122:123]
	v_lshlrev_b32_e32 v122, 16, v175
	v_and_b32_e32 v123, 0xffff0000, v175
	v_pk_fma_f32 v[124:125], v[138:139], v[124:125], v[126:127]
	s_nop 0
	v_pk_fma_f32 v[122:123], v[142:143], v[122:123], v[124:125]
	s_nop 0
	v_pk_mul_f32 v[124:125], v[122:123], s[30:31] op_sel_hi:[1,0]
	v_pk_mul_f32 v[122:123], v[122:123], 0.5 op_sel_hi:[1,0]
	v_med3_f32 v124, v124, s47, v225
	v_med3_f32 v125, v125, s47, v225
	v_pk_mul_f32 v[126:127], v[124:125], v[124:125]
	s_nop 0
	v_pk_fma_f32 v[128:129], v[126:127], s[34:35], v[210:211] op_sel_hi:[1,0,0] neg_lo:[1,0,0] neg_hi:[1,0,0]
	s_nop 0
	v_pk_fma_f32 v[128:129], v[126:127], v[128:129], s[38:39] op_sel_hi:[1,1,0]
	s_nop 0
	v_pk_fma_f32 v[128:129], v[126:127], v[128:129], s[40:41] op_sel_hi:[1,1,0]
	s_nop 0
	v_pk_fma_f32 v[128:129], v[126:127], v[128:129], s[42:43] op_sel_hi:[1,1,0]
	s_nop 0
	v_pk_fma_f32 v[128:129], v[126:127], v[128:129], s[44:45] op_sel_hi:[1,1,0]
	s_nop 0
	v_pk_fma_f32 v[128:129], v[126:127], v[128:129], s[46:47] op_sel_hi:[1,1,0]
	s_nop 0
	v_pk_fma_f32 v[126:127], v[126:127], v[128:129], s[48:49] op_sel_hi:[1,1,0]
	s_nop 0
	v_pk_mul_f32 v[124:125], v[124:125], v[126:127]
	v_lshlrev_b32_e32 v126, 16, v168
	v_pk_fma_f32 v[122:123], v[122:123], v[124:125], v[122:123]
	v_and_b32_e32 v127, 0xffff0000, v168
	v_pk_mul_f32 v[118:119], v[118:119], v[122:123]
	v_cvt_pk_bf16_f32 v122, v116, v117
	v_mov_b64_e32 v[116:117], s[8:9]
	v_mad_i64_i32 v[176:177], s[8:9], v194, s91, v[116:117]
	v_cvt_pk_bf16_f32 v123, v118, v119
	v_lshl_add_u64 v[118:119], v[176:177], 0, v[180:181]
	global_store_dwordx4 v[118:119], v[120:123], off
	v_mov_b32_dpp v125, v173 row_ror:2 row_mask:0xf bank_mask:0xf bound_ctrl:1
	v_mov_b32_dpp v119, v172 row_ror:1 row_mask:0xf bank_mask:0xf bound_ctrl:1
	v_mov_b32_dpp v123, v172 row_ror:2 row_mask:0xf bank_mask:0xf bound_ctrl:1
	v_mov_b32_dpp v121, v173 row_ror:1 row_mask:0xf bank_mask:0xf bound_ctrl:1
	v_mov_b32_dpp v119, v168 row_shr:1 row_mask:0xf bank_mask:0xf
	v_mov_b32_dpp v123, v168 row_shr:2 row_mask:0xf bank_mask:0xf
	v_lshlrev_b32_e32 v122, 16, v123
	v_and_b32_e32 v123, 0xffff0000, v123
	v_lshlrev_b32_e32 v118, 16, v119
	v_and_b32_e32 v119, 0xffff0000, v119
	v_pk_fma_f32 v[122:123], v[148:149], v[122:123], v[160:161]
	v_mov_b32_dpp v125, v169 row_shr:2 row_mask:0xf bank_mask:0xf
	v_pk_fma_f32 v[118:119], v[152:153], v[118:119], v[122:123]
	v_mov_b32_dpp v121, v169 row_shr:1 row_mask:0xf bank_mask:0xf
	v_pk_fma_f32 v[118:119], v[156:157], v[126:127], v[118:119]
	v_lshlrev_b32_e32 v124, 16, v125
	v_pk_mul_f32 v[122:123], v[118:119], s[30:31] op_sel_hi:[1,0]
	v_and_b32_e32 v125, 0xffff0000, v125
	v_med3_f32 v122, v122, s47, v225
	v_med3_f32 v123, v123, s47, v225
	v_pk_mul_f32 v[126:127], v[122:123], v[122:123]
	v_pk_mul_f32 v[118:119], v[118:119], 0.5 op_sel_hi:[1,0]
	v_pk_fma_f32 v[128:129], v[126:127], s[34:35], v[210:211] op_sel_hi:[1,0,0] neg_lo:[1,0,0] neg_hi:[1,0,0]
	v_lshlrev_b32_e32 v120, 16, v121
	v_pk_fma_f32 v[128:129], v[126:127], v[128:129], s[38:39] op_sel_hi:[1,1,0]
	v_and_b32_e32 v121, 0xffff0000, v121
;     static __device__ __forceinline__ void unpk4(const u32x2 w, float (&o)[4]) { o[0] = bf_lo(w.x); o[1] = bf_hi(w.x); o[2] = bf_lo(w.y); o[3] = bf_hi(w.y); }
;     template <int N> static __device__ __forceinline__ u32x2 dpp_prev(const u32x2 pv, const u32x2 cur) { u32x2 r; r.x = dpp_prev1<N>(pv.x, cur.x); r.y = dpp_prev1<N>(pv.y, cur.y); return r; }
;     __device__ __forceinline__ void operator()(const f32x4 (&acc)[2][2][4][2], const Unit& u, int wr, int wc, int fr, int fq) const {
;     ...
;                 for (int m = 0; m < 4; ++m) { const u32x4 cur = gq[m]; u32x4 hw;
; #pragma unroll
;                     for (int hv = 0; hv < 2; ++hv) { const u32x2 c2 = half2(cur, hv), p2 = half2(pv, hv);
;                         const u32x2 q1 = dpp_prev<1>(p2, c2), q2 = dpp_prev<2>(p2, c2);
;                         float g0[4], g1[4], g2[4]; unpk4(c2, g0); unpk4(q1, g1); unpk4(q2, g2);
;                         const u32x2 r = finish2(g0, g1, g2, w0[hv], w1[hv], w2[hv], bb[hv], acc[ai][bj][m][hv], rs8[ai][m]);
;                         if (hv == 0) { hw.x = r.x; hw.y = r.y; } else { hw.z = r.x; hw.w = r.y; } }
;                     *(u32x4*)(H + (size_t)(R0 + fr + 16 * m) * 2816 + col8) = hw;
;                     pv = cur; } }
	v_pk_fma_f32 v[128:129], v[126:127], v[128:129], s[40:41] op_sel_hi:[1,1,0]
	v_mad_i64_i32 v[172:173], s[8:9], v192, s91, v[116:117]
	v_pk_fma_f32 v[128:129], v[126:127], v[128:129], s[42:43] op_sel_hi:[1,1,0]
	s_nop 0
	v_pk_fma_f32 v[128:129], v[126:127], v[128:129], s[44:45] op_sel_hi:[1,1,0]
	s_nop 0
	v_pk_fma_f32 v[128:129], v[126:127], v[128:129], s[46:47] op_sel_hi:[1,1,0]
	s_nop 0
	v_pk_fma_f32 v[126:127], v[126:127], v[128:129], s[48:49] op_sel_hi:[1,1,0]
	s_nop 0
	v_pk_mul_f32 v[122:123], v[122:123], v[126:127]
	s_nop 0
	v_pk_fma_f32 v[118:119], v[118:119], v[122:123], v[118:119]
	v_pk_fma_f32 v[122:123], v[150:151], v[124:125], v[162:163]
	v_pk_mul_f32 v[112:113], v[112:113], v[118:119]
	v_lshlrev_b32_e32 v118, 16, v169
	v_and_b32_e32 v119, 0xffff0000, v169
	v_pk_fma_f32 v[120:121], v[154:155], v[120:121], v[122:123]
	v_cvt_pk_bf16_f32 v112, v112, v113
	s_nop 0
	v_pk_fma_f32 v[118:119], v[158:159], v[118:119], v[120:121]
	s_nop 0
	v_pk_mul_f32 v[120:121], v[118:119], s[30:31] op_sel_hi:[1,0]
	v_pk_mul_f32 v[118:119], v[118:119], 0.5 op_sel_hi:[1,0]
	v_med3_f32 v120, v120, s47, v225
	v_med3_f32 v121, v121, s47, v225
	v_pk_mul_f32 v[122:123], v[120:121], v[120:121]
	s_nop 0
	v_pk_fma_f32 v[124:125], v[122:123], s[34:35], v[210:211] op_sel_hi:[1,0,0] neg_lo:[1,0,0] neg_hi:[1,0,0]
	s_nop 0
	v_pk_fma_f32 v[124:125], v[122:123], v[124:125], s[38:39] op_sel_hi:[1,1,0]
	s_nop 0
	v_pk_fma_f32 v[124:125], v[122:123], v[124:125], s[40:41] op_sel_hi:[1,1,0]
	s_nop 0
	v_pk_fma_f32 v[124:125], v[122:123], v[124:125], s[42:43] op_sel_hi:[1,1,0]
	s_nop 0
	v_pk_fma_f32 v[124:125], v[122:123], v[124:125], s[44:45] op_sel_hi:[1,1,0]
	s_nop 0
	v_pk_fma_f32 v[124:125], v[122:123], v[124:125], s[46:47] op_sel_hi:[1,1,0]
	s_nop 0
	v_pk_fma_f32 v[122:123], v[122:123], v[124:125], s[48:49] op_sel_hi:[1,1,0]
	v_lshlrev_b32_e32 v124, 16, v170
	v_pk_mul_f32 v[120:121], v[120:121], v[122:123]
	v_and_b32_e32 v125, 0xffff0000, v170
	v_pk_fma_f32 v[118:119], v[118:119], v[120:121], v[118:119]
	v_mov_b32_dpp v121, v174 row_ror:2 row_mask:0xf bank_mask:0xf bound_ctrl:1
	v_pk_mul_f32 v[114:115], v[114:115], v[118:119]
	v_mov_b32_dpp v123, v175 row_ror:2 row_mask:0xf bank_mask:0xf bound_ctrl:1
	v_cvt_pk_bf16_f32 v113, v114, v115
	v_mov_b32_dpp v121, v170 row_shr:2 row_mask:0xf bank_mask:0xf
	v_mov_b32_dpp v115, v174 row_ror:1 row_mask:0xf bank_mask:0xf bound_ctrl:1
	v_lshlrev_b32_e32 v120, 16, v121
	v_and_b32_e32 v121, 0xffff0000, v121
	v_mov_b32_dpp v115, v170 row_shr:1 row_mask:0xf bank_mask:0xf
	v_lshlrev_b32_e32 v114, 16, v115
	v_and_b32_e32 v115, 0xffff0000, v115
	v_pk_fma_f32 v[120:121], v[132:133], v[120:121], v[144:145]
	v_mov_b32_dpp v119, v175 row_ror:1 row_mask:0xf bank_mask:0xf bound_ctrl:1
	v_pk_fma_f32 v[114:115], v[136:137], v[114:115], v[120:121]
	v_mov_b32_dpp v123, v171 row_shr:2 row_mask:0xf bank_mask:0xf
	v_pk_fma_f32 v[114:115], v[140:141], v[124:125], v[114:115]
	v_mov_b32_dpp v119, v171 row_shr:1 row_mask:0xf bank_mask:0xf
	v_pk_mul_f32 v[120:121], v[114:115], s[30:31] op_sel_hi:[1,0]
	v_lshlrev_b32_e32 v122, 16, v123
	v_med3_f32 v120, v120, s47, v225
	v_med3_f32 v121, v121, s47, v225
	v_pk_mul_f32 v[124:125], v[120:121], v[120:121]
	v_and_b32_e32 v123, 0xffff0000, v123
	v_pk_fma_f32 v[126:127], v[124:125], s[34:35], v[210:211] op_sel_hi:[1,0,0] neg_lo:[1,0,0] neg_hi:[1,0,0]
	v_pk_mul_f32 v[114:115], v[114:115], 0.5 op_sel_hi:[1,0]
	v_pk_fma_f32 v[126:127], v[124:125], v[126:127], s[38:39] op_sel_hi:[1,1,0]
	v_lshlrev_b32_e32 v118, 16, v119
	v_pk_fma_f32 v[126:127], v[124:125], v[126:127], s[40:41] op_sel_hi:[1,1,0]
	v_and_b32_e32 v119, 0xffff0000, v119
	v_pk_fma_f32 v[126:127], v[124:125], v[126:127], s[42:43] op_sel_hi:[1,1,0]
	s_nop 0
	v_pk_fma_f32 v[126:127], v[124:125], v[126:127], s[44:45] op_sel_hi:[1,1,0]
	s_nop 0
	v_pk_fma_f32 v[126:127], v[124:125], v[126:127], s[46:47] op_sel_hi:[1,1,0]
	s_nop 0
	v_pk_fma_f32 v[124:125], v[124:125], v[126:127], s[48:49] op_sel_hi:[1,1,0]
	s_nop 0
	v_pk_mul_f32 v[120:121], v[120:121], v[124:125]
	s_nop 0
	v_pk_fma_f32 v[114:115], v[114:115], v[120:121], v[114:115]
	v_pk_fma_f32 v[120:121], v[134:135], v[122:123], v[146:147]
	v_pk_mul_f32 v[108:109], v[108:109], v[114:115]
	v_lshlrev_b32_e32 v114, 16, v171
	v_and_b32_e32 v115, 0xffff0000, v171
	v_pk_fma_f32 v[118:119], v[138:139], v[118:119], v[120:121]
	s_nop 0
	v_pk_fma_f32 v[114:115], v[142:143], v[114:115], v[118:119]
	s_nop 0
	v_pk_mul_f32 v[118:119], v[114:115], s[30:31] op_sel_hi:[1,0]
	v_pk_mul_f32 v[114:115], v[114:115], 0.5 op_sel_hi:[1,0]
	v_med3_f32 v118, v118, s47, v225
	v_med3_f32 v119, v119, s47, v225
	v_pk_mul_f32 v[120:121], v[118:119], v[118:119]
	s_nop 0
	v_pk_fma_f32 v[122:123], v[120:121], s[34:35], v[210:211] op_sel_hi:[1,0,0] neg_lo:[1,0,0] neg_hi:[1,0,0]
	s_nop 0
	v_pk_fma_f32 v[122:123], v[120:121], v[122:123], s[38:39] op_sel_hi:[1,1,0]
	s_nop 0
	v_pk_fma_f32 v[122:123], v[120:121], v[122:123], s[40:41] op_sel_hi:[1,1,0]
	s_nop 0
	v_pk_fma_f32 v[122:123], v[120:121], v[122:123], s[42:43] op_sel_hi:[1,1,0]
	s_nop 0
	v_pk_fma_f32 v[122:123], v[120:121], v[122:123], s[44:45] op_sel_hi:[1,1,0]
	s_nop 0
	v_pk_fma_f32 v[122:123], v[120:121], v[122:123], s[46:47] op_sel_hi:[1,1,0]
	s_nop 0
	v_pk_fma_f32 v[120:121], v[120:121], v[122:123], s[48:49] op_sel_hi:[1,1,0]
	s_nop 0
	v_pk_mul_f32 v[118:119], v[118:119], v[120:121]
	s_nop 0
	v_pk_fma_f32 v[114:115], v[114:115], v[118:119], v[114:115]
	v_lshlrev_b32_e32 v118, 16, v164
	v_pk_mul_f32 v[110:111], v[110:111], v[114:115]
	v_cvt_pk_bf16_f32 v114, v108, v109
	v_lshl_add_u64 v[108:109], v[172:173], 0, v[180:181]
	v_cvt_pk_bf16_f32 v115, v110, v111
	global_store_dwordx4 v[108:109], v[112:115], off
;     static __device__ __forceinline__ void unpk4(const u32x2 w, float (&o)[4]) { o[0] = bf_lo(w.x); o[1] = bf_hi(w.x); o[2] = bf_lo(w.y); o[3] = bf_hi(w.y); }
;     template <int N> static __device__ __forceinline__ u32x2 dpp_prev(const u32x2 pv, const u32x2 cur) { u32x2 r; r.x = dpp_prev1<N>(pv.x, cur.x); r.y = dpp_prev1<N>(pv.y, cur.y); return r; }
; __device__ __forceinline__ f32x2 gelu_pk(f32x2 v) {
;     f32x2 x = v * 0.70710678118f;
;     x.x = __builtin_amdgcn_fmed3f(x.x, -2.9f, 2.9f); x.y = __builtin_amdgcn_fmed3f(x.y, -2.9f, 2.9f);
;     const f32x2 t = x * x;
;     f32x2 p = t * (-4.953124630e-07f) + 1.987094038e-05f;
;     p = p * t + (-3.472001117e-04f); p = p * t + 3.517547622e-03f; p = p * t + (-2.333305031e-02f); p = p * t + 1.087993085e-01f; p = p * t + (-3.740358949e-01f); p = p * t + 1.128076553e+00f;
;     const f32x2 hv = v * 0.5f;
;     return hv * (x * p) + hv;
; }
;     __device__ __forceinline__ void operator()(const f32x4 (&acc)[2][2][4][2], const Unit& u, int wr, int wc, int fr, int fq) const {
;     ...
;                 for (int m = 0; m < 4; ++m) { const u32x4 cur = gq[m]; u32x4 hw;
; #pragma unroll
;                     for (int hv = 0; hv < 2; ++hv) { const u32x2 c2 = half2(cur, hv), p2 = half2(pv, hv);
;                         const u32x2 q1 = dpp_prev<1>(p2, c2), q2 = dpp_prev<2>(p2, c2);
;                         float g0[4], g1[4], g2[4]; unpk4(c2, g0); unpk4(q1, g1); unpk4(q2, g2);
;                         const u32x2 r = finish2(g0, g1, g2, w0[hv], w1[hv], w2[hv], bb[hv], acc[ai][bj][m][hv], rs8[ai][m]);
;                         if (hv == 0) { hw.x = r.x; hw.y = r.y; } else { hw.z = r.x; hw.w = r.y; } }
	v_and_b32_e32 v119, 0xffff0000, v164
	v_mov_b32_dpp v109, v168 row_ror:1 row_mask:0xf bank_mask:0xf bound_ctrl:1
	v_mov_b32_dpp v113, v168 row_ror:2 row_mask:0xf bank_mask:0xf bound_ctrl:1
	v_mov_b32_dpp v115, v169 row_ror:2 row_mask:0xf bank_mask:0xf bound_ctrl:1
	v_mov_b32_dpp v109, v164 row_shr:1 row_mask:0xf bank_mask:0xf
	v_mov_b32_dpp v113, v164 row_shr:2 row_mask:0xf bank_mask:0xf
	v_lshlrev_b32_e32 v112, 16, v113
	v_and_b32_e32 v113, 0xffff0000, v113
	v_lshlrev_b32_e32 v108, 16, v109
	v_and_b32_e32 v109, 0xffff0000, v109
	v_pk_fma_f32 v[112:113], v[148:149], v[112:113], v[160:161]
	v_mov_b32_dpp v111, v169 row_ror:1 row_mask:0xf bank_mask:0xf bound_ctrl:1
	v_pk_fma_f32 v[108:109], v[152:153], v[108:109], v[112:113]
	v_mov_b32_dpp v115, v165 row_shr:2 row_mask:0xf bank_mask:0xf
	v_pk_fma_f32 v[108:109], v[156:157], v[118:119], v[108:109]
	v_mov_b32_dpp v111, v165 row_shr:1 row_mask:0xf bank_mask:0xf
	v_pk_mul_f32 v[112:113], v[108:109], s[30:31] op_sel_hi:[1,0]
	v_lshlrev_b32_e32 v114, 16, v115
	v_med3_f32 v112, v112, s47, v225
	v_med3_f32 v113, v113, s47, v225
	v_pk_mul_f32 v[118:119], v[112:113], v[112:113]
	v_and_b32_e32 v115, 0xffff0000, v115
	v_pk_fma_f32 v[120:121], v[118:119], s[34:35], v[210:211] op_sel_hi:[1,0,0] neg_lo:[1,0,0] neg_hi:[1,0,0]
	v_pk_mul_f32 v[108:109], v[108:109], 0.5 op_sel_hi:[1,0]
	v_pk_fma_f32 v[120:121], v[118:119], v[120:121], s[38:39] op_sel_hi:[1,1,0]
	v_lshlrev_b32_e32 v110, 16, v111
	v_pk_fma_f32 v[120:121], v[118:119], v[120:121], s[40:41] op_sel_hi:[1,1,0]
	v_and_b32_e32 v111, 0xffff0000, v111
	v_pk_fma_f32 v[120:121], v[118:119], v[120:121], s[42:43] op_sel_hi:[1,1,0]
	s_nop 0
	v_pk_fma_f32 v[120:121], v[118:119], v[120:121], s[44:45] op_sel_hi:[1,1,0]
	s_nop 0
	v_pk_fma_f32 v[120:121], v[118:119], v[120:121], s[46:47] op_sel_hi:[1,1,0]
	s_nop 0
	v_pk_fma_f32 v[118:119], v[118:119], v[120:121], s[48:49] op_sel_hi:[1,1,0]
	s_nop 0
	v_pk_mul_f32 v[112:113], v[112:113], v[118:119]
	s_nop 0
	v_pk_fma_f32 v[108:109], v[108:109], v[112:113], v[108:109]
	v_pk_fma_f32 v[112:113], v[150:151], v[114:115], v[162:163]
	v_pk_mul_f32 v[104:105], v[104:105], v[108:109]
	v_lshlrev_b32_e32 v108, 16, v165
	v_and_b32_e32 v109, 0xffff0000, v165
	v_pk_fma_f32 v[110:111], v[154:155], v[110:111], v[112:113]
	v_cvt_pk_bf16_f32 v120, v104, v105
	v_mov_b32_dpp v105, v170 row_ror:1 row_mask:0xf bank_mask:0xf bound_ctrl:1
	v_pk_fma_f32 v[108:109], v[158:159], v[108:109], v[110:111]
	s_nop 0
	v_pk_mul_f32 v[110:111], v[108:109], s[30:31] op_sel_hi:[1,0]
	v_pk_mul_f32 v[108:109], v[108:109], 0.5 op_sel_hi:[1,0]
	v_med3_f32 v110, v110, s47, v225
	v_med3_f32 v111, v111, s47, v225
	v_pk_mul_f32 v[112:113], v[110:111], v[110:111]
	v_mov_b32_dpp v105, v166 row_shr:1 row_mask:0xf bank_mask:0xf
	v_pk_fma_f32 v[114:115], v[112:113], s[34:35], v[210:211] op_sel_hi:[1,0,0] neg_lo:[1,0,0] neg_hi:[1,0,0]
	v_lshlrev_b32_e32 v104, 16, v105
	v_pk_fma_f32 v[114:115], v[112:113], v[114:115], s[38:39] op_sel_hi:[1,1,0]
	v_and_b32_e32 v105, 0xffff0000, v105
	v_pk_fma_f32 v[114:115], v[112:113], v[114:115], s[40:41] op_sel_hi:[1,1,0]
	s_nop 0
	v_pk_fma_f32 v[114:115], v[112:113], v[114:115], s[42:43] op_sel_hi:[1,1,0]
	s_nop 0
	v_pk_fma_f32 v[114:115], v[112:113], v[114:115], s[44:45] op_sel_hi:[1,1,0]
	s_nop 0
	v_pk_fma_f32 v[114:115], v[112:113], v[114:115], s[46:47] op_sel_hi:[1,1,0]
	s_nop 0
	v_pk_fma_f32 v[112:113], v[112:113], v[114:115], s[48:49] op_sel_hi:[1,1,0]
	s_nop 0
	v_pk_mul_f32 v[110:111], v[110:111], v[112:113]
	v_lshlrev_b32_e32 v112, 16, v166
	v_pk_fma_f32 v[108:109], v[108:109], v[110:111], v[108:109]
	v_and_b32_e32 v113, 0xffff0000, v166
	v_pk_mul_f32 v[106:107], v[106:107], v[108:109]
	v_mov_b32_dpp v109, v170 row_ror:2 row_mask:0xf bank_mask:0xf bound_ctrl:1
	v_mov_b32_dpp v111, v171 row_ror:2 row_mask:0xf bank_mask:0xf bound_ctrl:1
	v_cvt_pk_bf16_f32 v121, v106, v107
	v_mov_b32_dpp v107, v171 row_ror:1 row_mask:0xf bank_mask:0xf bound_ctrl:1
;     static __device__ __forceinline__ void unpk4(const u32x2 w, float (&o)[4]) { o[0] = bf_lo(w.x); o[1] = bf_hi(w.x); o[2] = bf_lo(w.y); o[3] = bf_hi(w.y); }
;     template <int N> static __device__ __forceinline__ u32x2 dpp_prev(const u32x2 pv, const u32x2 cur) { u32x2 r; r.x = dpp_prev1<N>(pv.x, cur.x); r.y = dpp_prev1<N>(pv.y, cur.y); return r; }
;     __device__ __forceinline__ void operator()(const f32x4 (&acc)[2][2][4][2], const Unit& u, int wr, int wc, int fr, int fq) const {
;     ...
;             for (int ai = 0; ai < 2; ++ai) { const int R0 = u.rb + ai * HALF + wr * 64; const bf16_t* gp = G + (size_t)(R0 + fr) * 2816 + col8;
;                 u32x4 gq[4], prv = (u32x4){0u, 0u, 0u, 0u};
; #pragma unroll
;                 for (int m = 0; m < 4; ++m) gq[m] = *(const u32x4*)(gp + (size_t)m * 16 * 2816);
;                 if ((R0 & 8191) != 0) prv = *(const u32x4*)(gp - (size_t)16 * 2816);
;                 u32x4 pv = prv;
; #pragma unroll
;                 for (int m = 0; m < 4; ++m) { const u32x4 cur = gq[m]; u32x4 hw;
; #pragma unroll
;                     for (int hv = 0; hv < 2; ++hv) { const u32x2 c2 = half2(cur, hv), p2 = half2(pv, hv);
;                         const u32x2 q1 = dpp_prev<1>(p2, c2), q2 = dpp_prev<2>(p2, c2);
;                         float g0[4], g1[4], g2[4]; unpk4(c2, g0); unpk4(q1, g1); unpk4(q2, g2);
;                         const u32x2 r = finish2(g0, g1, g2, w0[hv], w1[hv], w2[hv], bb[hv], acc[ai][bj][m][hv], rs8[ai][m]);
;                         if (hv == 0) { hw.x = r.x; hw.y = r.y; } else { hw.z = r.x; hw.w = r.y; } }
;                     *(u32x4*)(H + (size_t)(R0 + fr + 16 * m) * 2816 + col8) = hw;
;                     pv = cur; } }
	v_mov_b32_dpp v109, v166 row_shr:2 row_mask:0xf bank_mask:0xf
	v_lshlrev_b32_e32 v108, 16, v109
	v_and_b32_e32 v109, 0xffff0000, v109
	v_pk_fma_f32 v[108:109], v[132:133], v[108:109], v[144:145]
	v_mov_b32_dpp v111, v167 row_shr:2 row_mask:0xf bank_mask:0xf
	v_pk_fma_f32 v[104:105], v[136:137], v[104:105], v[108:109]
	v_mov_b32_dpp v107, v167 row_shr:1 row_mask:0xf bank_mask:0xf
	v_pk_fma_f32 v[104:105], v[140:141], v[112:113], v[104:105]
	v_lshlrev_b32_e32 v110, 16, v111
	v_pk_mul_f32 v[108:109], v[104:105], s[30:31] op_sel_hi:[1,0]
	v_and_b32_e32 v111, 0xffff0000, v111
	v_med3_f32 v108, v108, s47, v225
	v_med3_f32 v109, v109, s47, v225
	v_pk_mul_f32 v[112:113], v[108:109], v[108:109]
	v_pk_mul_f32 v[104:105], v[104:105], 0.5 op_sel_hi:[1,0]
	v_pk_fma_f32 v[114:115], v[112:113], s[34:35], v[210:211] op_sel_hi:[1,0,0] neg_lo:[1,0,0] neg_hi:[1,0,0]
	v_lshlrev_b32_e32 v106, 16, v107
	v_pk_fma_f32 v[114:115], v[112:113], v[114:115], s[38:39] op_sel_hi:[1,1,0]
	v_and_b32_e32 v107, 0xffff0000, v107
	v_pk_fma_f32 v[114:115], v[112:113], v[114:115], s[40:41] op_sel_hi:[1,1,0]
	s_nop 0
	v_pk_fma_f32 v[114:115], v[112:113], v[114:115], s[42:43] op_sel_hi:[1,1,0]
	s_nop 0
	v_pk_fma_f32 v[114:115], v[112:113], v[114:115], s[44:45] op_sel_hi:[1,1,0]
	s_nop 0
	v_pk_fma_f32 v[114:115], v[112:113], v[114:115], s[46:47] op_sel_hi:[1,1,0]
	s_nop 0
	v_pk_fma_f32 v[112:113], v[112:113], v[114:115], s[48:49] op_sel_hi:[1,1,0]
	s_nop 0
	v_pk_mul_f32 v[108:109], v[108:109], v[112:113]
	s_nop 0
	v_pk_fma_f32 v[104:105], v[104:105], v[108:109], v[104:105]
	v_pk_fma_f32 v[108:109], v[134:135], v[110:111], v[146:147]
	v_pk_mul_f32 v[100:101], v[100:101], v[104:105]
	v_lshlrev_b32_e32 v104, 16, v167
	v_and_b32_e32 v105, 0xffff0000, v167
	v_pk_fma_f32 v[106:107], v[138:139], v[106:107], v[108:109]
	v_cvt_pk_bf16_f32 v122, v100, v101
	v_mov_b64_e32 v[100:101], s[2:3]
	v_pk_fma_f32 v[104:105], v[142:143], v[104:105], v[106:107]
	v_mad_i64_i32 v[164:165], s[2:3], v1, s91, v[100:101]
	v_pk_mul_f32 v[106:107], v[104:105], s[30:31] op_sel_hi:[1,0]
	v_lshl_add_u64 v[118:119], v[164:165], 0, v[180:181]
	v_med3_f32 v106, v106, s47, v225
	v_med3_f32 v107, v107, s47, v225
	v_pk_mul_f32 v[108:109], v[106:107], v[106:107]
	v_pk_mul_f32 v[104:105], v[104:105], 0.5 op_sel_hi:[1,0]
	v_pk_fma_f32 v[110:111], v[108:109], s[34:35], v[210:211] op_sel_hi:[1,0,0] neg_lo:[1,0,0] neg_hi:[1,0,0]
	v_add_co_u32_e32 v100, vcc, s10, v118
	v_pk_fma_f32 v[110:111], v[108:109], v[110:111], s[38:39] op_sel_hi:[1,1,0]
	s_nop 0
	v_addc_co_u32_e32 v101, vcc, 0, v119, vcc
	v_pk_fma_f32 v[110:111], v[108:109], v[110:111], s[40:41] op_sel_hi:[1,1,0]
	v_mad_i64_i32 v[166:167], s[2:3], v190, s91, v[116:117]
	v_pk_fma_f32 v[110:111], v[108:109], v[110:111], s[42:43] op_sel_hi:[1,1,0]
	v_lshl_add_u64 v[116:117], v[166:167], 0, v[180:181]
	v_pk_fma_f32 v[110:111], v[108:109], v[110:111], s[44:45] op_sel_hi:[1,1,0]
	s_cselect_b64 s[2:3], -1, 0
	v_pk_fma_f32 v[110:111], v[108:109], v[110:111], s[46:47] op_sel_hi:[1,1,0]
	s_cmp_eq_u32 s7, 0
	v_pk_fma_f32 v[108:109], v[108:109], v[110:111], s[48:49] op_sel_hi:[1,1,0]
	s_nop 0
	v_pk_mul_f32 v[106:107], v[106:107], v[108:109]
	s_nop 0
	v_pk_fma_f32 v[104:105], v[104:105], v[106:107], v[104:105]
	s_nop 0
	v_pk_mul_f32 v[102:103], v[102:103], v[104:105]
	s_nop 0
	v_cvt_pk_bf16_f32 v123, v102, v103
	global_load_dwordx4 v[112:115], v[118:119], off nt
	global_load_dwordx4 v[108:111], v[100:101], off nt
	v_add_co_u32_e32 v100, vcc, 0x2c000, v118
	s_nop 1
	v_addc_co_u32_e32 v101, vcc, 0, v119, vcc
	v_add_co_u32_e32 v102, vcc, 0x42000, v118
	s_nop 1
	v_addc_co_u32_e32 v103, vcc, 0, v119, vcc
	global_load_dwordx4 v[104:107], v[100:101], off nt
	s_nop 0
	global_load_dwordx4 v[100:103], v[102:103], off nt
	s_nop 0
	global_store_dwordx4 v[116:117], v[120:123], off
	s_cbranch_scc1 .LBB0_1015
	v_add_co_u32_e32 v116, vcc, 0xfffea000, v118
	s_nop 1
	v_addc_co_u32_e32 v117, vcc, -1, v119, vcc
	global_load_dwordx4 v[116:119], v[116:117], off nt
	s_branch .LBB0_1016

;     static __device__ __forceinline__ void unpk4(const u32x2 w, float (&o)[4]) { o[0] = bf_lo(w.x); o[1] = bf_hi(w.x); o[2] = bf_lo(w.y); o[3] = bf_hi(w.y); }
;     template <int N> static __device__ __forceinline__ u32x2 dpp_prev(const u32x2 pv, const u32x2 cur) { u32x2 r; r.x = dpp_prev1<N>(pv.x, cur.x); r.y = dpp_prev1<N>(pv.y, cur.y); return r; }
;     __device__ __forceinline__ void operator()(const f32x4 (&acc)[2][2][4][2], const Unit& u, int wr, int wc, int fr, int fq) const {
;     ...
;             for (int m = 0; m < 4; ++m) rs8[ai][m] = rsqrtf(SS[u.rb + (u.half ? 0 : ai * HALF) + wr * 64 + fr + 16 * m] * (1.f / 1024.f) + 1e-6f);
;         if (u.pm < 128) {
; #pragma unroll
;           for (int bj = 0; bj < 2; ++bj) {
;             const int col8 = u.pn * BM + bj * HALF + wc * 32 + 8 * fq;
;             float w0[2][4], w1[2][4], w2[2][4], bb[2][4];
; #pragma unroll
;             for (int hv = 0; hv < 2; ++hv) { ld4f(cw + col8 + 4 * hv, w0[hv]); ld4f(cw + 2816 + col8 + 4 * hv, w1[hv]); ld4f(cw + 2 * 2816 + col8 + 4 * hv, w2[hv]); ld4f(cb + col8 + 4 * hv, bb[hv]); }
; #pragma unroll
;             for (int ai = 0; ai < 2; ++ai) { const int R0 = u.rb + ai * HALF + wr * 64; const bf16_t* gp = G + (size_t)(R0 + fr) * 2816 + col8;
;                 u32x4 gq[4], prv = (u32x4){0u, 0u, 0u, 0u};
; #pragma unroll
;                 for (int m = 0; m < 4; ++m) gq[m] = *(const u32x4*)(gp + (size_t)m * 16 * 2816);
;                 if ((R0 & 8191) != 0) prv = *(const u32x4*)(gp - (size_t)16 * 2816);
;                 u32x4 pv = prv;
; #pragma unroll
;                 for (int m = 0; m < 4; ++m) { const u32x4 cur = gq[m]; u32x4 hw;
; #pragma unroll
;                     for (int hv = 0; hv < 2; ++hv) { const u32x2 c2 = half2(cur, hv), p2 = half2(pv, hv);
;                         const u32x2 q1 = dpp_prev<1>(p2, c2), q2 = dpp_prev<2>(p2, c2);
;                         float g0[4], g1[4], g2[4]; unpk4(c2, g0); unpk4(q1, g1); unpk4(q2, g2);
;                         const u32x2 r = finish2(g0, g1, g2, w0[hv], w1[hv], w2[hv], bb[hv], acc[ai][bj][m][hv], rs8[ai][m]);
;                         if (hv == 0) { hw.x = r.x; hw.y = r.y; } else { hw.z = r.x; hw.w = r.y; } }
.LBB0_1016:
	v_fmamk_f32 v122, v189, 0x3a800000, v224
	v_cmp_gt_f32_e32 vcc, s5, v122
	v_mul_f32_e32 v123, 0x4b800000, v122
	v_fmamk_f32 v3, v3, 0x3a800000, v224
	v_cndmask_b32_e32 v122, v122, v123, vcc
	v_rsq_f32_e32 v122, v122
	s_waitcnt vmcnt(0)
	v_mov_b32_dpp v125, v116 row_ror:2 row_mask:0xf bank_mask:0xf bound_ctrl:1
	v_mov_b32_dpp v127, v117 row_ror:2 row_mask:0xf bank_mask:0xf bound_ctrl:1
	v_lshlrev_b32_e32 v178, 16, v112
	v_mul_f32_e32 v123, 0x45800000, v122
	v_cndmask_b32_e32 v128, v122, v123, vcc
	v_fmamk_f32 v122, v187, 0x3a800000, v224
	v_cmp_gt_f32_e32 vcc, s5, v122
	v_mul_f32_e32 v123, 0x4b800000, v122
	v_mov_b32_dpp v125, v112 row_shr:2 row_mask:0xf bank_mask:0xf
	v_cndmask_b32_e32 v122, v122, v123, vcc
	v_rsq_f32_e32 v122, v122
	v_lshlrev_b32_e32 v170, 16, v125
	v_and_b32_e32 v171, 0xffff0000, v125
	v_pk_fma_f32 v[170:171], v[148:149], v[170:171], v[160:161]
	v_mul_f32_e32 v123, 0x45800000, v122
	v_cndmask_b32_e32 v126, v122, v123, vcc
	v_cmp_gt_f32_e32 vcc, s5, v3
	v_mul_f32_e32 v122, 0x4b800000, v3
	v_mov_b32_dpp v123, v117 row_ror:1 row_mask:0xf bank_mask:0xf bound_ctrl:1
	v_cndmask_b32_e32 v3, v3, v122, vcc
	v_rsq_f32_e32 v3, v3
	v_and_b32_e32 v179, 0xffff0000, v112
	v_mov_b32_dpp v127, v113 row_shr:2 row_mask:0xf bank_mask:0xf
	v_mov_b32_dpp v123, v113 row_shr:1 row_mask:0xf bank_mask:0xf
	v_mul_f32_e32 v122, 0x45800000, v3
	v_cndmask_b32_e32 v124, v3, v122, vcc
	v_fmamk_f32 v3, v185, 0x3a800000, v224
	v_cmp_gt_f32_e32 vcc, s5, v3
	v_mul_f32_e32 v122, 0x4b800000, v3
	v_lshlrev_b32_e32 v174, 16, v127
	v_cndmask_b32_e32 v3, v3, v122, vcc
	v_rsq_f32_e32 v3, v3
	v_and_b32_e32 v175, 0xffff0000, v127
	v_lshlrev_b32_e32 v168, 16, v123
	v_and_b32_e32 v169, 0xffff0000, v123
	v_mul_f32_e32 v122, 0x45800000, v3
	v_cndmask_b32_e32 v122, v3, v122, vcc
	v_mov_b32_dpp v3, v116 row_ror:1 row_mask:0xf bank_mask:0xf bound_ctrl:1
	v_pk_mul_f32 v[96:97], v[96:97], v[128:129] op_sel_hi:[1,0]
	v_pk_fma_f32 v[174:175], v[150:151], v[174:175], v[162:163]
	v_mov_b32_dpp v3, v112 row_shr:1 row_mask:0xf bank_mask:0xf
	v_lshlrev_b32_e32 v116, 16, v3
	v_and_b32_e32 v117, 0xffff0000, v3
	v_pk_fma_f32 v[116:117], v[152:153], v[116:117], v[170:171]
	v_pk_fma_f32 v[168:169], v[154:155], v[168:169], v[174:175]
	v_pk_fma_f32 v[170:171], v[156:157], v[178:179], v[116:117]
	v_mov_b32_dpp v125, v118 row_ror:2 row_mask:0xf bank_mask:0xf bound_ctrl:1
	v_pk_mul_f32 v[116:117], v[170:171], s[30:31] op_sel_hi:[1,0]
	v_pk_mul_f32 v[170:171], v[170:171], 0.5 op_sel_hi:[1,0]
	v_med3_f32 v178, v116, s47, v225
	v_med3_f32 v179, v117, s47, v225
	v_pk_mul_f32 v[182:183], v[178:179], v[178:179]
	v_mov_b64_e32 v[116:117], s[36:37]
	v_pk_fma_f32 v[190:191], v[182:183], s[34:35], v[116:117] op_sel_hi:[1,0,0] neg_lo:[1,0,0] neg_hi:[1,0,0]
	v_pk_mul_f32 v[98:99], v[98:99], v[128:129] op_sel_hi:[1,0]
	v_pk_fma_f32 v[190:191], v[182:183], v[190:191], s[38:39] op_sel_hi:[1,1,0]
	v_mov_b32_dpp v3, v118 row_ror:1 row_mask:0xf bank_mask:0xf bound_ctrl:1
	v_pk_fma_f32 v[190:191], v[182:183], v[190:191], s[40:41] op_sel_hi:[1,1,0]
	v_mov_b32_dpp v125, v114 row_shr:2 row_mask:0xf bank_mask:0xf
	v_pk_fma_f32 v[190:191], v[182:183], v[190:191], s[42:43] op_sel_hi:[1,1,0]
	v_mov_b32_dpp v3, v114 row_shr:1 row_mask:0xf bank_mask:0xf
	v_pk_fma_f32 v[190:191], v[182:183], v[190:191], s[44:45] op_sel_hi:[1,1,0]
	v_mov_b32_dpp v127, v119 row_ror:2 row_mask:0xf bank_mask:0xf bound_ctrl:1
	v_pk_fma_f32 v[190:191], v[182:183], v[190:191], s[46:47] op_sel_hi:[1,1,0]
	v_mov_b32_dpp v123, v119 row_ror:1 row_mask:0xf bank_mask:0xf bound_ctrl:1
	v_pk_fma_f32 v[182:183], v[182:183], v[190:191], s[48:49] op_sel_hi:[1,1,0]
	v_mov_b32_dpp v127, v115 row_shr:2 row_mask:0xf bank_mask:0xf
	v_pk_mul_f32 v[178:179], v[178:179], v[182:183]
	v_mov_b32_dpp v123, v115 row_shr:1 row_mask:0xf bank_mask:0xf
	v_pk_fma_f32 v[170:171], v[170:171], v[178:179], v[170:171]
	v_lshlrev_b32_e32 v118, 16, v123
	v_pk_mul_f32 v[96:97], v[96:97], v[170:171]
	v_lshlrev_b32_e32 v170, 16, v113
	v_and_b32_e32 v171, 0xffff0000, v113
	v_pk_fma_f32 v[168:169], v[158:159], v[170:171], v[168:169]
	v_cvt_pk_bf16_f32 v96, v96, v97
	v_and_b32_e32 v119, 0xffff0000, v123
	v_pk_mul_f32 v[170:171], v[168:169], s[30:31] op_sel_hi:[1,0]
	v_pk_mul_f32 v[168:169], v[168:169], 0.5 op_sel_hi:[1,0]
	v_med3_f32 v170, v170, s47, v225
	v_med3_f32 v171, v171, s47, v225
	v_pk_mul_f32 v[174:175], v[170:171], v[170:171]
	v_pk_mul_f32 v[92:93], v[92:93], v[128:129] op_sel_hi:[1,0]
	v_pk_fma_f32 v[178:179], v[174:175], s[34:35], v[116:117] op_sel_hi:[1,0,0] neg_lo:[1,0,0] neg_hi:[1,0,0]
	v_mad_i64_i32 v[120:121], s[8:9], v1, s91, 0
	v_pk_fma_f32 v[178:179], v[174:175], v[178:179], s[38:39] op_sel_hi:[1,1,0]
	v_readlane_b32 s8, v240, 58
	v_pk_fma_f32 v[178:179], v[174:175], v[178:179], s[40:41] op_sel_hi:[1,1,0]
	v_readlane_b32 s9, v240, 59
	v_pk_fma_f32 v[178:179], v[174:175], v[178:179], s[42:43] op_sel_hi:[1,1,0]
	v_pk_mul_f32 v[94:95], v[94:95], v[128:129] op_sel_hi:[1,0]
	v_pk_fma_f32 v[178:179], v[174:175], v[178:179], s[44:45] op_sel_hi:[1,1,0]
	v_pk_mul_f32 v[88:89], v[88:89], v[126:127] op_sel_hi:[1,0]
	v_pk_fma_f32 v[178:179], v[174:175], v[178:179], s[46:47] op_sel_hi:[1,1,0]
	v_pk_mul_f32 v[90:91], v[90:91], v[126:127] op_sel_hi:[1,0]
	v_pk_fma_f32 v[174:175], v[174:175], v[178:179], s[48:49] op_sel_hi:[1,1,0]
	v_pk_mul_f32 v[84:85], v[84:85], v[126:127] op_sel_hi:[1,0]
	v_pk_mul_f32 v[170:171], v[170:171], v[174:175]
	v_lshlrev_b32_e32 v174, 16, v114
	v_pk_fma_f32 v[168:169], v[168:169], v[170:171], v[168:169]
	v_and_b32_e32 v175, 0xffff0000, v114
	v_pk_mul_f32 v[98:99], v[98:99], v[168:169]
	v_lshlrev_b32_e32 v168, 16, v125
;     static __device__ __forceinline__ void unpk4(const u32x2 w, float (&o)[4]) { o[0] = bf_lo(w.x); o[1] = bf_hi(w.x); o[2] = bf_lo(w.y); o[3] = bf_hi(w.y); }
;     template <int N> static __device__ __forceinline__ u32x2 dpp_prev(const u32x2 pv, const u32x2 cur) { u32x2 r; r.x = dpp_prev1<N>(pv.x, cur.x); r.y = dpp_prev1<N>(pv.y, cur.y); return r; }
;     __device__ __forceinline__ void operator()(const f32x4 (&acc)[2][2][4][2], const Unit& u, int wr, int wc, int fr, int fq) const {
;     ...
;                 for (int m = 0; m < 4; ++m) { const u32x4 cur = gq[m]; u32x4 hw;
; #pragma unroll
;                     for (int hv = 0; hv < 2; ++hv) { const u32x2 c2 = half2(cur, hv), p2 = half2(pv, hv);
;                         const u32x2 q1 = dpp_prev<1>(p2, c2), q2 = dpp_prev<2>(p2, c2);
;                         float g0[4], g1[4], g2[4]; unpk4(c2, g0); unpk4(q1, g1); unpk4(q2, g2);
;                         const u32x2 r = finish2(g0, g1, g2, w0[hv], w1[hv], w2[hv], bb[hv], acc[ai][bj][m][hv], rs8[ai][m]);
;                         if (hv == 0) { hw.x = r.x; hw.y = r.y; } else { hw.z = r.x; hw.w = r.y; } }
;                     *(u32x4*)(H + (size_t)(R0 + fr + 16 * m) * 2816 + col8) = hw;
;                     pv = cur; } }
	v_and_b32_e32 v169, 0xffff0000, v125
	v_cvt_pk_bf16_f32 v97, v98, v99
	v_lshlrev_b32_e32 v98, 16, v3
	v_and_b32_e32 v99, 0xffff0000, v3
	v_pk_fma_f32 v[168:169], v[132:133], v[168:169], v[144:145]
	v_lshlrev_b32_e32 v170, 16, v127
	v_pk_fma_f32 v[98:99], v[136:137], v[98:99], v[168:169]
	v_and_b32_e32 v171, 0xffff0000, v127
	v_pk_fma_f32 v[98:99], v[140:141], v[174:175], v[98:99]
	v_mov_b32_dpp v3, v112 row_ror:1 row_mask:0xf bank_mask:0xf bound_ctrl:1
	v_pk_mul_f32 v[168:169], v[98:99], s[30:31] op_sel_hi:[1,0]
	v_pk_mul_f32 v[98:99], v[98:99], 0.5 op_sel_hi:[1,0]
	v_med3_f32 v168, v168, s47, v225
	v_med3_f32 v169, v169, s47, v225
	v_pk_mul_f32 v[174:175], v[168:169], v[168:169]
	v_mov_b32_dpp v3, v108 row_shr:1 row_mask:0xf bank_mask:0xf
	v_pk_fma_f32 v[178:179], v[174:175], s[34:35], v[116:117] op_sel_hi:[1,0,0] neg_lo:[1,0,0] neg_hi:[1,0,0]
	v_pk_mul_f32 v[86:87], v[86:87], v[126:127] op_sel_hi:[1,0]
	v_pk_fma_f32 v[178:179], v[174:175], v[178:179], s[38:39] op_sel_hi:[1,1,0]
	v_pk_mul_f32 v[80:81], v[80:81], v[124:125] op_sel_hi:[1,0]
	v_pk_fma_f32 v[178:179], v[174:175], v[178:179], s[40:41] op_sel_hi:[1,1,0]
	v_pk_mul_f32 v[82:83], v[82:83], v[124:125] op_sel_hi:[1,0]
	v_pk_fma_f32 v[178:179], v[174:175], v[178:179], s[42:43] op_sel_hi:[1,1,0]
	v_pk_mul_f32 v[76:77], v[76:77], v[124:125] op_sel_hi:[1,0]
	v_pk_fma_f32 v[178:179], v[174:175], v[178:179], s[44:45] op_sel_hi:[1,1,0]
	v_pk_mul_f32 v[78:79], v[78:79], v[124:125] op_sel_hi:[1,0]
	v_pk_fma_f32 v[178:179], v[174:175], v[178:179], s[46:47] op_sel_hi:[1,1,0]
	v_pk_mul_f32 v[72:73], v[72:73], v[122:123] op_sel_hi:[1,0]
	v_pk_fma_f32 v[174:175], v[174:175], v[178:179], s[48:49] op_sel_hi:[1,1,0]
	v_pk_mul_f32 v[74:75], v[74:75], v[122:123] op_sel_hi:[1,0]
	v_pk_mul_f32 v[168:169], v[168:169], v[174:175]
	v_pk_mul_f32 v[64:65], v[64:65], v[122:123] op_sel_hi:[1,0]
	v_pk_fma_f32 v[98:99], v[98:99], v[168:169], v[98:99]
	v_pk_fma_f32 v[168:169], v[134:135], v[170:171], v[146:147]
	v_pk_mul_f32 v[92:93], v[92:93], v[98:99]
	v_lshlrev_b32_e32 v98, 16, v115
	v_and_b32_e32 v99, 0xffff0000, v115
	v_pk_fma_f32 v[118:119], v[138:139], v[118:119], v[168:169]
	v_pk_mul_f32 v[66:67], v[66:67], v[122:123] op_sel_hi:[1,0]
	v_pk_fma_f32 v[98:99], v[142:143], v[98:99], v[118:119]
	v_readlane_b32 s52, v240, 62
	v_pk_mul_f32 v[118:119], v[98:99], s[30:31] op_sel_hi:[1,0]
	v_pk_mul_f32 v[98:99], v[98:99], 0.5 op_sel_hi:[1,0]
	v_med3_f32 v118, v118, s47, v225
	v_med3_f32 v119, v119, s47, v225
	v_pk_mul_f32 v[168:169], v[118:119], v[118:119]
	v_readlane_b32 s66, v239, 12
	v_pk_fma_f32 v[170:171], v[168:169], s[34:35], v[116:117] op_sel_hi:[1,0,0] neg_lo:[1,0,0] neg_hi:[1,0,0]
	v_readlane_b32 s67, v239, 13
	v_pk_fma_f32 v[170:171], v[168:169], v[170:171], s[38:39] op_sel_hi:[1,1,0]
	v_readlane_b32 s53, v240, 63
	v_pk_fma_f32 v[170:171], v[168:169], v[170:171], s[40:41] op_sel_hi:[1,1,0]
	v_readlane_b32 s54, v239, 0
	v_pk_fma_f32 v[170:171], v[168:169], v[170:171], s[42:43] op_sel_hi:[1,1,0]
	v_readlane_b32 s55, v239, 1
	v_pk_fma_f32 v[170:171], v[168:169], v[170:171], s[44:45] op_sel_hi:[1,1,0]
	v_readlane_b32 s56, v239, 2
	v_pk_fma_f32 v[170:171], v[168:169], v[170:171], s[46:47] op_sel_hi:[1,1,0]
	v_readlane_b32 s57, v239, 3
	v_pk_fma_f32 v[168:169], v[168:169], v[170:171], s[48:49] op_sel_hi:[1,1,0]
	v_readlane_b32 s58, v239, 4
	v_pk_mul_f32 v[118:119], v[118:119], v[168:169]
	v_lshl_add_u64 v[168:169], s[8:9], 0, v[120:121]
	v_pk_fma_f32 v[98:99], v[98:99], v[118:119], v[98:99]
	v_mov_b32_e32 v120, 0
	v_pk_mul_f32 v[94:95], v[94:95], v[98:99]
	v_cvt_pk_bf16_f32 v98, v92, v93
	v_lshl_add_u64 v[92:93], v[168:169], 0, v[180:181]
	v_cvt_pk_bf16_f32 v99, v94, v95
	global_store_dwordx4 v[92:93], v[96:99], off
	v_lshlrev_b32_e32 v92, 16, v3
	v_and_b32_e32 v93, 0xffff0000, v3
	v_mov_b32_dpp v97, v112 row_ror:2 row_mask:0xf bank_mask:0xf bound_ctrl:1
	v_mov_b32_dpp v95, v113 row_ror:1 row_mask:0xf bank_mask:0xf bound_ctrl:1
	v_mov_b32_dpp v99, v113 row_ror:2 row_mask:0xf bank_mask:0xf bound_ctrl:1
	v_mov_b32_dpp v97, v108 row_shr:2 row_mask:0xf bank_mask:0xf
	v_lshlrev_b32_e32 v96, 16, v97
	v_and_b32_e32 v97, 0xffff0000, v97
	v_pk_fma_f32 v[96:97], v[148:149], v[96:97], v[160:161]
	v_lshlrev_b32_e32 v112, 16, v108
	v_and_b32_e32 v113, 0xffff0000, v108
	v_pk_fma_f32 v[92:93], v[152:153], v[92:93], v[96:97]
	v_mov_b32_dpp v99, v109 row_shr:2 row_mask:0xf bank_mask:0xf
	v_pk_fma_f32 v[92:93], v[156:157], v[112:113], v[92:93]
	v_mov_b32_dpp v95, v109 row_shr:1 row_mask:0xf bank_mask:0xf
	v_pk_mul_f32 v[96:97], v[92:93], s[30:31] op_sel_hi:[1,0]
	v_lshlrev_b32_e32 v98, 16, v99
	v_med3_f32 v96, v96, s47, v225
	v_med3_f32 v97, v97, s47, v225
	v_pk_mul_f32 v[112:113], v[96:97], v[96:97]
	v_and_b32_e32 v99, 0xffff0000, v99
	v_pk_fma_f32 v[118:119], v[112:113], s[34:35], v[116:117] op_sel_hi:[1,0,0] neg_lo:[1,0,0] neg_hi:[1,0,0]
	v_pk_mul_f32 v[92:93], v[92:93], 0.5 op_sel_hi:[1,0]
	v_pk_fma_f32 v[118:119], v[112:113], v[118:119], s[38:39] op_sel_hi:[1,1,0]
	v_lshlrev_b32_e32 v94, 16, v95
	v_pk_fma_f32 v[118:119], v[112:113], v[118:119], s[40:41] op_sel_hi:[1,1,0]
	v_and_b32_e32 v95, 0xffff0000, v95
	v_pk_fma_f32 v[118:119], v[112:113], v[118:119], s[42:43] op_sel_hi:[1,1,0]
	v_mov_b32_dpp v3, v114 row_ror:1 row_mask:0xf bank_mask:0xf bound_ctrl:1
	v_pk_fma_f32 v[118:119], v[112:113], v[118:119], s[44:45] op_sel_hi:[1,1,0]
	v_mov_b32_e32 v121, 0
	v_pk_fma_f32 v[118:119], v[112:113], v[118:119], s[46:47] op_sel_hi:[1,1,0]
	v_mov_b32_dpp v3, v110 row_shr:1 row_mask:0xf bank_mask:0xf
	v_pk_fma_f32 v[112:113], v[112:113], v[118:119], s[48:49] op_sel_hi:[1,1,0]
	v_mov_b32_e32 v118, 0
	v_pk_mul_f32 v[96:97], v[96:97], v[112:113]
;     static __device__ __forceinline__ void unpk4(const u32x2 w, float (&o)[4]) { o[0] = bf_lo(w.x); o[1] = bf_hi(w.x); o[2] = bf_lo(w.y); o[3] = bf_hi(w.y); }
;     template <int N> static __device__ __forceinline__ u32x2 dpp_prev(const u32x2 pv, const u32x2 cur) { u32x2 r; r.x = dpp_prev1<N>(pv.x, cur.x); r.y = dpp_prev1<N>(pv.y, cur.y); return r; }
;     __device__ __forceinline__ void operator()(const f32x4 (&acc)[2][2][4][2], const Unit& u, int wr, int wc, int fr, int fq) const {
;     ...
;                 for (int m = 0; m < 4; ++m) { const u32x4 cur = gq[m]; u32x4 hw;
; #pragma unroll
;                     for (int hv = 0; hv < 2; ++hv) { const u32x2 c2 = half2(cur, hv), p2 = half2(pv, hv);
;                         const u32x2 q1 = dpp_prev<1>(p2, c2), q2 = dpp_prev<2>(p2, c2);
;                         float g0[4], g1[4], g2[4]; unpk4(c2, g0); unpk4(q1, g1); unpk4(q2, g2);
;                         const u32x2 r = finish2(g0, g1, g2, w0[hv], w1[hv], w2[hv], bb[hv], acc[ai][bj][m][hv], rs8[ai][m]);
;                         if (hv == 0) { hw.x = r.x; hw.y = r.y; } else { hw.z = r.x; hw.w = r.y; } }
;                     *(u32x4*)(H + (size_t)(R0 + fr + 16 * m) * 2816 + col8) = hw;
;                     pv = cur; } }
	v_mov_b32_e32 v119, 0
	v_pk_fma_f32 v[92:93], v[92:93], v[96:97], v[92:93]
	v_pk_fma_f32 v[96:97], v[150:151], v[98:99], v[162:163]
	v_pk_mul_f32 v[88:89], v[88:89], v[92:93]
	v_lshlrev_b32_e32 v92, 16, v109
	v_and_b32_e32 v93, 0xffff0000, v109
	v_pk_fma_f32 v[94:95], v[154:155], v[94:95], v[96:97]
	v_cvt_pk_bf16_f32 v88, v88, v89
	v_readlane_b32 s59, v239, 5
	v_pk_fma_f32 v[92:93], v[158:159], v[92:93], v[94:95]
	v_readlane_b32 s60, v239, 6
	v_pk_mul_f32 v[94:95], v[92:93], s[30:31] op_sel_hi:[1,0]
	v_pk_mul_f32 v[92:93], v[92:93], 0.5 op_sel_hi:[1,0]
	v_med3_f32 v94, v94, s47, v225
	v_med3_f32 v95, v95, s47, v225
	v_pk_mul_f32 v[96:97], v[94:95], v[94:95]
	v_readlane_b32 s61, v239, 7
	v_pk_fma_f32 v[98:99], v[96:97], s[34:35], v[116:117] op_sel_hi:[1,0,0] neg_lo:[1,0,0] neg_hi:[1,0,0]
	v_readlane_b32 s62, v239, 8
	v_pk_fma_f32 v[98:99], v[96:97], v[98:99], s[38:39] op_sel_hi:[1,1,0]
	v_readlane_b32 s63, v239, 9
	v_pk_fma_f32 v[98:99], v[96:97], v[98:99], s[40:41] op_sel_hi:[1,1,0]
	v_readlane_b32 s64, v239, 10
	v_pk_fma_f32 v[98:99], v[96:97], v[98:99], s[42:43] op_sel_hi:[1,1,0]
	v_readlane_b32 s65, v239, 11
	v_pk_fma_f32 v[98:99], v[96:97], v[98:99], s[44:45] op_sel_hi:[1,1,0]
	s_nop 0
	v_pk_fma_f32 v[98:99], v[96:97], v[98:99], s[46:47] op_sel_hi:[1,1,0]
	s_nop 0
	v_pk_fma_f32 v[96:97], v[96:97], v[98:99], s[48:49] op_sel_hi:[1,1,0]
	v_lshlrev_b32_e32 v98, 16, v110
	v_pk_mul_f32 v[94:95], v[94:95], v[96:97]
	v_and_b32_e32 v99, 0xffff0000, v110
	v_pk_fma_f32 v[92:93], v[92:93], v[94:95], v[92:93]
	v_mov_b32_dpp v95, v114 row_ror:2 row_mask:0xf bank_mask:0xf bound_ctrl:1
	v_pk_mul_f32 v[90:91], v[90:91], v[92:93]
	v_mov_b32_dpp v97, v115 row_ror:2 row_mask:0xf bank_mask:0xf bound_ctrl:1
	v_mov_b32_dpp v95, v110 row_shr:2 row_mask:0xf bank_mask:0xf
	v_lshlrev_b32_e32 v94, 16, v95
	v_and_b32_e32 v95, 0xffff0000, v95
	v_cvt_pk_bf16_f32 v89, v90, v91
	v_lshlrev_b32_e32 v90, 16, v3
	v_and_b32_e32 v91, 0xffff0000, v3
	v_pk_fma_f32 v[94:95], v[132:133], v[94:95], v[144:145]
	v_mov_b32_dpp v93, v115 row_ror:1 row_mask:0xf bank_mask:0xf bound_ctrl:1
	v_pk_fma_f32 v[90:91], v[136:137], v[90:91], v[94:95]
	v_mov_b32_dpp v97, v111 row_shr:2 row_mask:0xf bank_mask:0xf
	v_pk_fma_f32 v[90:91], v[140:141], v[98:99], v[90:91]
	v_mov_b32_dpp v93, v111 row_shr:1 row_mask:0xf bank_mask:0xf
	v_pk_mul_f32 v[94:95], v[90:91], s[30:31] op_sel_hi:[1,0]
	v_lshlrev_b32_e32 v96, 16, v97
	v_med3_f32 v94, v94, s47, v225
	v_med3_f32 v95, v95, s47, v225
	v_pk_mul_f32 v[98:99], v[94:95], v[94:95]
	v_and_b32_e32 v97, 0xffff0000, v97
	v_pk_fma_f32 v[112:113], v[98:99], s[34:35], v[116:117] op_sel_hi:[1,0,0] neg_lo:[1,0,0] neg_hi:[1,0,0]
	v_pk_mul_f32 v[90:91], v[90:91], 0.5 op_sel_hi:[1,0]
	v_pk_fma_f32 v[112:113], v[98:99], v[112:113], s[38:39] op_sel_hi:[1,1,0]
	v_lshlrev_b32_e32 v92, 16, v93
	v_pk_fma_f32 v[112:113], v[98:99], v[112:113], s[40:41] op_sel_hi:[1,1,0]
	v_and_b32_e32 v93, 0xffff0000, v93
	v_pk_fma_f32 v[112:113], v[98:99], v[112:113], s[42:43] op_sel_hi:[1,1,0]
	v_add_u32_e32 v3, 16, v1
	v_pk_fma_f32 v[112:113], v[98:99], v[112:113], s[44:45] op_sel_hi:[1,1,0]
	s_nop 0
	v_pk_fma_f32 v[112:113], v[98:99], v[112:113], s[46:47] op_sel_hi:[1,1,0]
	s_nop 0
	v_pk_fma_f32 v[98:99], v[98:99], v[112:113], s[48:49] op_sel_hi:[1,1,0]
	s_nop 0
	v_pk_mul_f32 v[94:95], v[94:95], v[98:99]
	s_nop 0
	v_pk_fma_f32 v[90:91], v[90:91], v[94:95], v[90:91]
	v_pk_fma_f32 v[94:95], v[134:135], v[96:97], v[146:147]
	v_pk_mul_f32 v[84:85], v[84:85], v[90:91]
	v_lshlrev_b32_e32 v90, 16, v111
	v_and_b32_e32 v91, 0xffff0000, v111
	v_pk_fma_f32 v[92:93], v[138:139], v[92:93], v[94:95]
	s_nop 0
	v_pk_fma_f32 v[90:91], v[142:143], v[90:91], v[92:93]
	s_nop 0
	v_pk_mul_f32 v[92:93], v[90:91], s[30:31] op_sel_hi:[1,0]
	v_pk_mul_f32 v[90:91], v[90:91], 0.5 op_sel_hi:[1,0]
	v_med3_f32 v92, v92, s47, v225
	v_med3_f32 v93, v93, s47, v225
	v_pk_mul_f32 v[94:95], v[92:93], v[92:93]
	s_nop 0
	v_pk_fma_f32 v[96:97], v[94:95], s[34:35], v[116:117] op_sel_hi:[1,0,0] neg_lo:[1,0,0] neg_hi:[1,0,0]
	s_nop 0
	v_pk_fma_f32 v[96:97], v[94:95], v[96:97], s[38:39] op_sel_hi:[1,1,0]
	s_nop 0
	v_pk_fma_f32 v[96:97], v[94:95], v[96:97], s[40:41] op_sel_hi:[1,1,0]
	s_nop 0
	v_pk_fma_f32 v[96:97], v[94:95], v[96:97], s[42:43] op_sel_hi:[1,1,0]
	s_nop 0
	v_pk_fma_f32 v[96:97], v[94:95], v[96:97], s[44:45] op_sel_hi:[1,1,0]
	s_nop 0
	v_pk_fma_f32 v[96:97], v[94:95], v[96:97], s[46:47] op_sel_hi:[1,1,0]
	s_nop 0
	v_pk_fma_f32 v[94:95], v[94:95], v[96:97], s[48:49] op_sel_hi:[1,1,0]
	s_nop 0
	v_pk_mul_f32 v[92:93], v[92:93], v[94:95]
	v_lshlrev_b32_e32 v94, 16, v104
	v_pk_fma_f32 v[90:91], v[90:91], v[92:93], v[90:91]
	v_and_b32_e32 v95, 0xffff0000, v104
	v_pk_mul_f32 v[86:87], v[86:87], v[90:91]
	v_cvt_pk_bf16_f32 v90, v84, v85
	v_mov_b64_e32 v[84:85], s[8:9]
	v_mad_i64_i32 v[170:171], s[8:9], v3, s91, v[84:85]
	v_cvt_pk_bf16_f32 v91, v86, v87
	v_lshl_add_u64 v[86:87], v[170:171], 0, v[180:181]
	global_store_dwordx4 v[86:87], v[88:91], off
	v_mov_b32_dpp v3, v108 row_ror:1 row_mask:0xf bank_mask:0xf bound_ctrl:1
	v_mov_b32_dpp v93, v109 row_ror:2 row_mask:0xf bank_mask:0xf bound_ctrl:1
	v_mov_b32_dpp v91, v108 row_ror:2 row_mask:0xf bank_mask:0xf bound_ctrl:1
	v_mov_b32_dpp v3, v104 row_shr:1 row_mask:0xf bank_mask:0xf
	v_lshlrev_b32_e32 v86, 16, v3
	v_mov_b32_dpp v91, v104 row_shr:2 row_mask:0xf bank_mask:0xf
	v_lshlrev_b32_e32 v90, 16, v91
	v_and_b32_e32 v91, 0xffff0000, v91
	v_and_b32_e32 v87, 0xffff0000, v3
	v_pk_fma_f32 v[90:91], v[148:149], v[90:91], v[160:161]
	v_mov_b32_dpp v89, v109 row_ror:1 row_mask:0xf bank_mask:0xf bound_ctrl:1
	v_pk_fma_f32 v[86:87], v[152:153], v[86:87], v[90:91]
;     static __device__ __forceinline__ void unpk4(const u32x2 w, float (&o)[4]) { o[0] = bf_lo(w.x); o[1] = bf_hi(w.x); o[2] = bf_lo(w.y); o[3] = bf_hi(w.y); }
;     template <int N> static __device__ __forceinline__ u32x2 dpp_prev(const u32x2 pv, const u32x2 cur) { u32x2 r; r.x = dpp_prev1<N>(pv.x, cur.x); r.y = dpp_prev1<N>(pv.y, cur.y); return r; }
; __device__ __forceinline__ f32x2 gelu_pk(f32x2 v) {
;     f32x2 x = v * 0.70710678118f;
;     x.x = __builtin_amdgcn_fmed3f(x.x, -2.9f, 2.9f); x.y = __builtin_amdgcn_fmed3f(x.y, -2.9f, 2.9f);
;     const f32x2 t = x * x;
;     f32x2 p = t * (-4.953124630e-07f) + 1.987094038e-05f;
;     p = p * t + (-3.472001117e-04f); p = p * t + 3.517547622e-03f; p = p * t + (-2.333305031e-02f); p = p * t + 1.087993085e-01f; p = p * t + (-3.740358949e-01f); p = p * t + 1.128076553e+00f;
;     const f32x2 hv = v * 0.5f;
;     return hv * (x * p) + hv;
; }
;     __device__ __forceinline__ void operator()(const f32x4 (&acc)[2][2][4][2], const Unit& u, int wr, int wc, int fr, int fq) const {
;     ...
;                 for (int m = 0; m < 4; ++m) { const u32x4 cur = gq[m]; u32x4 hw;
; #pragma unroll
;                     for (int hv = 0; hv < 2; ++hv) { const u32x2 c2 = half2(cur, hv), p2 = half2(pv, hv);
;                         const u32x2 q1 = dpp_prev<1>(p2, c2), q2 = dpp_prev<2>(p2, c2);
;                         float g0[4], g1[4], g2[4]; unpk4(c2, g0); unpk4(q1, g1); unpk4(q2, g2);
;                         const u32x2 r = finish2(g0, g1, g2, w0[hv], w1[hv], w2[hv], bb[hv], acc[ai][bj][m][hv], rs8[ai][m]);
;                         if (hv == 0) { hw.x = r.x; hw.y = r.y; } else { hw.z = r.x; hw.w = r.y; } }
	v_mov_b32_dpp v93, v105 row_shr:2 row_mask:0xf bank_mask:0xf
	v_pk_fma_f32 v[86:87], v[156:157], v[94:95], v[86:87]
	v_mov_b32_dpp v89, v105 row_shr:1 row_mask:0xf bank_mask:0xf
	v_pk_mul_f32 v[90:91], v[86:87], s[30:31] op_sel_hi:[1,0]
	v_lshlrev_b32_e32 v92, 16, v93
	v_med3_f32 v90, v90, s47, v225
	v_med3_f32 v91, v91, s47, v225
	v_pk_mul_f32 v[94:95], v[90:91], v[90:91]
	v_and_b32_e32 v93, 0xffff0000, v93
	v_pk_fma_f32 v[96:97], v[94:95], s[34:35], v[116:117] op_sel_hi:[1,0,0] neg_lo:[1,0,0] neg_hi:[1,0,0]
	v_pk_mul_f32 v[86:87], v[86:87], 0.5 op_sel_hi:[1,0]
	v_pk_fma_f32 v[96:97], v[94:95], v[96:97], s[38:39] op_sel_hi:[1,1,0]
	v_lshlrev_b32_e32 v88, 16, v89
	v_pk_fma_f32 v[96:97], v[94:95], v[96:97], s[40:41] op_sel_hi:[1,1,0]
	v_and_b32_e32 v89, 0xffff0000, v89
	v_pk_fma_f32 v[96:97], v[94:95], v[96:97], s[42:43] op_sel_hi:[1,1,0]
	v_mov_b32_dpp v3, v110 row_ror:1 row_mask:0xf bank_mask:0xf bound_ctrl:1
	v_pk_fma_f32 v[96:97], v[94:95], v[96:97], s[44:45] op_sel_hi:[1,1,0]
	s_nop 0
	v_pk_fma_f32 v[96:97], v[94:95], v[96:97], s[46:47] op_sel_hi:[1,1,0]
	v_mov_b32_dpp v3, v106 row_shr:1 row_mask:0xf bank_mask:0xf
	v_pk_fma_f32 v[94:95], v[94:95], v[96:97], s[48:49] op_sel_hi:[1,1,0]
	s_nop 0
	v_pk_mul_f32 v[90:91], v[90:91], v[94:95]
	s_nop 0
	v_pk_fma_f32 v[86:87], v[86:87], v[90:91], v[86:87]
	v_pk_fma_f32 v[90:91], v[150:151], v[92:93], v[162:163]
	v_pk_mul_f32 v[80:81], v[80:81], v[86:87]
	v_lshlrev_b32_e32 v86, 16, v105
	v_and_b32_e32 v87, 0xffff0000, v105
	v_pk_fma_f32 v[88:89], v[154:155], v[88:89], v[90:91]
	v_cvt_pk_bf16_f32 v80, v80, v81
	s_nop 0
	v_pk_fma_f32 v[86:87], v[158:159], v[86:87], v[88:89]
	s_nop 0
	v_pk_mul_f32 v[88:89], v[86:87], s[30:31] op_sel_hi:[1,0]
	v_pk_mul_f32 v[86:87], v[86:87], 0.5 op_sel_hi:[1,0]
	v_med3_f32 v88, v88, s47, v225
	v_med3_f32 v89, v89, s47, v225
	v_pk_mul_f32 v[90:91], v[88:89], v[88:89]
	s_nop 0
	v_pk_fma_f32 v[92:93], v[90:91], s[34:35], v[116:117] op_sel_hi:[1,0,0] neg_lo:[1,0,0] neg_hi:[1,0,0]
	s_nop 0
	v_pk_fma_f32 v[92:93], v[90:91], v[92:93], s[38:39] op_sel_hi:[1,1,0]
	s_nop 0
	v_pk_fma_f32 v[92:93], v[90:91], v[92:93], s[40:41] op_sel_hi:[1,1,0]
	s_nop 0
	v_pk_fma_f32 v[92:93], v[90:91], v[92:93], s[42:43] op_sel_hi:[1,1,0]
	s_nop 0
	v_pk_fma_f32 v[92:93], v[90:91], v[92:93], s[44:45] op_sel_hi:[1,1,0]
	s_nop 0
	v_pk_fma_f32 v[92:93], v[90:91], v[92:93], s[46:47] op_sel_hi:[1,1,0]
	s_nop 0
	v_pk_fma_f32 v[90:91], v[90:91], v[92:93], s[48:49] op_sel_hi:[1,1,0]
	v_lshlrev_b32_e32 v92, 16, v106
	v_pk_mul_f32 v[88:89], v[88:89], v[90:91]
	v_and_b32_e32 v93, 0xffff0000, v106
	v_pk_fma_f32 v[86:87], v[86:87], v[88:89], v[86:87]
	v_mov_b32_dpp v89, v110 row_ror:2 row_mask:0xf bank_mask:0xf bound_ctrl:1
	v_pk_mul_f32 v[82:83], v[82:83], v[86:87]
	v_mov_b32_dpp v91, v111 row_ror:2 row_mask:0xf bank_mask:0xf bound_ctrl:1
	v_mov_b32_dpp v89, v106 row_shr:2 row_mask:0xf bank_mask:0xf
	v_lshlrev_b32_e32 v88, 16, v89
	v_and_b32_e32 v89, 0xffff0000, v89
	v_cvt_pk_bf16_f32 v81, v82, v83
	v_lshlrev_b32_e32 v82, 16, v3
	v_and_b32_e32 v83, 0xffff0000, v3
	v_pk_fma_f32 v[88:89], v[132:133], v[88:89], v[144:145]
	v_mov_b32_dpp v87, v111 row_ror:1 row_mask:0xf bank_mask:0xf bound_ctrl:1
	v_pk_fma_f32 v[82:83], v[136:137], v[82:83], v[88:89]
	v_mov_b32_dpp v91, v107 row_shr:2 row_mask:0xf bank_mask:0xf
	v_pk_fma_f32 v[82:83], v[140:141], v[92:93], v[82:83]
	v_mov_b32_dpp v87, v107 row_shr:1 row_mask:0xf bank_mask:0xf
	v_pk_mul_f32 v[88:89], v[82:83], s[30:31] op_sel_hi:[1,0]
	v_lshlrev_b32_e32 v90, 16, v91
	v_med3_f32 v88, v88, s47, v225
	v_med3_f32 v89, v89, s47, v225
	v_pk_mul_f32 v[92:93], v[88:89], v[88:89]
	v_and_b32_e32 v91, 0xffff0000, v91
	v_pk_fma_f32 v[94:95], v[92:93], s[34:35], v[116:117] op_sel_hi:[1,0,0] neg_lo:[1,0,0] neg_hi:[1,0,0]
	v_pk_mul_f32 v[82:83], v[82:83], 0.5 op_sel_hi:[1,0]
	v_pk_fma_f32 v[94:95], v[92:93], v[94:95], s[38:39] op_sel_hi:[1,1,0]
	v_lshlrev_b32_e32 v86, 16, v87
	v_pk_fma_f32 v[94:95], v[92:93], v[94:95], s[40:41] op_sel_hi:[1,1,0]
	v_and_b32_e32 v87, 0xffff0000, v87
	v_pk_fma_f32 v[94:95], v[92:93], v[94:95], s[42:43] op_sel_hi:[1,1,0]
	v_add_u32_e32 v3, 32, v1
	v_pk_fma_f32 v[94:95], v[92:93], v[94:95], s[44:45] op_sel_hi:[1,1,0]
	v_mad_i64_i32 v[174:175], s[8:9], v3, s91, v[84:85]
	v_pk_fma_f32 v[94:95], v[92:93], v[94:95], s[46:47] op_sel_hi:[1,1,0]
	v_mov_b32_dpp v3, v104 row_ror:1 row_mask:0xf bank_mask:0xf bound_ctrl:1
	v_pk_fma_f32 v[92:93], v[92:93], v[94:95], s[48:49] op_sel_hi:[1,1,0]
	v_add_u32_e32 v1, 48, v1
	v_pk_mul_f32 v[88:89], v[88:89], v[92:93]
	v_mov_b32_dpp v3, v100 row_shr:1 row_mask:0xf bank_mask:0xf
	v_pk_fma_f32 v[82:83], v[82:83], v[88:89], v[82:83]
	v_pk_fma_f32 v[88:89], v[134:135], v[90:91], v[146:147]
	v_pk_mul_f32 v[76:77], v[76:77], v[82:83]
	v_lshlrev_b32_e32 v82, 16, v107
	v_and_b32_e32 v83, 0xffff0000, v107
	v_pk_fma_f32 v[86:87], v[138:139], v[86:87], v[88:89]
	s_nop 0
	v_pk_fma_f32 v[82:83], v[142:143], v[82:83], v[86:87]
	s_nop 0
	v_pk_mul_f32 v[86:87], v[82:83], s[30:31] op_sel_hi:[1,0]
	v_pk_mul_f32 v[82:83], v[82:83], 0.5 op_sel_hi:[1,0]
	v_med3_f32 v86, v86, s47, v225
	v_med3_f32 v87, v87, s47, v225
	v_pk_mul_f32 v[88:89], v[86:87], v[86:87]
	s_nop 0
	v_pk_fma_f32 v[90:91], v[88:89], s[34:35], v[116:117] op_sel_hi:[1,0,0] neg_lo:[1,0,0] neg_hi:[1,0,0]
	s_nop 0
	v_pk_fma_f32 v[90:91], v[88:89], v[90:91], s[38:39] op_sel_hi:[1,1,0]
	s_nop 0
	v_pk_fma_f32 v[90:91], v[88:89], v[90:91], s[40:41] op_sel_hi:[1,1,0]
	s_nop 0
	v_pk_fma_f32 v[90:91], v[88:89], v[90:91], s[42:43] op_sel_hi:[1,1,0]
	s_nop 0
	v_pk_fma_f32 v[90:91], v[88:89], v[90:91], s[44:45] op_sel_hi:[1,1,0]
	s_nop 0
	v_pk_fma_f32 v[90:91], v[88:89], v[90:91], s[46:47] op_sel_hi:[1,1,0]
;     static __device__ __forceinline__ void unpk4(const u32x2 w, float (&o)[4]) { o[0] = bf_lo(w.x); o[1] = bf_hi(w.x); o[2] = bf_lo(w.y); o[3] = bf_hi(w.y); }
;     template <int N> static __device__ __forceinline__ u32x2 dpp_prev(const u32x2 pv, const u32x2 cur) { u32x2 r; r.x = dpp_prev1<N>(pv.x, cur.x); r.y = dpp_prev1<N>(pv.y, cur.y); return r; }
;     __device__ __forceinline__ void operator()(const f32x4 (&acc)[2][2][4][2], const Unit& u, int wr, int wc, int fr, int fq) const {
;     ...
;                 for (int m = 0; m < 4; ++m) { const u32x4 cur = gq[m]; u32x4 hw;
; #pragma unroll
;                     for (int hv = 0; hv < 2; ++hv) { const u32x2 c2 = half2(cur, hv), p2 = half2(pv, hv);
;                         const u32x2 q1 = dpp_prev<1>(p2, c2), q2 = dpp_prev<2>(p2, c2);
;                         float g0[4], g1[4], g2[4]; unpk4(c2, g0); unpk4(q1, g1); unpk4(q2, g2);
;                         const u32x2 r = finish2(g0, g1, g2, w0[hv], w1[hv], w2[hv], bb[hv], acc[ai][bj][m][hv], rs8[ai][m]);
;                         if (hv == 0) { hw.x = r.x; hw.y = r.y; } else { hw.z = r.x; hw.w = r.y; } }
;                     *(u32x4*)(H + (size_t)(R0 + fr + 16 * m) * 2816 + col8) = hw;
;                     pv = cur; } }
	s_nop 0
	v_pk_fma_f32 v[88:89], v[88:89], v[90:91], s[48:49] op_sel_hi:[1,1,0]
	s_nop 0
	v_pk_mul_f32 v[86:87], v[86:87], v[88:89]
	s_nop 0
	v_pk_fma_f32 v[82:83], v[82:83], v[86:87], v[82:83]
	v_lshlrev_b32_e32 v86, 16, v100
	v_pk_mul_f32 v[78:79], v[78:79], v[82:83]
	v_cvt_pk_bf16_f32 v82, v76, v77
	v_lshl_add_u64 v[76:77], v[174:175], 0, v[180:181]
	v_cvt_pk_bf16_f32 v83, v78, v79
	global_store_dwordx4 v[76:77], v[80:83], off
	v_lshlrev_b32_e32 v76, 16, v3
	v_and_b32_e32 v77, 0xffff0000, v3
	v_mov_b32_dpp v81, v104 row_ror:2 row_mask:0xf bank_mask:0xf bound_ctrl:1
	v_and_b32_e32 v87, 0xffff0000, v100
	v_mov_b32_dpp v83, v105 row_ror:2 row_mask:0xf bank_mask:0xf bound_ctrl:1
	v_mov_b32_dpp v81, v100 row_shr:2 row_mask:0xf bank_mask:0xf
	v_lshlrev_b32_e32 v80, 16, v81
	v_and_b32_e32 v81, 0xffff0000, v81
	v_pk_fma_f32 v[80:81], v[148:149], v[80:81], v[160:161]
	v_mov_b32_dpp v79, v105 row_ror:1 row_mask:0xf bank_mask:0xf bound_ctrl:1
	v_pk_fma_f32 v[76:77], v[152:153], v[76:77], v[80:81]
	v_mov_b32_dpp v83, v101 row_shr:2 row_mask:0xf bank_mask:0xf
	v_pk_fma_f32 v[76:77], v[156:157], v[86:87], v[76:77]
	v_mov_b32_dpp v79, v101 row_shr:1 row_mask:0xf bank_mask:0xf
	v_pk_mul_f32 v[80:81], v[76:77], s[30:31] op_sel_hi:[1,0]
	v_lshlrev_b32_e32 v82, 16, v83
	v_med3_f32 v80, v80, s47, v225
	v_med3_f32 v81, v81, s47, v225
	v_pk_mul_f32 v[86:87], v[80:81], v[80:81]
	v_and_b32_e32 v83, 0xffff0000, v83
	v_pk_fma_f32 v[88:89], v[86:87], s[34:35], v[116:117] op_sel_hi:[1,0,0] neg_lo:[1,0,0] neg_hi:[1,0,0]
	v_pk_mul_f32 v[76:77], v[76:77], 0.5 op_sel_hi:[1,0]
	v_pk_fma_f32 v[88:89], v[86:87], v[88:89], s[38:39] op_sel_hi:[1,1,0]
	v_lshlrev_b32_e32 v78, 16, v79
	v_pk_fma_f32 v[88:89], v[86:87], v[88:89], s[40:41] op_sel_hi:[1,1,0]
	v_and_b32_e32 v79, 0xffff0000, v79
	v_pk_fma_f32 v[88:89], v[86:87], v[88:89], s[42:43] op_sel_hi:[1,1,0]
	v_mov_b32_dpp v3, v106 row_ror:1 row_mask:0xf bank_mask:0xf bound_ctrl:1
	v_pk_fma_f32 v[88:89], v[86:87], v[88:89], s[44:45] op_sel_hi:[1,1,0]
	s_nop 0
	v_pk_fma_f32 v[88:89], v[86:87], v[88:89], s[46:47] op_sel_hi:[1,1,0]
	v_mov_b32_dpp v3, v102 row_shr:1 row_mask:0xf bank_mask:0xf
	v_pk_fma_f32 v[86:87], v[86:87], v[88:89], s[48:49] op_sel_hi:[1,1,0]
	s_nop 0
	v_pk_mul_f32 v[80:81], v[80:81], v[86:87]
	s_nop 0
	v_pk_fma_f32 v[76:77], v[76:77], v[80:81], v[76:77]
	v_pk_fma_f32 v[80:81], v[150:151], v[82:83], v[162:163]
	v_pk_mul_f32 v[72:73], v[72:73], v[76:77]
	v_lshlrev_b32_e32 v76, 16, v101
	v_and_b32_e32 v77, 0xffff0000, v101
	v_pk_fma_f32 v[78:79], v[154:155], v[78:79], v[80:81]
	v_cvt_pk_bf16_f32 v72, v72, v73
	s_nop 0
	v_pk_fma_f32 v[76:77], v[158:159], v[76:77], v[78:79]
	s_nop 0
	v_pk_mul_f32 v[78:79], v[76:77], s[30:31] op_sel_hi:[1,0]
	v_pk_mul_f32 v[76:77], v[76:77], 0.5 op_sel_hi:[1,0]
	v_med3_f32 v78, v78, s47, v225
	v_med3_f32 v79, v79, s47, v225
	v_pk_mul_f32 v[80:81], v[78:79], v[78:79]
	s_nop 0
	v_pk_fma_f32 v[82:83], v[80:81], s[34:35], v[116:117] op_sel_hi:[1,0,0] neg_lo:[1,0,0] neg_hi:[1,0,0]
	s_nop 0
	v_pk_fma_f32 v[82:83], v[80:81], v[82:83], s[38:39] op_sel_hi:[1,1,0]
	s_nop 0
	v_pk_fma_f32 v[82:83], v[80:81], v[82:83], s[40:41] op_sel_hi:[1,1,0]
	s_nop 0
	v_pk_fma_f32 v[82:83], v[80:81], v[82:83], s[42:43] op_sel_hi:[1,1,0]
	s_nop 0
	v_pk_fma_f32 v[82:83], v[80:81], v[82:83], s[44:45] op_sel_hi:[1,1,0]
	s_nop 0
	v_pk_fma_f32 v[82:83], v[80:81], v[82:83], s[46:47] op_sel_hi:[1,1,0]
	s_nop 0
	v_pk_fma_f32 v[80:81], v[80:81], v[82:83], s[48:49] op_sel_hi:[1,1,0]
	v_lshlrev_b32_e32 v82, 16, v102
	v_pk_mul_f32 v[78:79], v[78:79], v[80:81]
	v_and_b32_e32 v83, 0xffff0000, v102
	v_pk_fma_f32 v[76:77], v[76:77], v[78:79], v[76:77]
	v_mov_b32_dpp v79, v106 row_ror:2 row_mask:0xf bank_mask:0xf bound_ctrl:1
	v_pk_mul_f32 v[74:75], v[74:75], v[76:77]
	v_mov_b32_dpp v81, v107 row_ror:2 row_mask:0xf bank_mask:0xf bound_ctrl:1
	v_mov_b32_dpp v79, v102 row_shr:2 row_mask:0xf bank_mask:0xf
	v_lshlrev_b32_e32 v78, 16, v79
	v_and_b32_e32 v79, 0xffff0000, v79
	v_cvt_pk_bf16_f32 v73, v74, v75
	v_lshlrev_b32_e32 v74, 16, v3
	v_and_b32_e32 v75, 0xffff0000, v3
	v_pk_fma_f32 v[78:79], v[132:133], v[78:79], v[144:145]
	v_mov_b32_dpp v77, v107 row_ror:1 row_mask:0xf bank_mask:0xf bound_ctrl:1
	v_pk_fma_f32 v[74:75], v[136:137], v[74:75], v[78:79]
	v_mov_b32_dpp v81, v103 row_shr:2 row_mask:0xf bank_mask:0xf
	v_pk_fma_f32 v[74:75], v[140:141], v[82:83], v[74:75]
	v_mov_b32_dpp v77, v103 row_shr:1 row_mask:0xf bank_mask:0xf
	v_pk_mul_f32 v[78:79], v[74:75], s[30:31] op_sel_hi:[1,0]
	v_lshlrev_b32_e32 v80, 16, v81
	v_med3_f32 v78, v78, s47, v225
	v_med3_f32 v79, v79, s47, v225
	v_pk_mul_f32 v[82:83], v[78:79], v[78:79]
	v_and_b32_e32 v81, 0xffff0000, v81
	v_pk_fma_f32 v[86:87], v[82:83], s[34:35], v[116:117] op_sel_hi:[1,0,0] neg_lo:[1,0,0] neg_hi:[1,0,0]
	v_pk_mul_f32 v[74:75], v[74:75], 0.5 op_sel_hi:[1,0]
	v_pk_fma_f32 v[86:87], v[82:83], v[86:87], s[38:39] op_sel_hi:[1,1,0]
	v_lshlrev_b32_e32 v76, 16, v77
	v_pk_fma_f32 v[86:87], v[82:83], v[86:87], s[40:41] op_sel_hi:[1,1,0]
	v_and_b32_e32 v77, 0xffff0000, v77
	v_pk_fma_f32 v[86:87], v[82:83], v[86:87], s[42:43] op_sel_hi:[1,1,0]
	v_mad_i64_i32 v[132:133], s[8:9], v1, s91, v[84:85]
	v_pk_fma_f32 v[86:87], v[82:83], v[86:87], s[44:45] op_sel_hi:[1,1,0]
	v_readlane_b32 s8, v240, 19
	v_pk_fma_f32 v[86:87], v[82:83], v[86:87], s[46:47] op_sel_hi:[1,1,0]
	v_readlane_b32 s9, v240, 20
	v_pk_fma_f32 v[82:83], v[82:83], v[86:87], s[48:49] op_sel_hi:[1,1,0]
	s_nop 0
	v_pk_mul_f32 v[78:79], v[78:79], v[82:83]
	s_nop 0
	v_pk_fma_f32 v[74:75], v[74:75], v[78:79], v[74:75]
	v_pk_fma_f32 v[78:79], v[134:135], v[80:81], v[146:147]
	v_pk_mul_f32 v[64:65], v[64:65], v[74:75]
;     static __device__ __forceinline__ void unpk4(const u32x2 w, float (&o)[4]) { o[0] = bf_lo(w.x); o[1] = bf_hi(w.x); o[2] = bf_lo(w.y); o[3] = bf_hi(w.y); }
;     template <int N> static __device__ __forceinline__ u32x2 dpp_prev(const u32x2 pv, const u32x2 cur) { u32x2 r; r.x = dpp_prev1<N>(pv.x, cur.x); r.y = dpp_prev1<N>(pv.y, cur.y); return r; }
;     __device__ __forceinline__ void operator()(const f32x4 (&acc)[2][2][4][2], const Unit& u, int wr, int wc, int fr, int fq) const {
;     ...
;           for (int bj = 0; bj < 2; ++bj) {
;             const int col8 = u.pn * BM + bj * HALF + wc * 32 + 8 * fq;
;             float w0[2][4], w1[2][4], w2[2][4], bb[2][4];
; #pragma unroll
;             for (int hv = 0; hv < 2; ++hv) { ld4f(cw + col8 + 4 * hv, w0[hv]); ld4f(cw + 2816 + col8 + 4 * hv, w1[hv]); ld4f(cw + 2 * 2816 + col8 + 4 * hv, w2[hv]); ld4f(cb + col8 + 4 * hv, bb[hv]); }
; #pragma unroll
;             for (int ai = 0; ai < 2; ++ai) { const int R0 = u.rb + ai * HALF + wr * 64; const bf16_t* gp = G + (size_t)(R0 + fr) * 2816 + col8;
;                 u32x4 gq[4], prv = (u32x4){0u, 0u, 0u, 0u};
; #pragma unroll
;                 for (int m = 0; m < 4; ++m) gq[m] = *(const u32x4*)(gp + (size_t)m * 16 * 2816);
;                 if ((R0 & 8191) != 0) prv = *(const u32x4*)(gp - (size_t)16 * 2816);
;                 u32x4 pv = prv;
; #pragma unroll
;                 for (int m = 0; m < 4; ++m) { const u32x4 cur = gq[m]; u32x4 hw;
; #pragma unroll
;                     for (int hv = 0; hv < 2; ++hv) { const u32x2 c2 = half2(cur, hv), p2 = half2(pv, hv);
;                         const u32x2 q1 = dpp_prev<1>(p2, c2), q2 = dpp_prev<2>(p2, c2);
;                         float g0[4], g1[4], g2[4]; unpk4(c2, g0); unpk4(q1, g1); unpk4(q2, g2);
;                         const u32x2 r = finish2(g0, g1, g2, w0[hv], w1[hv], w2[hv], bb[hv], acc[ai][bj][m][hv], rs8[ai][m]);
;                         if (hv == 0) { hw.x = r.x; hw.y = r.y; } else { hw.z = r.x; hw.w = r.y; } }
;                     *(u32x4*)(H + (size_t)(R0 + fr + 16 * m) * 2816 + col8) = hw;
;                     pv = cur; } }
	v_lshlrev_b32_e32 v74, 16, v103
	v_and_b32_e32 v75, 0xffff0000, v103
	v_pk_fma_f32 v[76:77], v[138:139], v[76:77], v[78:79]
	v_add_u32_e32 v134, 0x80, v212
	v_pk_fma_f32 v[74:75], v[142:143], v[74:75], v[76:77]
	v_ashrrev_i32_e32 v135, 31, v134
	v_pk_mul_f32 v[76:77], v[74:75], s[30:31] op_sel_hi:[1,0]
	v_pk_mul_f32 v[74:75], v[74:75], 0.5 op_sel_hi:[1,0]
	v_med3_f32 v76, v76, s47, v225
	v_med3_f32 v77, v77, s47, v225
	v_pk_mul_f32 v[78:79], v[76:77], v[76:77]
	v_lshl_add_u64 v[136:137], v[134:135], 1, v[214:215]
	v_pk_fma_f32 v[80:81], v[78:79], s[34:35], v[116:117] op_sel_hi:[1,0,0] neg_lo:[1,0,0] neg_hi:[1,0,0]
	v_add_co_u32_e32 v100, vcc, s10, v136
	v_pk_fma_f32 v[80:81], v[78:79], v[80:81], s[38:39] op_sel_hi:[1,1,0]
	s_nop 0
	v_addc_co_u32_e32 v101, vcc, 0, v137, vcc
	v_pk_fma_f32 v[80:81], v[78:79], v[80:81], s[40:41] op_sel_hi:[1,1,0]
	s_nop 0
	v_pk_fma_f32 v[80:81], v[78:79], v[80:81], s[42:43] op_sel_hi:[1,1,0]
	s_nop 0
	v_pk_fma_f32 v[80:81], v[78:79], v[80:81], s[44:45] op_sel_hi:[1,1,0]
	s_nop 0
	v_pk_fma_f32 v[80:81], v[78:79], v[80:81], s[46:47] op_sel_hi:[1,1,0]
	s_nop 0
	v_pk_fma_f32 v[78:79], v[78:79], v[80:81], s[48:49] op_sel_hi:[1,1,0]
	s_nop 0
	v_pk_mul_f32 v[76:77], v[76:77], v[78:79]
	s_nop 0
	v_pk_fma_f32 v[74:75], v[74:75], v[76:77], v[74:75]
	s_nop 0
	v_pk_mul_f32 v[66:67], v[66:67], v[74:75]
	v_cvt_pk_bf16_f32 v74, v64, v65
	v_lshl_add_u64 v[64:65], v[132:133], 0, v[180:181]
	v_cvt_pk_bf16_f32 v75, v66, v67
	global_store_dwordx4 v[64:65], v[72:75], off
	v_lshlrev_b64 v[64:65], 2, v[134:135]
	v_lshl_add_u64 v[76:77], s[8:9], 0, v[64:65]
	v_readlane_b32 s8, v240, 21
	v_readlane_b32 s9, v240, 22
	v_lshl_add_u64 v[72:73], s[66:67], 0, v[64:65]
	v_lshl_add_u64 v[96:97], s[88:89], 0, v[64:65]
	v_lshl_add_u64 v[80:81], s[8:9], 0, v[64:65]
	global_load_dwordx4 v[64:67], v[72:73], off offset:16
	global_load_dwordx4 v[84:87], v[72:73], off
	s_nop 0
	global_load_dwordx4 v[72:75], v[76:77], off offset:16
	global_load_dwordx4 v[88:91], v[76:77], off
	s_nop 0
	global_load_dwordx4 v[76:79], v[80:81], off offset:16
	global_load_dwordx4 v[92:95], v[80:81], off
	s_nop 0
	global_load_dwordx4 v[80:83], v[96:97], off offset:16
	s_nop 0
	global_load_dwordx4 v[96:99], v[96:97], off
	s_nop 0
	global_load_dwordx4 v[114:117], v[136:137], off nt
	global_load_dwordx4 v[110:113], v[100:101], off nt
	v_add_co_u32_e32 v100, vcc, 0x2c000, v136
	s_nop 1
	v_addc_co_u32_e32 v101, vcc, 0, v137, vcc
	global_load_dwordx4 v[106:109], v[100:101], off nt
	v_add_co_u32_e32 v100, vcc, 0x42000, v136
	s_nop 1
	v_addc_co_u32_e32 v101, vcc, 0, v137, vcc
	global_load_dwordx4 v[102:105], v[100:101], off nt
	v_mov_b32_e32 v100, 0
	s_andn2_b64 vcc, exec, s[0:1]
	s_cbranch_vccnz .LBB0_1018
	v_add_co_u32_e32 v118, vcc, 0xfffea000, v136
	s_nop 1
	v_addc_co_u32_e32 v119, vcc, -1, v137, vcc
	global_load_dwordx4 v[118:121], v[118:119], off nt
.LBB0_1018:
	s_waitcnt vmcnt(0)
	s_nop 0
	v_mov_b32_dpp v123, v118 row_ror:2 row_mask:0xf bank_mask:0xf bound_ctrl:1
	v_mov_b32_dpp v1, v118 row_ror:1 row_mask:0xf bank_mask:0xf bound_ctrl:1
	v_mov_b32_dpp v101, v119 row_ror:1 row_mask:0xf bank_mask:0xf bound_ctrl:1
	v_mov_b32_dpp v123, v114 row_shr:2 row_mask:0xf bank_mask:0xf
	v_mov_b32_dpp v1, v114 row_shr:1 row_mask:0xf bank_mask:0xf
	v_lshlrev_b32_e32 v138, 16, v123
	v_and_b32_e32 v139, 0xffff0000, v123
	v_mov_b32_dpp v125, v119 row_ror:2 row_mask:0xf bank_mask:0xf bound_ctrl:1
	v_lshlrev_b32_e32 v118, 16, v1
	v_and_b32_e32 v119, 0xffff0000, v1
	v_pk_fma_f32 v[138:139], v[84:85], v[138:139], v[96:97]
	v_lshlrev_b32_e32 v142, 16, v114
	v_and_b32_e32 v143, 0xffff0000, v114
	v_pk_fma_f32 v[118:119], v[88:89], v[118:119], v[138:139]
	v_mov_b32_dpp v125, v115 row_shr:2 row_mask:0xf bank_mask:0xf
	v_pk_fma_f32 v[138:139], v[92:93], v[142:143], v[118:119]
	v_mov_b32_e32 v189, v188
	v_pk_mul_f32 v[118:119], v[138:139], s[30:31] op_sel_hi:[1,0]
	v_mov_b32_dpp v101, v115 row_shr:1 row_mask:0xf bank_mask:0xf
	v_med3_f32 v142, v118, s47, v225
	v_med3_f32 v143, v119, s47, v225
	v_pk_mul_f32 v[144:145], v[142:143], v[142:143]
	v_mov_b64_e32 v[118:119], s[36:37]
	v_pk_fma_f32 v[146:147], v[144:145], s[34:35], v[118:119] op_sel_hi:[1,0,0] neg_lo:[1,0,0] neg_hi:[1,0,0]
	v_lshlrev_b32_e32 v140, 16, v125
	v_pk_fma_f32 v[146:147], v[144:145], v[146:147], s[38:39] op_sel_hi:[1,1,0]
	v_and_b32_e32 v141, 0xffff0000, v125
	v_pk_fma_f32 v[146:147], v[144:145], v[146:147], s[40:41] op_sel_hi:[1,1,0]
	v_pk_mul_f32 v[138:139], v[138:139], 0.5 op_sel_hi:[1,0]
	v_pk_fma_f32 v[146:147], v[144:145], v[146:147], s[42:43] op_sel_hi:[1,1,0]
	v_lshlrev_b32_e32 v136, 16, v101
	v_pk_fma_f32 v[146:147], v[144:145], v[146:147], s[44:45] op_sel_hi:[1,1,0]
	v_and_b32_e32 v137, 0xffff0000, v101
	v_pk_fma_f32 v[146:147], v[144:145], v[146:147], s[46:47] op_sel_hi:[1,1,0]
	v_pk_mul_f32 v[68:69], v[68:69], v[188:189]
	v_pk_fma_f32 v[144:145], v[144:145], v[146:147], s[48:49] op_sel_hi:[1,1,0]
	v_pk_fma_f32 v[140:141], v[86:87], v[140:141], v[98:99]
	v_pk_mul_f32 v[142:143], v[142:143], v[144:145]
	v_pk_fma_f32 v[136:137], v[90:91], v[136:137], v[140:141]
	v_pk_fma_f32 v[138:139], v[138:139], v[142:143], v[138:139]
	v_mov_b32_dpp v123, v120 row_ror:2 row_mask:0xf bank_mask:0xf bound_ctrl:1
	v_pk_mul_f32 v[68:69], v[68:69], v[138:139]
	v_lshlrev_b32_e32 v138, 16, v115
	v_and_b32_e32 v139, 0xffff0000, v115
	v_pk_fma_f32 v[136:137], v[94:95], v[138:139], v[136:137]
	v_pk_mul_f32 v[70:71], v[70:71], v[188:189]
	v_pk_mul_f32 v[138:139], v[136:137], s[30:31] op_sel_hi:[1,0]
	v_pk_mul_f32 v[136:137], v[136:137], 0.5 op_sel_hi:[1,0]
	v_med3_f32 v138, v138, s47, v225
	v_med3_f32 v139, v139, s47, v225
;     static __device__ __forceinline__ void unpk4(const u32x2 w, float (&o)[4]) { o[0] = bf_lo(w.x); o[1] = bf_hi(w.x); o[2] = bf_lo(w.y); o[3] = bf_hi(w.y); }
;     template <int N> static __device__ __forceinline__ u32x2 dpp_prev(const u32x2 pv, const u32x2 cur) { u32x2 r; r.x = dpp_prev1<N>(pv.x, cur.x); r.y = dpp_prev1<N>(pv.y, cur.y); return r; }
;     __device__ __forceinline__ void operator()(const f32x4 (&acc)[2][2][4][2], const Unit& u, int wr, int wc, int fr, int fq) const {
;     ...
;                 for (int m = 0; m < 4; ++m) { const u32x4 cur = gq[m]; u32x4 hw;
; #pragma unroll
;                     for (int hv = 0; hv < 2; ++hv) { const u32x2 c2 = half2(cur, hv), p2 = half2(pv, hv);
;                         const u32x2 q1 = dpp_prev<1>(p2, c2), q2 = dpp_prev<2>(p2, c2);
;                         float g0[4], g1[4], g2[4]; unpk4(c2, g0); unpk4(q1, g1); unpk4(q2, g2);
;                         const u32x2 r = finish2(g0, g1, g2, w0[hv], w1[hv], w2[hv], bb[hv], acc[ai][bj][m][hv], rs8[ai][m]);
;                         if (hv == 0) { hw.x = r.x; hw.y = r.y; } else { hw.z = r.x; hw.w = r.y; } }
;                     *(u32x4*)(H + (size_t)(R0 + fr + 16 * m) * 2816 + col8) = hw;
;                     pv = cur; } }
	v_pk_mul_f32 v[140:141], v[138:139], v[138:139]
	v_mov_b32_dpp v1, v120 row_ror:1 row_mask:0xf bank_mask:0xf bound_ctrl:1
	v_pk_fma_f32 v[142:143], v[140:141], s[34:35], v[118:119] op_sel_hi:[1,0,0] neg_lo:[1,0,0] neg_hi:[1,0,0]
	v_mov_b32_dpp v123, v116 row_shr:2 row_mask:0xf bank_mask:0xf
	v_pk_fma_f32 v[142:143], v[140:141], v[142:143], s[38:39] op_sel_hi:[1,1,0]
	v_mov_b32_dpp v1, v116 row_shr:1 row_mask:0xf bank_mask:0xf
	v_pk_fma_f32 v[142:143], v[140:141], v[142:143], s[40:41] op_sel_hi:[1,1,0]
	v_cvt_pk_bf16_f32 v68, v68, v69
	v_mov_b32_dpp v125, v121 row_ror:2 row_mask:0xf bank_mask:0xf bound_ctrl:1
	v_pk_fma_f32 v[142:143], v[140:141], v[142:143], s[42:43] op_sel_hi:[1,1,0]
	v_mov_b32_dpp v101, v121 row_ror:1 row_mask:0xf bank_mask:0xf bound_ctrl:1
	v_pk_fma_f32 v[142:143], v[140:141], v[142:143], s[44:45] op_sel_hi:[1,1,0]
	v_mov_b32_dpp v125, v117 row_shr:2 row_mask:0xf bank_mask:0xf
	v_pk_fma_f32 v[142:143], v[140:141], v[142:143], s[46:47] op_sel_hi:[1,1,0]
	v_mov_b32_dpp v101, v117 row_shr:1 row_mask:0xf bank_mask:0xf
	v_pk_fma_f32 v[140:141], v[140:141], v[142:143], s[48:49] op_sel_hi:[1,1,0]
	v_lshlrev_b32_e32 v120, 16, v101
	v_pk_mul_f32 v[138:139], v[138:139], v[140:141]
	v_lshlrev_b32_e32 v140, 16, v116
	v_pk_fma_f32 v[136:137], v[136:137], v[138:139], v[136:137]
	v_and_b32_e32 v141, 0xffff0000, v116
	v_pk_mul_f32 v[70:71], v[70:71], v[136:137]
	v_lshlrev_b32_e32 v136, 16, v123
	v_and_b32_e32 v137, 0xffff0000, v123
	v_cvt_pk_bf16_f32 v69, v70, v71
	v_lshlrev_b32_e32 v70, 16, v1
	v_and_b32_e32 v71, 0xffff0000, v1
	v_pk_fma_f32 v[136:137], v[64:65], v[136:137], v[80:81]
	v_lshlrev_b32_e32 v138, 16, v125
	v_pk_fma_f32 v[70:71], v[72:73], v[70:71], v[136:137]
	v_and_b32_e32 v139, 0xffff0000, v125
	v_pk_fma_f32 v[70:71], v[76:77], v[140:141], v[70:71]
	v_and_b32_e32 v121, 0xffff0000, v101
	v_pk_mul_f32 v[136:137], v[70:71], s[30:31] op_sel_hi:[1,0]
	v_pk_mul_f32 v[70:71], v[70:71], 0.5 op_sel_hi:[1,0]
	v_med3_f32 v136, v136, s47, v225
	v_med3_f32 v137, v137, s47, v225
	v_pk_mul_f32 v[140:141], v[136:137], v[136:137]
	v_pk_mul_f32 v[60:61], v[60:61], v[188:189]
	v_pk_fma_f32 v[142:143], v[140:141], s[34:35], v[118:119] op_sel_hi:[1,0,0] neg_lo:[1,0,0] neg_hi:[1,0,0]
	v_pk_mul_f32 v[62:63], v[62:63], v[188:189]
	v_pk_fma_f32 v[142:143], v[140:141], v[142:143], s[38:39] op_sel_hi:[1,1,0]
	v_mov_b32_dpp v1, v114 row_ror:1 row_mask:0xf bank_mask:0xf bound_ctrl:1
	v_pk_fma_f32 v[142:143], v[140:141], v[142:143], s[40:41] op_sel_hi:[1,1,0]
	v_mov_b32_dpp v101, v115 row_ror:2 row_mask:0xf bank_mask:0xf bound_ctrl:1
	v_pk_fma_f32 v[142:143], v[140:141], v[142:143], s[42:43] op_sel_hi:[1,1,0]
	v_mov_b32_dpp v1, v110 row_shr:1 row_mask:0xf bank_mask:0xf
	v_pk_fma_f32 v[142:143], v[140:141], v[142:143], s[44:45] op_sel_hi:[1,1,0]
	v_mov_b32_dpp v101, v111 row_shr:2 row_mask:0xf bank_mask:0xf
	v_pk_fma_f32 v[142:143], v[140:141], v[142:143], s[46:47] op_sel_hi:[1,1,0]
	v_mov_b32_e32 v187, v186
	v_pk_fma_f32 v[140:141], v[140:141], v[142:143], s[48:49] op_sel_hi:[1,1,0]
	v_pk_mul_f32 v[56:57], v[56:57], v[186:187]
	v_pk_mul_f32 v[136:137], v[136:137], v[140:141]
	v_pk_mul_f32 v[58:59], v[58:59], v[186:187]
	v_pk_fma_f32 v[70:71], v[70:71], v[136:137], v[70:71]
	v_pk_fma_f32 v[136:137], v[66:67], v[138:139], v[82:83]
	v_pk_mul_f32 v[60:61], v[60:61], v[70:71]
	v_lshlrev_b32_e32 v70, 16, v117
	v_and_b32_e32 v71, 0xffff0000, v117
	v_pk_fma_f32 v[120:121], v[74:75], v[120:121], v[136:137]
	v_pk_mul_f32 v[52:53], v[52:53], v[186:187]
	v_pk_fma_f32 v[70:71], v[78:79], v[70:71], v[120:121]
	v_pk_mul_f32 v[54:55], v[54:55], v[186:187]
	v_pk_mul_f32 v[120:121], v[70:71], s[30:31] op_sel_hi:[1,0]
	v_pk_mul_f32 v[70:71], v[70:71], 0.5 op_sel_hi:[1,0]
	v_med3_f32 v120, v120, s47, v225
	v_med3_f32 v121, v121, s47, v225
	v_pk_mul_f32 v[136:137], v[120:121], v[120:121]
	v_mov_b32_e32 v185, v184
	v_pk_fma_f32 v[138:139], v[136:137], s[34:35], v[118:119] op_sel_hi:[1,0,0] neg_lo:[1,0,0] neg_hi:[1,0,0]
	v_pk_mul_f32 v[48:49], v[48:49], v[184:185]
	v_pk_fma_f32 v[138:139], v[136:137], v[138:139], s[38:39] op_sel_hi:[1,1,0]
	v_pk_mul_f32 v[50:51], v[50:51], v[184:185]
	v_pk_fma_f32 v[138:139], v[136:137], v[138:139], s[40:41] op_sel_hi:[1,1,0]
	v_pk_mul_f32 v[44:45], v[44:45], v[184:185]
	v_pk_fma_f32 v[138:139], v[136:137], v[138:139], s[42:43] op_sel_hi:[1,1,0]
	v_pk_mul_f32 v[46:47], v[46:47], v[184:185]
	v_pk_fma_f32 v[138:139], v[136:137], v[138:139], s[44:45] op_sel_hi:[1,1,0]
	v_mov_b32_e32 v3, v2
	v_pk_fma_f32 v[138:139], v[136:137], v[138:139], s[46:47] op_sel_hi:[1,1,0]
	v_pk_mul_f32 v[40:41], v[40:41], v[2:3]
	v_pk_fma_f32 v[136:137], v[136:137], v[138:139], s[48:49] op_sel_hi:[1,1,0]
	v_pk_mul_f32 v[42:43], v[42:43], v[2:3]
	v_pk_mul_f32 v[120:121], v[120:121], v[136:137]
	v_pk_mul_f32 v[36:37], v[36:37], v[2:3]
	v_pk_fma_f32 v[70:71], v[70:71], v[120:121], v[70:71]
	v_lshlrev_b32_e32 v120, 16, v110
	v_pk_mul_f32 v[62:63], v[62:63], v[70:71]
	v_cvt_pk_bf16_f32 v70, v60, v61
	v_lshlrev_b64 v[60:61], 1, v[134:135]
	v_cvt_pk_bf16_f32 v71, v62, v63
	v_lshl_add_u64 v[62:63], v[130:131], 0, v[60:61]
	global_store_dwordx4 v[62:63], v[68:71], off
	v_lshlrev_b32_e32 v62, 16, v1
	v_and_b32_e32 v63, 0xffff0000, v1
	v_mov_b32_dpp v71, v114 row_ror:2 row_mask:0xf bank_mask:0xf bound_ctrl:1
	v_and_b32_e32 v121, 0xffff0000, v110
	v_mov_b32_dpp v69, v115 row_ror:1 row_mask:0xf bank_mask:0xf bound_ctrl:1
	v_mov_b32_dpp v71, v110 row_shr:2 row_mask:0xf bank_mask:0xf
	v_lshlrev_b32_e32 v70, 16, v71
	v_and_b32_e32 v71, 0xffff0000, v71
	v_pk_fma_f32 v[70:71], v[84:85], v[70:71], v[96:97]
	v_mov_b32_dpp v69, v111 row_shr:1 row_mask:0xf bank_mask:0xf
;     static __device__ __forceinline__ void unpk4(const u32x2 w, float (&o)[4]) { o[0] = bf_lo(w.x); o[1] = bf_hi(w.x); o[2] = bf_lo(w.y); o[3] = bf_hi(w.y); }
;     template <int N> static __device__ __forceinline__ u32x2 dpp_prev(const u32x2 pv, const u32x2 cur) { u32x2 r; r.x = dpp_prev1<N>(pv.x, cur.x); r.y = dpp_prev1<N>(pv.y, cur.y); return r; }
; __device__ __forceinline__ f32x2 gelu_pk(f32x2 v) {
;     f32x2 x = v * 0.70710678118f;
;     x.x = __builtin_amdgcn_fmed3f(x.x, -2.9f, 2.9f); x.y = __builtin_amdgcn_fmed3f(x.y, -2.9f, 2.9f);
;     const f32x2 t = x * x;
;     f32x2 p = t * (-4.953124630e-07f) + 1.987094038e-05f;
;     p = p * t + (-3.472001117e-04f); p = p * t + 3.517547622e-03f; p = p * t + (-2.333305031e-02f); p = p * t + 1.087993085e-01f; p = p * t + (-3.740358949e-01f); p = p * t + 1.128076553e+00f;
;     const f32x2 hv = v * 0.5f;
;     return hv * (x * p) + hv;
; }
;     __device__ __forceinline__ void operator()(const f32x4 (&acc)[2][2][4][2], const Unit& u, int wr, int wc, int fr, int fq) const {
;     ...
;                 for (int m = 0; m < 4; ++m) { const u32x4 cur = gq[m]; u32x4 hw;
; #pragma unroll
;                     for (int hv = 0; hv < 2; ++hv) { const u32x2 c2 = half2(cur, hv), p2 = half2(pv, hv);
;                         const u32x2 q1 = dpp_prev<1>(p2, c2), q2 = dpp_prev<2>(p2, c2);
;                         float g0[4], g1[4], g2[4]; unpk4(c2, g0); unpk4(q1, g1); unpk4(q2, g2);
;                         const u32x2 r = finish2(g0, g1, g2, w0[hv], w1[hv], w2[hv], bb[hv], acc[ai][bj][m][hv], rs8[ai][m]);
;                         if (hv == 0) { hw.x = r.x; hw.y = r.y; } else { hw.z = r.x; hw.w = r.y; } }
	v_pk_fma_f32 v[62:63], v[88:89], v[62:63], v[70:71]
	v_lshlrev_b32_e32 v114, 16, v101
	v_pk_fma_f32 v[62:63], v[92:93], v[120:121], v[62:63]
	v_and_b32_e32 v115, 0xffff0000, v101
	v_pk_mul_f32 v[70:71], v[62:63], s[30:31] op_sel_hi:[1,0]
	v_pk_mul_f32 v[62:63], v[62:63], 0.5 op_sel_hi:[1,0]
	v_med3_f32 v70, v70, s47, v225
	v_med3_f32 v71, v71, s47, v225
	v_pk_mul_f32 v[120:121], v[70:71], v[70:71]
	v_lshlrev_b32_e32 v68, 16, v69
	v_pk_fma_f32 v[130:131], v[120:121], s[34:35], v[118:119] op_sel_hi:[1,0,0] neg_lo:[1,0,0] neg_hi:[1,0,0]
	v_and_b32_e32 v69, 0xffff0000, v69
	v_pk_fma_f32 v[130:131], v[120:121], v[130:131], s[38:39] op_sel_hi:[1,1,0]
	v_mov_b32_dpp v1, v116 row_ror:1 row_mask:0xf bank_mask:0xf bound_ctrl:1
	v_pk_fma_f32 v[130:131], v[120:121], v[130:131], s[40:41] op_sel_hi:[1,1,0]
	v_pk_mul_f32 v[2:3], v[38:39], v[2:3]
	v_pk_fma_f32 v[130:131], v[120:121], v[130:131], s[42:43] op_sel_hi:[1,1,0]
	v_mov_b32_dpp v1, v112 row_shr:1 row_mask:0xf bank_mask:0xf
	v_pk_fma_f32 v[130:131], v[120:121], v[130:131], s[44:45] op_sel_hi:[1,1,0]
	v_readlane_b32 s64, v240, 23
	v_pk_fma_f32 v[130:131], v[120:121], v[130:131], s[46:47] op_sel_hi:[1,1,0]
	v_mov_b32_e32 v101, 0
	v_pk_fma_f32 v[120:121], v[120:121], v[130:131], s[48:49] op_sel_hi:[1,1,0]
	v_readlane_b32 s65, v240, 24
	v_pk_mul_f32 v[70:71], v[70:71], v[120:121]
	s_mov_b64 s[54:55], s[68:69]
	v_pk_fma_f32 v[62:63], v[62:63], v[70:71], v[62:63]
	v_pk_fma_f32 v[70:71], v[86:87], v[114:115], v[98:99]
	v_pk_mul_f32 v[56:57], v[56:57], v[62:63]
	v_lshlrev_b32_e32 v62, 16, v111
	v_and_b32_e32 v63, 0xffff0000, v111
	v_pk_fma_f32 v[68:69], v[90:91], v[68:69], v[70:71]
	v_cvt_pk_bf16_f32 v56, v56, v57
	s_nop 0
	v_pk_fma_f32 v[62:63], v[94:95], v[62:63], v[68:69]
	s_nop 0
	v_pk_mul_f32 v[68:69], v[62:63], s[30:31] op_sel_hi:[1,0]
	v_pk_mul_f32 v[62:63], v[62:63], 0.5 op_sel_hi:[1,0]
	v_med3_f32 v68, v68, s47, v225
	v_med3_f32 v69, v69, s47, v225
	v_pk_mul_f32 v[70:71], v[68:69], v[68:69]
	s_nop 0
	v_pk_fma_f32 v[114:115], v[70:71], s[34:35], v[118:119] op_sel_hi:[1,0,0] neg_lo:[1,0,0] neg_hi:[1,0,0]
	s_nop 0
	v_pk_fma_f32 v[114:115], v[70:71], v[114:115], s[38:39] op_sel_hi:[1,1,0]
	s_nop 0
	v_pk_fma_f32 v[114:115], v[70:71], v[114:115], s[40:41] op_sel_hi:[1,1,0]
	s_nop 0
	v_pk_fma_f32 v[114:115], v[70:71], v[114:115], s[42:43] op_sel_hi:[1,1,0]
	s_nop 0
	v_pk_fma_f32 v[114:115], v[70:71], v[114:115], s[44:45] op_sel_hi:[1,1,0]
	s_nop 0
	v_pk_fma_f32 v[114:115], v[70:71], v[114:115], s[46:47] op_sel_hi:[1,1,0]
	s_nop 0
	v_pk_fma_f32 v[70:71], v[70:71], v[114:115], s[48:49] op_sel_hi:[1,1,0]
	v_lshlrev_b32_e32 v114, 16, v112
	v_pk_mul_f32 v[68:69], v[68:69], v[70:71]
	v_and_b32_e32 v115, 0xffff0000, v112
	v_pk_fma_f32 v[62:63], v[62:63], v[68:69], v[62:63]
	v_mov_b32_dpp v69, v116 row_ror:2 row_mask:0xf bank_mask:0xf bound_ctrl:1
	v_pk_mul_f32 v[58:59], v[58:59], v[62:63]
	v_mov_b32_dpp v63, v117 row_ror:1 row_mask:0xf bank_mask:0xf bound_ctrl:1
	v_mov_b32_dpp v69, v112 row_shr:2 row_mask:0xf bank_mask:0xf
	v_lshlrev_b32_e32 v68, 16, v69
	v_and_b32_e32 v69, 0xffff0000, v69
	v_cvt_pk_bf16_f32 v57, v58, v59
	v_lshlrev_b32_e32 v58, 16, v1
	v_and_b32_e32 v59, 0xffff0000, v1
	v_pk_fma_f32 v[68:69], v[64:65], v[68:69], v[80:81]
	v_mov_b32_dpp v71, v117 row_ror:2 row_mask:0xf bank_mask:0xf bound_ctrl:1
	v_pk_fma_f32 v[58:59], v[72:73], v[58:59], v[68:69]
	v_mov_b32_dpp v63, v113 row_shr:1 row_mask:0xf bank_mask:0xf
	v_pk_fma_f32 v[58:59], v[76:77], v[114:115], v[58:59]
	v_mov_b32_dpp v71, v113 row_shr:2 row_mask:0xf bank_mask:0xf
	v_pk_mul_f32 v[68:69], v[58:59], s[30:31] op_sel_hi:[1,0]
	v_lshlrev_b32_e32 v70, 16, v71
	v_med3_f32 v68, v68, s47, v225
	v_med3_f32 v69, v69, s47, v225
	v_pk_mul_f32 v[114:115], v[68:69], v[68:69]
	v_and_b32_e32 v71, 0xffff0000, v71
	v_pk_fma_f32 v[116:117], v[114:115], s[34:35], v[118:119] op_sel_hi:[1,0,0] neg_lo:[1,0,0] neg_hi:[1,0,0]
	v_pk_mul_f32 v[58:59], v[58:59], 0.5 op_sel_hi:[1,0]
	v_pk_fma_f32 v[116:117], v[114:115], v[116:117], s[38:39] op_sel_hi:[1,1,0]
	v_lshlrev_b32_e32 v62, 16, v63
	v_pk_fma_f32 v[116:117], v[114:115], v[116:117], s[40:41] op_sel_hi:[1,1,0]
	v_and_b32_e32 v63, 0xffff0000, v63
	v_pk_fma_f32 v[116:117], v[114:115], v[116:117], s[42:43] op_sel_hi:[1,1,0]
	v_mov_b32_dpp v1, v110 row_ror:1 row_mask:0xf bank_mask:0xf bound_ctrl:1
	v_pk_fma_f32 v[116:117], v[114:115], v[116:117], s[44:45] op_sel_hi:[1,1,0]
	s_nop 0
	v_pk_fma_f32 v[116:117], v[114:115], v[116:117], s[46:47] op_sel_hi:[1,1,0]
	v_mov_b32_dpp v1, v106 row_shr:1 row_mask:0xf bank_mask:0xf
	v_pk_fma_f32 v[114:115], v[114:115], v[116:117], s[48:49] op_sel_hi:[1,1,0]
	s_nop 0
	v_pk_mul_f32 v[68:69], v[68:69], v[114:115]
	s_nop 0
	v_pk_fma_f32 v[58:59], v[58:59], v[68:69], v[58:59]
	v_pk_fma_f32 v[68:69], v[66:67], v[70:71], v[82:83]
	v_pk_mul_f32 v[52:53], v[52:53], v[58:59]
	v_lshlrev_b32_e32 v58, 16, v113
	v_and_b32_e32 v59, 0xffff0000, v113
	v_pk_fma_f32 v[62:63], v[74:75], v[62:63], v[68:69]
	s_nop 0
	v_pk_fma_f32 v[58:59], v[78:79], v[58:59], v[62:63]
	s_nop 0
	v_pk_mul_f32 v[62:63], v[58:59], s[30:31] op_sel_hi:[1,0]
	v_pk_mul_f32 v[58:59], v[58:59], 0.5 op_sel_hi:[1,0]
	v_med3_f32 v62, v62, s47, v225
	v_med3_f32 v63, v63, s47, v225
	v_pk_mul_f32 v[68:69], v[62:63], v[62:63]
	s_nop 0
	v_pk_fma_f32 v[70:71], v[68:69], s[34:35], v[118:119] op_sel_hi:[1,0,0] neg_lo:[1,0,0] neg_hi:[1,0,0]
	s_nop 0
	v_pk_fma_f32 v[70:71], v[68:69], v[70:71], s[38:39] op_sel_hi:[1,1,0]
	s_nop 0
	v_pk_fma_f32 v[70:71], v[68:69], v[70:71], s[40:41] op_sel_hi:[1,1,0]
	s_nop 0
	v_pk_fma_f32 v[70:71], v[68:69], v[70:71], s[42:43] op_sel_hi:[1,1,0]
	s_nop 0
	v_pk_fma_f32 v[70:71], v[68:69], v[70:71], s[44:45] op_sel_hi:[1,1,0]
;     static __device__ __forceinline__ void unpk4(const u32x2 w, float (&o)[4]) { o[0] = bf_lo(w.x); o[1] = bf_hi(w.x); o[2] = bf_lo(w.y); o[3] = bf_hi(w.y); }
;     template <int N> static __device__ __forceinline__ u32x2 dpp_prev(const u32x2 pv, const u32x2 cur) { u32x2 r; r.x = dpp_prev1<N>(pv.x, cur.x); r.y = dpp_prev1<N>(pv.y, cur.y); return r; }
;     __device__ __forceinline__ void operator()(const f32x4 (&acc)[2][2][4][2], const Unit& u, int wr, int wc, int fr, int fq) const {
;     ...
;                 for (int m = 0; m < 4; ++m) { const u32x4 cur = gq[m]; u32x4 hw;
; #pragma unroll
;                     for (int hv = 0; hv < 2; ++hv) { const u32x2 c2 = half2(cur, hv), p2 = half2(pv, hv);
;                         const u32x2 q1 = dpp_prev<1>(p2, c2), q2 = dpp_prev<2>(p2, c2);
;                         float g0[4], g1[4], g2[4]; unpk4(c2, g0); unpk4(q1, g1); unpk4(q2, g2);
;                         const u32x2 r = finish2(g0, g1, g2, w0[hv], w1[hv], w2[hv], bb[hv], acc[ai][bj][m][hv], rs8[ai][m]);
;                         if (hv == 0) { hw.x = r.x; hw.y = r.y; } else { hw.z = r.x; hw.w = r.y; } }
;                     *(u32x4*)(H + (size_t)(R0 + fr + 16 * m) * 2816 + col8) = hw;
;                     pv = cur; } }
	s_nop 0
	v_pk_fma_f32 v[70:71], v[68:69], v[70:71], s[46:47] op_sel_hi:[1,1,0]
	s_nop 0
	v_pk_fma_f32 v[68:69], v[68:69], v[70:71], s[48:49] op_sel_hi:[1,1,0]
	s_nop 0
	v_pk_mul_f32 v[62:63], v[62:63], v[68:69]
	s_nop 0
	v_pk_fma_f32 v[58:59], v[58:59], v[62:63], v[58:59]
	v_lshlrev_b32_e32 v62, 16, v106
	v_pk_mul_f32 v[54:55], v[54:55], v[58:59]
	v_cvt_pk_bf16_f32 v58, v52, v53
	v_lshl_add_u64 v[52:53], v[176:177], 0, v[60:61]
	v_cvt_pk_bf16_f32 v59, v54, v55
	global_store_dwordx4 v[52:53], v[56:59], off
	v_lshlrev_b32_e32 v52, 16, v1
	v_and_b32_e32 v53, 0xffff0000, v1
	v_mov_b32_dpp v57, v110 row_ror:2 row_mask:0xf bank_mask:0xf bound_ctrl:1
	v_and_b32_e32 v63, 0xffff0000, v106
	v_mov_b32_dpp v59, v111 row_ror:2 row_mask:0xf bank_mask:0xf bound_ctrl:1
	v_mov_b32_dpp v57, v106 row_shr:2 row_mask:0xf bank_mask:0xf
	v_lshlrev_b32_e32 v56, 16, v57
	v_and_b32_e32 v57, 0xffff0000, v57
	v_pk_fma_f32 v[56:57], v[84:85], v[56:57], v[96:97]
	v_mov_b32_dpp v55, v111 row_ror:1 row_mask:0xf bank_mask:0xf bound_ctrl:1
	v_pk_fma_f32 v[52:53], v[88:89], v[52:53], v[56:57]
	v_mov_b32_dpp v59, v107 row_shr:2 row_mask:0xf bank_mask:0xf
	v_pk_fma_f32 v[52:53], v[92:93], v[62:63], v[52:53]
	v_mov_b32_dpp v55, v107 row_shr:1 row_mask:0xf bank_mask:0xf
	v_pk_mul_f32 v[56:57], v[52:53], s[30:31] op_sel_hi:[1,0]
	v_lshlrev_b32_e32 v58, 16, v59
	v_med3_f32 v56, v56, s47, v225
	v_med3_f32 v57, v57, s47, v225
	v_pk_mul_f32 v[62:63], v[56:57], v[56:57]
	v_and_b32_e32 v59, 0xffff0000, v59
	v_pk_fma_f32 v[68:69], v[62:63], s[34:35], v[118:119] op_sel_hi:[1,0,0] neg_lo:[1,0,0] neg_hi:[1,0,0]
	v_pk_mul_f32 v[52:53], v[52:53], 0.5 op_sel_hi:[1,0]
	v_pk_fma_f32 v[68:69], v[62:63], v[68:69], s[38:39] op_sel_hi:[1,1,0]
	v_lshlrev_b32_e32 v54, 16, v55
	v_pk_fma_f32 v[68:69], v[62:63], v[68:69], s[40:41] op_sel_hi:[1,1,0]
	v_and_b32_e32 v55, 0xffff0000, v55
	v_pk_fma_f32 v[68:69], v[62:63], v[68:69], s[42:43] op_sel_hi:[1,1,0]
	v_mov_b32_dpp v1, v112 row_ror:1 row_mask:0xf bank_mask:0xf bound_ctrl:1
	v_pk_fma_f32 v[68:69], v[62:63], v[68:69], s[44:45] op_sel_hi:[1,1,0]
	s_nop 0
	v_pk_fma_f32 v[68:69], v[62:63], v[68:69], s[46:47] op_sel_hi:[1,1,0]
	v_mov_b32_dpp v1, v108 row_shr:1 row_mask:0xf bank_mask:0xf
	v_pk_fma_f32 v[62:63], v[62:63], v[68:69], s[48:49] op_sel_hi:[1,1,0]
	s_nop 0
	v_pk_mul_f32 v[56:57], v[56:57], v[62:63]
	s_nop 0
	v_pk_fma_f32 v[52:53], v[52:53], v[56:57], v[52:53]
	v_pk_fma_f32 v[56:57], v[86:87], v[58:59], v[98:99]
	v_pk_mul_f32 v[48:49], v[48:49], v[52:53]
	v_lshlrev_b32_e32 v52, 16, v107
	v_and_b32_e32 v53, 0xffff0000, v107
	v_pk_fma_f32 v[54:55], v[90:91], v[54:55], v[56:57]
	v_cvt_pk_bf16_f32 v48, v48, v49
	s_nop 0
	v_pk_fma_f32 v[52:53], v[94:95], v[52:53], v[54:55]
	s_nop 0
	v_pk_mul_f32 v[54:55], v[52:53], s[30:31] op_sel_hi:[1,0]
	v_pk_mul_f32 v[52:53], v[52:53], 0.5 op_sel_hi:[1,0]
	v_med3_f32 v54, v54, s47, v225
	v_med3_f32 v55, v55, s47, v225
	v_pk_mul_f32 v[56:57], v[54:55], v[54:55]
	s_nop 0
	v_pk_fma_f32 v[58:59], v[56:57], s[34:35], v[118:119] op_sel_hi:[1,0,0] neg_lo:[1,0,0] neg_hi:[1,0,0]
	s_nop 0
	v_pk_fma_f32 v[58:59], v[56:57], v[58:59], s[38:39] op_sel_hi:[1,1,0]
	s_nop 0
	v_pk_fma_f32 v[58:59], v[56:57], v[58:59], s[40:41] op_sel_hi:[1,1,0]
	s_nop 0
	v_pk_fma_f32 v[58:59], v[56:57], v[58:59], s[42:43] op_sel_hi:[1,1,0]
	s_nop 0
	v_pk_fma_f32 v[58:59], v[56:57], v[58:59], s[44:45] op_sel_hi:[1,1,0]
	s_nop 0
	v_pk_fma_f32 v[58:59], v[56:57], v[58:59], s[46:47] op_sel_hi:[1,1,0]
	s_nop 0
	v_pk_fma_f32 v[56:57], v[56:57], v[58:59], s[48:49] op_sel_hi:[1,1,0]
	v_lshlrev_b32_e32 v58, 16, v108
	v_pk_mul_f32 v[54:55], v[54:55], v[56:57]
	v_and_b32_e32 v59, 0xffff0000, v108
	v_pk_fma_f32 v[52:53], v[52:53], v[54:55], v[52:53]
	v_mov_b32_dpp v55, v112 row_ror:2 row_mask:0xf bank_mask:0xf bound_ctrl:1
	v_pk_mul_f32 v[50:51], v[50:51], v[52:53]
	v_mov_b32_dpp v57, v113 row_ror:2 row_mask:0xf bank_mask:0xf bound_ctrl:1
	v_mov_b32_dpp v55, v108 row_shr:2 row_mask:0xf bank_mask:0xf
	v_lshlrev_b32_e32 v54, 16, v55
	v_and_b32_e32 v55, 0xffff0000, v55
	v_cvt_pk_bf16_f32 v49, v50, v51
	v_lshlrev_b32_e32 v50, 16, v1
	v_and_b32_e32 v51, 0xffff0000, v1
	v_pk_fma_f32 v[54:55], v[64:65], v[54:55], v[80:81]
	v_mov_b32_dpp v53, v113 row_ror:1 row_mask:0xf bank_mask:0xf bound_ctrl:1
	v_pk_fma_f32 v[50:51], v[72:73], v[50:51], v[54:55]
	v_mov_b32_dpp v57, v109 row_shr:2 row_mask:0xf bank_mask:0xf
	v_pk_fma_f32 v[50:51], v[76:77], v[58:59], v[50:51]
	v_mov_b32_dpp v53, v109 row_shr:1 row_mask:0xf bank_mask:0xf
	v_pk_mul_f32 v[54:55], v[50:51], s[30:31] op_sel_hi:[1,0]
	v_lshlrev_b32_e32 v56, 16, v57
	v_med3_f32 v54, v54, s47, v225
	v_med3_f32 v55, v55, s47, v225
	v_pk_mul_f32 v[58:59], v[54:55], v[54:55]
	v_and_b32_e32 v57, 0xffff0000, v57
	v_pk_fma_f32 v[62:63], v[58:59], s[34:35], v[118:119] op_sel_hi:[1,0,0] neg_lo:[1,0,0] neg_hi:[1,0,0]
	v_pk_mul_f32 v[50:51], v[50:51], 0.5 op_sel_hi:[1,0]
	v_pk_fma_f32 v[62:63], v[58:59], v[62:63], s[38:39] op_sel_hi:[1,1,0]
	v_lshlrev_b32_e32 v52, 16, v53
	v_pk_fma_f32 v[62:63], v[58:59], v[62:63], s[40:41] op_sel_hi:[1,1,0]
	v_and_b32_e32 v53, 0xffff0000, v53
	v_pk_fma_f32 v[62:63], v[58:59], v[62:63], s[42:43] op_sel_hi:[1,1,0]
	v_mov_b32_dpp v1, v106 row_ror:1 row_mask:0xf bank_mask:0xf bound_ctrl:1
	v_pk_fma_f32 v[62:63], v[58:59], v[62:63], s[44:45] op_sel_hi:[1,1,0]
	s_nop 0
	v_pk_fma_f32 v[62:63], v[58:59], v[62:63], s[46:47] op_sel_hi:[1,1,0]
	v_mov_b32_dpp v1, v102 row_shr:1 row_mask:0xf bank_mask:0xf
	v_pk_fma_f32 v[58:59], v[58:59], v[62:63], s[48:49] op_sel_hi:[1,1,0]
	s_nop 0
	v_pk_mul_f32 v[54:55], v[54:55], v[58:59]
	s_nop 0
	v_pk_fma_f32 v[50:51], v[50:51], v[54:55], v[50:51]
;     static __device__ __forceinline__ void unpk4(const u32x2 w, float (&o)[4]) { o[0] = bf_lo(w.x); o[1] = bf_hi(w.x); o[2] = bf_lo(w.y); o[3] = bf_hi(w.y); }
;     template <int N> static __device__ __forceinline__ u32x2 dpp_prev(const u32x2 pv, const u32x2 cur) { u32x2 r; r.x = dpp_prev1<N>(pv.x, cur.x); r.y = dpp_prev1<N>(pv.y, cur.y); return r; }
;     __device__ __forceinline__ void operator()(const f32x4 (&acc)[2][2][4][2], const Unit& u, int wr, int wc, int fr, int fq) const {
;     ...
;                 for (int m = 0; m < 4; ++m) { const u32x4 cur = gq[m]; u32x4 hw;
; #pragma unroll
;                     for (int hv = 0; hv < 2; ++hv) { const u32x2 c2 = half2(cur, hv), p2 = half2(pv, hv);
;                         const u32x2 q1 = dpp_prev<1>(p2, c2), q2 = dpp_prev<2>(p2, c2);
;                         float g0[4], g1[4], g2[4]; unpk4(c2, g0); unpk4(q1, g1); unpk4(q2, g2);
;                         const u32x2 r = finish2(g0, g1, g2, w0[hv], w1[hv], w2[hv], bb[hv], acc[ai][bj][m][hv], rs8[ai][m]);
;                         if (hv == 0) { hw.x = r.x; hw.y = r.y; } else { hw.z = r.x; hw.w = r.y; } }
;                     *(u32x4*)(H + (size_t)(R0 + fr + 16 * m) * 2816 + col8) = hw;
;                     pv = cur; } }
	v_pk_fma_f32 v[54:55], v[66:67], v[56:57], v[82:83]
	v_pk_mul_f32 v[44:45], v[44:45], v[50:51]
	v_lshlrev_b32_e32 v50, 16, v109
	v_and_b32_e32 v51, 0xffff0000, v109
	v_pk_fma_f32 v[52:53], v[74:75], v[52:53], v[54:55]
	s_nop 0
	v_pk_fma_f32 v[50:51], v[78:79], v[50:51], v[52:53]
	s_nop 0
	v_pk_mul_f32 v[52:53], v[50:51], s[30:31] op_sel_hi:[1,0]
	v_pk_mul_f32 v[50:51], v[50:51], 0.5 op_sel_hi:[1,0]
	v_med3_f32 v52, v52, s47, v225
	v_med3_f32 v53, v53, s47, v225
	v_pk_mul_f32 v[54:55], v[52:53], v[52:53]
	s_nop 0
	v_pk_fma_f32 v[56:57], v[54:55], s[34:35], v[118:119] op_sel_hi:[1,0,0] neg_lo:[1,0,0] neg_hi:[1,0,0]
	s_nop 0
	v_pk_fma_f32 v[56:57], v[54:55], v[56:57], s[38:39] op_sel_hi:[1,1,0]
	s_nop 0
	v_pk_fma_f32 v[56:57], v[54:55], v[56:57], s[40:41] op_sel_hi:[1,1,0]
	s_nop 0
	v_pk_fma_f32 v[56:57], v[54:55], v[56:57], s[42:43] op_sel_hi:[1,1,0]
	s_nop 0
	v_pk_fma_f32 v[56:57], v[54:55], v[56:57], s[44:45] op_sel_hi:[1,1,0]
	s_nop 0
	v_pk_fma_f32 v[56:57], v[54:55], v[56:57], s[46:47] op_sel_hi:[1,1,0]
	s_nop 0
	v_pk_fma_f32 v[54:55], v[54:55], v[56:57], s[48:49] op_sel_hi:[1,1,0]
	v_lshl_add_u64 v[56:57], v[166:167], 0, v[60:61]
	v_pk_mul_f32 v[52:53], v[52:53], v[54:55]
	s_nop 0
	v_pk_fma_f32 v[50:51], v[50:51], v[52:53], v[50:51]
	v_lshlrev_b32_e32 v52, 16, v102
	v_pk_mul_f32 v[46:47], v[46:47], v[50:51]
	v_cvt_pk_bf16_f32 v50, v44, v45
	v_lshl_add_u64 v[44:45], v[172:173], 0, v[60:61]
	v_cvt_pk_bf16_f32 v51, v46, v47
	global_store_dwordx4 v[44:45], v[48:51], off
	v_lshlrev_b32_e32 v44, 16, v1
	v_and_b32_e32 v45, 0xffff0000, v1
	v_mov_b32_dpp v49, v106 row_ror:2 row_mask:0xf bank_mask:0xf bound_ctrl:1
	v_and_b32_e32 v53, 0xffff0000, v102
	v_mov_b32_dpp v51, v107 row_ror:2 row_mask:0xf bank_mask:0xf bound_ctrl:1
	v_mov_b32_dpp v49, v102 row_shr:2 row_mask:0xf bank_mask:0xf
	v_lshlrev_b32_e32 v48, 16, v49
	v_and_b32_e32 v49, 0xffff0000, v49
	v_pk_fma_f32 v[48:49], v[84:85], v[48:49], v[96:97]
	v_mov_b32_dpp v47, v107 row_ror:1 row_mask:0xf bank_mask:0xf bound_ctrl:1
	v_pk_fma_f32 v[44:45], v[88:89], v[44:45], v[48:49]
	v_mov_b32_dpp v51, v103 row_shr:2 row_mask:0xf bank_mask:0xf
	v_pk_fma_f32 v[44:45], v[92:93], v[52:53], v[44:45]
	v_mov_b32_dpp v47, v103 row_shr:1 row_mask:0xf bank_mask:0xf
	v_pk_mul_f32 v[48:49], v[44:45], s[30:31] op_sel_hi:[1,0]
	v_lshlrev_b32_e32 v50, 16, v51
	v_med3_f32 v48, v48, s47, v225
	v_med3_f32 v49, v49, s47, v225
	v_pk_mul_f32 v[52:53], v[48:49], v[48:49]
	v_and_b32_e32 v51, 0xffff0000, v51
	v_pk_fma_f32 v[54:55], v[52:53], s[34:35], v[118:119] op_sel_hi:[1,0,0] neg_lo:[1,0,0] neg_hi:[1,0,0]
	v_pk_mul_f32 v[44:45], v[44:45], 0.5 op_sel_hi:[1,0]
	v_pk_fma_f32 v[54:55], v[52:53], v[54:55], s[38:39] op_sel_hi:[1,1,0]
	v_lshlrev_b32_e32 v46, 16, v47
	v_pk_fma_f32 v[54:55], v[52:53], v[54:55], s[40:41] op_sel_hi:[1,1,0]
	v_and_b32_e32 v47, 0xffff0000, v47
	v_pk_fma_f32 v[54:55], v[52:53], v[54:55], s[42:43] op_sel_hi:[1,1,0]
	v_mov_b32_dpp v1, v108 row_ror:1 row_mask:0xf bank_mask:0xf bound_ctrl:1
	v_pk_fma_f32 v[54:55], v[52:53], v[54:55], s[44:45] op_sel_hi:[1,1,0]
	v_mov_b32_e32 v102, 0
	v_pk_fma_f32 v[54:55], v[52:53], v[54:55], s[46:47] op_sel_hi:[1,1,0]
	v_mov_b32_dpp v1, v104 row_shr:1 row_mask:0xf bank_mask:0xf
	v_pk_fma_f32 v[52:53], v[52:53], v[54:55], s[48:49] op_sel_hi:[1,1,0]
	s_nop 0
	v_pk_mul_f32 v[48:49], v[48:49], v[52:53]
	s_nop 0
	v_pk_fma_f32 v[44:45], v[44:45], v[48:49], v[44:45]
	v_pk_fma_f32 v[48:49], v[86:87], v[50:51], v[98:99]
	v_pk_mul_f32 v[40:41], v[40:41], v[44:45]
	v_lshlrev_b32_e32 v44, 16, v103
	v_and_b32_e32 v45, 0xffff0000, v103
	v_pk_fma_f32 v[46:47], v[90:91], v[46:47], v[48:49]
	v_cvt_pk_bf16_f32 v52, v40, v41
	v_lshlrev_b32_e32 v40, 16, v1
	v_pk_fma_f32 v[44:45], v[94:95], v[44:45], v[46:47]
	v_and_b32_e32 v41, 0xffff0000, v1
	v_pk_mul_f32 v[46:47], v[44:45], s[30:31] op_sel_hi:[1,0]
	v_pk_mul_f32 v[44:45], v[44:45], 0.5 op_sel_hi:[1,0]
	v_med3_f32 v46, v46, s47, v225
	v_med3_f32 v47, v47, s47, v225
	v_pk_mul_f32 v[48:49], v[46:47], v[46:47]
	v_mov_b32_e32 v103, 0
	v_pk_fma_f32 v[50:51], v[48:49], s[34:35], v[118:119] op_sel_hi:[1,0,0] neg_lo:[1,0,0] neg_hi:[1,0,0]
	s_nop 0
	v_pk_fma_f32 v[50:51], v[48:49], v[50:51], s[38:39] op_sel_hi:[1,1,0]
	s_nop 0
	v_pk_fma_f32 v[50:51], v[48:49], v[50:51], s[40:41] op_sel_hi:[1,1,0]
	s_nop 0
;     static __device__ __forceinline__ void unpk4(const u32x2 w, float (&o)[4]) { o[0] = bf_lo(w.x); o[1] = bf_hi(w.x); o[2] = bf_lo(w.y); o[3] = bf_hi(w.y); }
;     template <int N> static __device__ __forceinline__ u32x2 dpp_prev(const u32x2 pv, const u32x2 cur) { u32x2 r; r.x = dpp_prev1<N>(pv.x, cur.x); r.y = dpp_prev1<N>(pv.y, cur.y); return r; }
;     __device__ __forceinline__ void operator()(const f32x4 (&acc)[2][2][4][2], const Unit& u, int wr, int wc, int fr, int fq) const {
;     ...
;             for (int ai = 0; ai < 2; ++ai) { const int R0 = u.rb + ai * HALF + wr * 64; const bf16_t* gp = G + (size_t)(R0 + fr) * 2816 + col8;
;                 u32x4 gq[4], prv = (u32x4){0u, 0u, 0u, 0u};
; #pragma unroll
;                 for (int m = 0; m < 4; ++m) gq[m] = *(const u32x4*)(gp + (size_t)m * 16 * 2816);
;                 if ((R0 & 8191) != 0) prv = *(const u32x4*)(gp - (size_t)16 * 2816);
;                 u32x4 pv = prv;
; #pragma unroll
;                 for (int m = 0; m < 4; ++m) { const u32x4 cur = gq[m]; u32x4 hw;
; #pragma unroll
;                     for (int hv = 0; hv < 2; ++hv) { const u32x2 c2 = half2(cur, hv), p2 = half2(pv, hv);
;                         const u32x2 q1 = dpp_prev<1>(p2, c2), q2 = dpp_prev<2>(p2, c2);
;                         float g0[4], g1[4], g2[4]; unpk4(c2, g0); unpk4(q1, g1); unpk4(q2, g2);
;                         const u32x2 r = finish2(g0, g1, g2, w0[hv], w1[hv], w2[hv], bb[hv], acc[ai][bj][m][hv], rs8[ai][m]);
;                         if (hv == 0) { hw.x = r.x; hw.y = r.y; } else { hw.z = r.x; hw.w = r.y; } }
;                     *(u32x4*)(H + (size_t)(R0 + fr + 16 * m) * 2816 + col8) = hw;
;                     pv = cur; } }
	v_pk_fma_f32 v[50:51], v[48:49], v[50:51], s[42:43] op_sel_hi:[1,1,0]
	s_nop 0
	v_pk_fma_f32 v[50:51], v[48:49], v[50:51], s[44:45] op_sel_hi:[1,1,0]
	s_nop 0
	v_pk_fma_f32 v[50:51], v[48:49], v[50:51], s[46:47] op_sel_hi:[1,1,0]
	s_nop 0
	v_pk_fma_f32 v[48:49], v[48:49], v[50:51], s[48:49] op_sel_hi:[1,1,0]
	s_nop 0
	v_pk_mul_f32 v[46:47], v[46:47], v[48:49]
	v_lshlrev_b32_e32 v48, 16, v104
	v_pk_fma_f32 v[44:45], v[44:45], v[46:47], v[44:45]
	v_and_b32_e32 v49, 0xffff0000, v104
	v_pk_mul_f32 v[42:43], v[42:43], v[44:45]
	v_mov_b32_dpp v45, v108 row_ror:2 row_mask:0xf bank_mask:0xf bound_ctrl:1
	v_mov_b32_dpp v47, v109 row_ror:2 row_mask:0xf bank_mask:0xf bound_ctrl:1
	v_cvt_pk_bf16_f32 v53, v42, v43
	v_mov_b32_dpp v43, v109 row_ror:1 row_mask:0xf bank_mask:0xf bound_ctrl:1
	v_mov_b32_dpp v45, v104 row_shr:2 row_mask:0xf bank_mask:0xf
	v_lshlrev_b32_e32 v44, 16, v45
	v_and_b32_e32 v45, 0xffff0000, v45
	v_pk_fma_f32 v[44:45], v[64:65], v[44:45], v[80:81]
	v_mov_b32_dpp v47, v105 row_shr:2 row_mask:0xf bank_mask:0xf
	v_pk_fma_f32 v[40:41], v[72:73], v[40:41], v[44:45]
	v_mov_b32_dpp v43, v105 row_shr:1 row_mask:0xf bank_mask:0xf
	v_pk_fma_f32 v[40:41], v[76:77], v[48:49], v[40:41]
	v_lshlrev_b32_e32 v46, 16, v47
	v_pk_mul_f32 v[44:45], v[40:41], s[30:31] op_sel_hi:[1,0]
	v_and_b32_e32 v47, 0xffff0000, v47
	v_med3_f32 v44, v44, s47, v225
	v_med3_f32 v45, v45, s47, v225
	v_pk_mul_f32 v[48:49], v[44:45], v[44:45]
	v_pk_mul_f32 v[40:41], v[40:41], 0.5 op_sel_hi:[1,0]
	v_pk_fma_f32 v[50:51], v[48:49], s[34:35], v[118:119] op_sel_hi:[1,0,0] neg_lo:[1,0,0] neg_hi:[1,0,0]
	v_lshlrev_b32_e32 v42, 16, v43
	v_pk_fma_f32 v[50:51], v[48:49], v[50:51], s[38:39] op_sel_hi:[1,1,0]
	v_and_b32_e32 v43, 0xffff0000, v43
	v_pk_fma_f32 v[50:51], v[48:49], v[50:51], s[40:41] op_sel_hi:[1,1,0]
	s_nop 0
	v_pk_fma_f32 v[50:51], v[48:49], v[50:51], s[42:43] op_sel_hi:[1,1,0]
	s_nop 0
	v_pk_fma_f32 v[50:51], v[48:49], v[50:51], s[44:45] op_sel_hi:[1,1,0]
	s_nop 0
	v_pk_fma_f32 v[50:51], v[48:49], v[50:51], s[46:47] op_sel_hi:[1,1,0]
	s_nop 0
	v_pk_fma_f32 v[48:49], v[48:49], v[50:51], s[48:49] op_sel_hi:[1,1,0]
	s_nop 0
	v_pk_mul_f32 v[44:45], v[44:45], v[48:49]
	s_nop 0
	v_pk_fma_f32 v[40:41], v[40:41], v[44:45], v[40:41]
	v_pk_fma_f32 v[44:45], v[66:67], v[46:47], v[82:83]
	v_pk_mul_f32 v[36:37], v[36:37], v[40:41]
	v_lshlrev_b32_e32 v40, 16, v105
	v_and_b32_e32 v41, 0xffff0000, v105
	v_pk_fma_f32 v[42:43], v[74:75], v[42:43], v[44:45]
	v_cvt_pk_bf16_f32 v54, v36, v37
	s_nop 0
	v_pk_fma_f32 v[40:41], v[78:79], v[40:41], v[42:43]
	s_nop 0
	v_pk_mul_f32 v[42:43], v[40:41], s[30:31] op_sel_hi:[1,0]
	v_pk_mul_f32 v[40:41], v[40:41], 0.5 op_sel_hi:[1,0]
	v_med3_f32 v42, v42, s47, v225
	v_med3_f32 v43, v43, s47, v225
	v_pk_mul_f32 v[44:45], v[42:43], v[42:43]
	s_nop 0
	v_pk_fma_f32 v[46:47], v[44:45], s[34:35], v[118:119] op_sel_hi:[1,0,0] neg_lo:[1,0,0] neg_hi:[1,0,0]
	s_nop 0
	v_pk_fma_f32 v[46:47], v[44:45], v[46:47], s[38:39] op_sel_hi:[1,1,0]
	s_nop 0
	v_pk_fma_f32 v[46:47], v[44:45], v[46:47], s[40:41] op_sel_hi:[1,1,0]
	s_nop 0
	v_pk_fma_f32 v[46:47], v[44:45], v[46:47], s[42:43] op_sel_hi:[1,1,0]
	s_nop 0
	v_pk_fma_f32 v[46:47], v[44:45], v[46:47], s[44:45] op_sel_hi:[1,1,0]
	s_nop 0
	v_pk_fma_f32 v[46:47], v[44:45], v[46:47], s[46:47] op_sel_hi:[1,1,0]
	s_nop 0
	v_pk_fma_f32 v[44:45], v[44:45], v[46:47], s[48:49] op_sel_hi:[1,1,0]
	s_nop 0
	v_pk_mul_f32 v[42:43], v[42:43], v[44:45]
	s_nop 0
	v_pk_fma_f32 v[40:41], v[40:41], v[42:43], v[40:41]
	s_nop 0
	v_pk_mul_f32 v[2:3], v[2:3], v[40:41]
	s_nop 0
	v_cvt_pk_bf16_f32 v55, v2, v3
	v_lshl_add_u64 v[2:3], v[164:165], 0, v[60:61]
	v_add_co_u32_e32 v36, vcc, s10, v2
	s_nop 1
	v_addc_co_u32_e32 v37, vcc, 0, v3, vcc
	global_load_dwordx4 v[48:51], v[2:3], off nt
	global_load_dwordx4 v[44:47], v[36:37], off nt
	v_add_co_u32_e32 v36, vcc, 0x2c000, v2
	s_nop 1
	v_addc_co_u32_e32 v37, vcc, 0, v3, vcc
	v_add_co_u32_e32 v38, vcc, 0x42000, v2
	s_nop 1
	v_addc_co_u32_e32 v39, vcc, 0, v3, vcc
	global_load_dwordx4 v[40:43], v[36:37], off nt
	s_nop 0
	global_load_dwordx4 v[36:39], v[38:39], off nt
	s_andn2_b64 vcc, exec, s[2:3]
	global_store_dwordx4 v[56:57], v[52:55], off
	s_cbranch_vccnz .LBB0_1020
	v_add_co_u32_e32 v2, vcc, 0xfffea000, v2
	s_nop 1
	v_addc_co_u32_e32 v3, vcc, -1, v3, vcc
	global_load_dwordx4 v[100:103], v[2:3], off nt

;     __device__ __forceinline__ void operator()(const f32x4 (&acc)[2][2][4][2], const Unit& u, int wr, int wc, int fr, int fq) const {
;     ...
;             for (int m = 0; m < 4; ++m) rs8[ai][m] = rsqrtf(SS[u.rb + (u.half ? 0 : ai * HALF) + wr * 64 + fr + 16 * m] * (1.f / 1024.f) + 1e-6f);
;         if (u.pm < 128) {
; #pragma unroll
;           for (int bj = 0; bj < 2; ++bj) {
;             const int col8 = u.pn * BM + bj * HALF + wc * 32 + 8 * fq;
;             float w0[2][4], w1[2][4], w2[2][4], bb[2][4];
; #pragma unroll
;             for (int hv = 0; hv < 2; ++hv) { ld4f(cw + col8 + 4 * hv, w0[hv]); ld4f(cw + 2816 + col8 + 4 * hv, w1[hv]); ld4f(cw + 2 * 2816 + col8 + 4 * hv, w2[hv]); ld4f(cb + col8 + 4 * hv, bb[hv]); }
; #pragma unroll
;             for (int ai = 0; ai < 2; ++ai) { const int R0 = u.rb + ai * HALF + wr * 64; const bf16_t* gp = G + (size_t)(R0 + fr) * 2816 + col8;
;                 u32x4 gq[4], prv = (u32x4){0u, 0u, 0u, 0u};
; #pragma unroll
;                 for (int m = 0; m < 4; ++m) gq[m] = *(const u32x4*)(gp + (size_t)m * 16 * 2816);
;                 if ((R0 & 8191) != 0) prv = *(const u32x4*)(gp - (size_t)16 * 2816);
.LBB0_3142:
	s_and_b64 s[0:1], s[2:3], exec
	s_cselect_b32 s0, 0x80, 0
	v_add_u32_e32 v132, s0, v210
	v_add_u32_e32 v134, 16, v132
	v_ashrrev_i32_e32 v133, 31, v132
	v_ashrrev_i32_e32 v135, 31, v134
	s_lshl_b32 s0, s80, 8
	v_lshl_add_u64 v[164:165], v[132:133], 2, s[10:11]
	v_lshl_add_u64 v[166:167], v[134:135], 2, s[10:11]
	v_add_u32_e32 v134, 32, v132
	v_add_u32_e32 v132, 48, v132
	v_add_u32_e32 v212, s0, v3
	v_readlane_b32 s0, v240, 12
	v_ashrrev_i32_e32 v133, 31, v132
	v_readlane_b32 s1, v240, 13
	v_lshl_add_u64 v[132:133], v[132:133], 2, s[10:11]
	v_ashrrev_i32_e32 v213, 31, v212
	v_mov_b64_e32 v[170:171], s[0:1]
	global_load_dword v185, v[132:133], off
	v_lshlrev_b64 v[132:133], 2, v[212:213]
	v_mad_i64_i32 v[214:215], s[0:1], v210, s67, v[170:171]
	v_ashrrev_i32_e32 v135, 31, v134
	v_lshl_add_u64 v[136:137], s[12:13], 0, v[132:133]
	v_lshl_add_u64 v[140:141], s[18:19], 0, v[132:133]
	v_lshl_add_u64 v[144:145], s[20:21], 0, v[132:133]
	v_lshl_add_u64 v[160:161], s[14:15], 0, v[132:133]
	v_lshl_add_u64 v[180:181], v[212:213], 1, v[214:215]
	v_lshl_add_u64 v[168:169], v[134:135], 2, s[10:11]
	global_load_dwordx4 v[132:135], v[136:137], off offset:16
	global_load_dwordx4 v[148:151], v[136:137], off
	s_nop 0
	global_load_dwordx4 v[136:139], v[140:141], off offset:16
	global_load_dwordx4 v[152:155], v[140:141], off
	s_nop 0
	global_load_dwordx4 v[140:143], v[144:145], off offset:16
	global_load_dwordx4 v[156:159], v[144:145], off
	s_nop 0
	global_load_dwordx4 v[144:147], v[160:161], off offset:16
	s_nop 0
	global_load_dwordx4 v[160:163], v[160:161], off
	s_nop 0
	global_load_dword v189, v[164:165], off
	global_load_dword v187, v[166:167], off
	global_load_dword v3, v[168:169], off
	global_load_dwordx4 v[176:179], v[180:181], off nt
	v_add_co_u32_e32 v164, vcc, s45, v180
	s_and_b32 s0, s47, 0x1fff
	s_nop 0
	v_addc_co_u32_e32 v165, vcc, 0, v181, vcc
	v_add_co_u32_e32 v166, vcc, 0x2c000, v180
	s_cmp_lg_u32 s0, 0
	s_nop 0
	v_addc_co_u32_e32 v167, vcc, 0, v181, vcc
	global_load_dwordx4 v[172:175], v[164:165], off nt
	global_load_dwordx4 v[168:171], v[166:167], off nt
	v_add_co_u32_e32 v164, vcc, 0x42000, v180
	s_cselect_b64 s[2:3], -1, 0
	s_nop 0
	v_addc_co_u32_e32 v165, vcc, 0, v181, vcc
	global_load_dwordx4 v[164:167], v[164:165], off nt
	s_cmp_eq_u32 s0, 0
	s_cbranch_scc1 .LBB0_3144
	v_add_co_u32_e32 v180, vcc, 0xfffea000, v180
	s_nop 1
	v_addc_co_u32_e32 v181, vcc, -1, v181, vcc
	global_load_dwordx4 v[180:183], v[180:181], off nt
	s_branch .LBB0_3145

; __device__ __forceinline__ unsigned cvt_pk_bf16(float lo, float hi) { unsigned r; asm volatile("v_cvt_pk_bf16_f32 %0, %1, %2" : "=v"(r) : "v"(lo), "v"(hi)); return r; }
;     static __device__ __forceinline__ void unpk4(const u32x2 w, float (&o)[4]) { o[0] = bf_lo(w.x); o[1] = bf_hi(w.x); o[2] = bf_lo(w.y); o[3] = bf_hi(w.y); }
;     template <int N> static __device__ __forceinline__ u32x2 dpp_prev(const u32x2 pv, const u32x2 cur) { u32x2 r; r.x = dpp_prev1<N>(pv.x, cur.x); r.y = dpp_prev1<N>(pv.y, cur.y); return r; }
;     static __device__ __forceinline__ u32x2 finish2(const float (&g0)[4], const float (&g1)[4], const float (&g2)[4], const float (&w0)[4], const float (&w1)[4], const float (&w2)[4], const float (&bb)[4],
;                                                     const f32x4 v, float rs) {
;         float h[4];
; #pragma unroll
;         for (int j = 0; j < 4; j += 2) {
;             const f32x2 gc = (f32x2){bb[j] + w0[j] * g2[j] + w1[j] * g1[j] + w2[j] * g0[j], bb[j + 1] + w0[j + 1] * g2[j + 1] + w1[j + 1] * g1[j + 1] + w2[j + 1] * g0[j + 1]};
;             const f32x2 ge = gelu_pk(gc) * ((f32x2){v[j], v[j + 1]} * rs); h[j] = ge.x; h[j + 1] = ge.y; }
;         u32x2 w; w.x = cvt_pk_bf16(h[0], h[1]); w.y = cvt_pk_bf16(h[2], h[3]); return w;
;     }
;     __device__ __forceinline__ void operator()(const f32x4 (&acc)[2][2][4][2], const Unit& u, int wr, int wc, int fr, int fq) const {
;     ...
; #pragma unroll
;                 for (int m = 0; m < 4; ++m) { const u32x4 cur = gq[m]; u32x4 hw;
; #pragma unroll
;                     for (int hv = 0; hv < 2; ++hv) { const u32x2 c2 = half2(cur, hv), p2 = half2(pv, hv);
;                         const u32x2 q1 = dpp_prev<1>(p2, c2), q2 = dpp_prev<2>(p2, c2);
;                         float g0[4], g1[4], g2[4]; unpk4(c2, g0); unpk4(q1, g1); unpk4(q2, g2);
;                         const u32x2 r = finish2(g0, g1, g2, w0[hv], w1[hv], w2[hv], bb[hv], acc[ai][bj][m][hv], rs8[ai][m]);
;                         if (hv == 0) { hw.x = r.x; hw.y = r.y; } else { hw.z = r.x; hw.w = r.y; } }
;                     *(u32x4*)(H + (size_t)(R0 + fr + 16 * m) * 2816 + col8) = hw;
;                     pv = cur; } }
.LBB0_3145:
	s_waitcnt vmcnt(0)
	v_mov_b32_dpp v195, v180 row_ror:2 row_mask:0xf bank_mask:0xf bound_ctrl:1
	v_mov_b32_dpp v191, v180 row_ror:1 row_mask:0xf bank_mask:0xf bound_ctrl:1
	v_mad_i64_i32 v[230:231], s[0:1], v210, s67, 0
	v_mov_b32_dpp v195, v176 row_shr:2 row_mask:0xf bank_mask:0xf
	v_mov_b32_dpp v191, v176 row_shr:1 row_mask:0xf bank_mask:0xf
	v_lshlrev_b32_e32 v210, 16, v195
	v_and_b32_e32 v211, 0xffff0000, v195
	v_mov_b32_dpp v193, v181 row_ror:1 row_mask:0xf bank_mask:0xf bound_ctrl:1
	v_mov_b32_dpp v225, v181 row_ror:2 row_mask:0xf bank_mask:0xf bound_ctrl:1
	v_lshlrev_b32_e32 v180, 16, v191
	v_and_b32_e32 v181, 0xffff0000, v191
	v_pk_fma_f32 v[210:211], v[148:149], v[210:211], v[160:161]
	v_lshlrev_b32_e32 v232, 16, v176
	v_and_b32_e32 v233, 0xffff0000, v176
	v_pk_fma_f32 v[180:181], v[152:153], v[180:181], v[210:211]
	v_mov_b32_dpp v225, v177 row_shr:2 row_mask:0xf bank_mask:0xf
	v_pk_fma_f32 v[180:181], v[156:157], v[232:233], v[180:181]
	v_mov_b32_dpp v193, v177 row_shr:1 row_mask:0xf bank_mask:0xf
	v_pk_mul_f32 v[210:211], v[180:181], s[26:27] op_sel_hi:[1,0]
	v_lshlrev_b32_e32 v228, 16, v225
	v_med3_f32 v232, v210, s71, v224
	v_med3_f32 v233, v211, s71, v224
	v_pk_mul_f32 v[234:235], v[232:233], v[232:233]
	v_mov_b64_e32 v[210:211], s[30:31]
	v_pk_fma_f32 v[236:237], v[234:235], s[28:29], v[210:211] op_sel_hi:[1,0,0] neg_lo:[1,0,0] neg_hi:[1,0,0]
	v_and_b32_e32 v229, 0xffff0000, v225
	v_pk_fma_f32 v[236:237], v[234:235], v[236:237], s[34:35] op_sel_hi:[1,1,0]
	v_pk_mul_f32 v[180:181], v[180:181], 0.5 op_sel_hi:[1,0]
	v_pk_fma_f32 v[236:237], v[234:235], v[236:237], s[36:37] op_sel_hi:[1,1,0]
	v_lshlrev_b32_e32 v226, 16, v193
	v_pk_fma_f32 v[236:237], v[234:235], v[236:237], s[38:39] op_sel_hi:[1,1,0]
	v_and_b32_e32 v227, 0xffff0000, v193
	v_pk_fma_f32 v[236:237], v[234:235], v[236:237], s[40:41] op_sel_hi:[1,1,0]
	v_pk_mul_f32 v[128:129], v[128:129], v[188:189] op_sel_hi:[1,0]
	v_pk_fma_f32 v[236:237], v[234:235], v[236:237], s[42:43] op_sel_hi:[1,1,0]
	v_pk_fma_f32 v[228:229], v[150:151], v[228:229], v[162:163]
	v_pk_fma_f32 v[234:235], v[234:235], v[236:237], s[44:45] op_sel_hi:[1,1,0]
	v_pk_fma_f32 v[226:227], v[154:155], v[226:227], v[228:229]
	v_pk_mul_f32 v[232:233], v[232:233], v[234:235]
	v_pk_mul_f32 v[130:131], v[130:131], v[188:189] op_sel_hi:[1,0]
	v_pk_fma_f32 v[180:181], v[180:181], v[232:233], v[180:181]
	v_pk_mul_f32 v[124:125], v[124:125], v[188:189] op_sel_hi:[1,0]
	v_pk_mul_f32 v[128:129], v[128:129], v[180:181]
	v_lshlrev_b32_e32 v180, 16, v177
	v_and_b32_e32 v181, 0xffff0000, v177
	v_pk_fma_f32 v[180:181], v[158:159], v[180:181], v[226:227]
	v_readlane_b32 s0, v240, 58
	v_pk_mul_f32 v[226:227], v[180:181], s[26:27] op_sel_hi:[1,0]
	v_pk_mul_f32 v[180:181], v[180:181], 0.5 op_sel_hi:[1,0]
	v_med3_f32 v226, v226, s71, v224
	v_med3_f32 v227, v227, s71, v224
	v_pk_mul_f32 v[228:229], v[226:227], v[226:227]
	v_readlane_b32 s1, v240, 59
	v_pk_fma_f32 v[232:233], v[228:229], s[28:29], v[210:211] op_sel_hi:[1,0,0] neg_lo:[1,0,0] neg_hi:[1,0,0]
	v_pk_mul_f32 v[126:127], v[126:127], v[188:189] op_sel_hi:[1,0]
	v_pk_fma_f32 v[232:233], v[228:229], v[232:233], s[34:35] op_sel_hi:[1,1,0]
	v_pk_mul_f32 v[120:121], v[120:121], v[186:187] op_sel_hi:[1,0]
	v_pk_fma_f32 v[232:233], v[228:229], v[232:233], s[36:37] op_sel_hi:[1,1,0]
	v_pk_mul_f32 v[122:123], v[122:123], v[186:187] op_sel_hi:[1,0]
	v_pk_fma_f32 v[232:233], v[228:229], v[232:233], s[38:39] op_sel_hi:[1,1,0]
	v_pk_mul_f32 v[116:117], v[116:117], v[186:187] op_sel_hi:[1,0]
	v_pk_fma_f32 v[232:233], v[228:229], v[232:233], s[40:41] op_sel_hi:[1,1,0]
	v_pk_mul_f32 v[118:119], v[118:119], v[186:187] op_sel_hi:[1,0]
	v_pk_fma_f32 v[232:233], v[228:229], v[232:233], s[42:43] op_sel_hi:[1,1,0]
	v_pk_mul_f32 v[112:113], v[112:113], v[184:185] op_sel_hi:[1,0]
	v_pk_fma_f32 v[228:229], v[228:229], v[232:233], s[44:45] op_sel_hi:[1,1,0]
	v_pk_mul_f32 v[114:115], v[114:115], v[184:185] op_sel_hi:[1,0]
	v_pk_mul_f32 v[226:227], v[226:227], v[228:229]
	v_lshlrev_b32_e32 v228, 16, v178
	v_pk_fma_f32 v[180:181], v[180:181], v[226:227], v[180:181]
	v_cvt_pk_bf16_f32 v226, v128, v129
	v_mov_b32_dpp v129, v182 row_ror:1 row_mask:0xf bank_mask:0xf bound_ctrl:1
	v_pk_mul_f32 v[130:131], v[130:131], v[180:181]
	v_mov_b32_dpp v181, v182 row_ror:2 row_mask:0xf bank_mask:0xf bound_ctrl:1
	v_mov_b32_dpp v129, v178 row_shr:1 row_mask:0xf bank_mask:0xf
	v_lshlrev_b32_e32 v128, 16, v129
	v_mov_b32_dpp v181, v178 row_shr:2 row_mask:0xf bank_mask:0xf
	v_lshlrev_b32_e32 v180, 16, v181
	v_and_b32_e32 v181, 0xffff0000, v181
	v_and_b32_e32 v129, 0xffff0000, v129
	v_pk_fma_f32 v[180:181], v[132:133], v[180:181], v[144:145]
	v_and_b32_e32 v229, 0xffff0000, v178
	v_pk_fma_f32 v[128:129], v[136:137], v[128:129], v[180:181]
	v_cvt_pk_bf16_f32 v227, v130, v131
	v_mov_b32_dpp v131, v183 row_ror:1 row_mask:0xf bank_mask:0xf bound_ctrl:1
	v_pk_fma_f32 v[128:129], v[140:141], v[228:229], v[128:129]
	v_mov_b32_dpp v183, v183 row_ror:2 row_mask:0xf bank_mask:0xf bound_ctrl:1
	v_pk_mul_f32 v[180:181], v[128:129], s[26:27] op_sel_hi:[1,0]
	v_mov_b32_dpp v131, v179 row_shr:1 row_mask:0xf bank_mask:0xf
	v_med3_f32 v180, v180, s71, v224
	v_med3_f32 v181, v181, s71, v224
	v_pk_mul_f32 v[228:229], v[180:181], v[180:181]
	v_mov_b32_dpp v183, v179 row_shr:2 row_mask:0xf bank_mask:0xf
	v_pk_fma_f32 v[232:233], v[228:229], s[28:29], v[210:211] op_sel_hi:[1,0,0] neg_lo:[1,0,0] neg_hi:[1,0,0]
	v_lshlrev_b32_e32 v182, 16, v183
	v_pk_fma_f32 v[232:233], v[228:229], v[232:233], s[34:35] op_sel_hi:[1,1,0]
	v_and_b32_e32 v183, 0xffff0000, v183
	v_pk_fma_f32 v[232:233], v[228:229], v[232:233], s[36:37] op_sel_hi:[1,1,0]
; __device__ __forceinline__ unsigned cvt_pk_bf16(float lo, float hi) { unsigned r; asm volatile("v_cvt_pk_bf16_f32 %0, %1, %2" : "=v"(r) : "v"(lo), "v"(hi)); return r; }
;     static __device__ __forceinline__ void unpk4(const u32x2 w, float (&o)[4]) { o[0] = bf_lo(w.x); o[1] = bf_hi(w.x); o[2] = bf_lo(w.y); o[3] = bf_hi(w.y); }
;     template <int N> static __device__ __forceinline__ u32x2 dpp_prev(const u32x2 pv, const u32x2 cur) { u32x2 r; r.x = dpp_prev1<N>(pv.x, cur.x); r.y = dpp_prev1<N>(pv.y, cur.y); return r; }
;     static __device__ __forceinline__ u32x2 finish2(const float (&g0)[4], const float (&g1)[4], const float (&g2)[4], const float (&w0)[4], const float (&w1)[4], const float (&w2)[4], const float (&bb)[4],
;                                                     const f32x4 v, float rs) {
;         float h[4];
; #pragma unroll
;         for (int j = 0; j < 4; j += 2) {
;             const f32x2 gc = (f32x2){bb[j] + w0[j] * g2[j] + w1[j] * g1[j] + w2[j] * g0[j], bb[j + 1] + w0[j + 1] * g2[j + 1] + w1[j + 1] * g1[j + 1] + w2[j + 1] * g0[j + 1]};
;             const f32x2 ge = gelu_pk(gc) * ((f32x2){v[j], v[j + 1]} * rs); h[j] = ge.x; h[j + 1] = ge.y; }
;         u32x2 w; w.x = cvt_pk_bf16(h[0], h[1]); w.y = cvt_pk_bf16(h[2], h[3]); return w;
;     }
;     __device__ __forceinline__ void operator()(const f32x4 (&acc)[2][2][4][2], const Unit& u, int wr, int wc, int fr, int fq) const {
;     ...
; #pragma unroll
;                 for (int m = 0; m < 4; ++m) { const u32x4 cur = gq[m]; u32x4 hw;
; #pragma unroll
;                     for (int hv = 0; hv < 2; ++hv) { const u32x2 c2 = half2(cur, hv), p2 = half2(pv, hv);
;                         const u32x2 q1 = dpp_prev<1>(p2, c2), q2 = dpp_prev<2>(p2, c2);
;                         float g0[4], g1[4], g2[4]; unpk4(c2, g0); unpk4(q1, g1); unpk4(q2, g2);
;                         const u32x2 r = finish2(g0, g1, g2, w0[hv], w1[hv], w2[hv], bb[hv], acc[ai][bj][m][hv], rs8[ai][m]);
;                         if (hv == 0) { hw.x = r.x; hw.y = r.y; } else { hw.z = r.x; hw.w = r.y; } }
;                     *(u32x4*)(H + (size_t)(R0 + fr + 16 * m) * 2816 + col8) = hw;
;                     pv = cur; } }
	v_pk_mul_f32 v[128:129], v[128:129], 0.5 op_sel_hi:[1,0]
	v_pk_fma_f32 v[232:233], v[228:229], v[232:233], s[38:39] op_sel_hi:[1,1,0]
	v_lshlrev_b32_e32 v130, 16, v131
	v_pk_fma_f32 v[232:233], v[228:229], v[232:233], s[40:41] op_sel_hi:[1,1,0]
	v_and_b32_e32 v131, 0xffff0000, v131
	v_pk_fma_f32 v[232:233], v[228:229], v[232:233], s[42:43] op_sel_hi:[1,1,0]
	v_pk_mul_f32 v[108:109], v[108:109], v[184:185] op_sel_hi:[1,0]
	v_pk_fma_f32 v[228:229], v[228:229], v[232:233], s[44:45] op_sel_hi:[1,1,0]
	v_pk_mul_f32 v[110:111], v[110:111], v[184:185] op_sel_hi:[1,0]
	v_pk_mul_f32 v[180:181], v[180:181], v[228:229]
	v_pk_mul_f32 v[104:105], v[104:105], v[2:3] op_sel_hi:[1,0]
	v_pk_fma_f32 v[128:129], v[128:129], v[180:181], v[128:129]
	v_pk_fma_f32 v[180:181], v[134:135], v[182:183], v[146:147]
	v_pk_mul_f32 v[124:125], v[124:125], v[128:129]
	v_lshlrev_b32_e32 v128, 16, v179
	v_and_b32_e32 v129, 0xffff0000, v179
	v_pk_fma_f32 v[130:131], v[138:139], v[130:131], v[180:181]
	v_cvt_pk_bf16_f32 v228, v124, v125
	v_pk_mul_f32 v[106:107], v[106:107], v[2:3] op_sel_hi:[1,0]
	v_pk_fma_f32 v[128:129], v[142:143], v[128:129], v[130:131]
	v_pk_mul_f32 v[100:101], v[100:101], v[2:3] op_sel_hi:[1,0]
	v_pk_mul_f32 v[130:131], v[128:129], s[26:27] op_sel_hi:[1,0]
	v_pk_mul_f32 v[128:129], v[128:129], 0.5 op_sel_hi:[1,0]
	v_med3_f32 v130, v130, s71, v224
	v_med3_f32 v131, v131, s71, v224
	v_pk_mul_f32 v[180:181], v[130:131], v[130:131]
	s_addk_i32 s47, 0x80
	v_pk_fma_f32 v[182:183], v[180:181], s[28:29], v[210:211] op_sel_hi:[1,0,0] neg_lo:[1,0,0] neg_hi:[1,0,0]
	v_add_u32_e32 v1, s47, v1
	v_pk_fma_f32 v[182:183], v[180:181], v[182:183], s[34:35] op_sel_hi:[1,1,0]
	v_pk_mul_f32 v[102:103], v[102:103], v[2:3] op_sel_hi:[1,0]
	v_pk_fma_f32 v[182:183], v[180:181], v[182:183], s[36:37] op_sel_hi:[1,1,0]
	s_nop 0
	v_pk_fma_f32 v[182:183], v[180:181], v[182:183], s[38:39] op_sel_hi:[1,1,0]
	s_nop 0
	v_pk_fma_f32 v[182:183], v[180:181], v[182:183], s[40:41] op_sel_hi:[1,1,0]
	s_nop 0
	v_pk_fma_f32 v[182:183], v[180:181], v[182:183], s[42:43] op_sel_hi:[1,1,0]
	s_nop 0
	v_pk_fma_f32 v[180:181], v[180:181], v[182:183], s[44:45] op_sel_hi:[1,1,0]
	v_lshlrev_b32_e32 v182, 16, v172
	v_pk_mul_f32 v[130:131], v[130:131], v[180:181]
	v_lshlrev_b64 v[180:181], 1, v[212:213]
	v_pk_fma_f32 v[128:129], v[128:129], v[130:131], v[128:129]
	v_lshl_add_u64 v[130:131], s[0:1], 0, v[230:231]
	v_pk_mul_f32 v[126:127], v[126:127], v[128:129]
	v_lshl_add_u64 v[124:125], v[130:131], 0, v[180:181]
	v_mov_b32_dpp v129, v176 row_ror:2 row_mask:0xf bank_mask:0xf bound_ctrl:1
	v_cvt_pk_bf16_f32 v229, v126, v127
	global_store_dwordx4 v[124:125], v[226:229], off
	v_mov_b32_dpp v125, v176 row_ror:1 row_mask:0xf bank_mask:0xf bound_ctrl:1
	v_mov_b32_dpp v129, v172 row_shr:2 row_mask:0xf bank_mask:0xf
	v_lshlrev_b32_e32 v128, 16, v129
	v_mov_b32_dpp v125, v172 row_shr:1 row_mask:0xf bank_mask:0xf
	v_and_b32_e32 v129, 0xffff0000, v129
	v_lshlrev_b32_e32 v124, 16, v125
	v_and_b32_e32 v125, 0xffff0000, v125
	v_pk_fma_f32 v[128:129], v[148:149], v[128:129], v[160:161]
	v_and_b32_e32 v183, 0xffff0000, v172
	v_pk_fma_f32 v[124:125], v[152:153], v[124:125], v[128:129]
	v_mov_b32_dpp v127, v177 row_ror:1 row_mask:0xf bank_mask:0xf bound_ctrl:1
	v_pk_fma_f32 v[124:125], v[156:157], v[182:183], v[124:125]
	v_mov_b32_dpp v177, v177 row_ror:2 row_mask:0xf bank_mask:0xf bound_ctrl:1
	v_pk_mul_f32 v[128:129], v[124:125], s[26:27] op_sel_hi:[1,0]
	v_mov_b32_dpp v127, v173 row_shr:1 row_mask:0xf bank_mask:0xf
	v_med3_f32 v128, v128, s71, v224
	v_med3_f32 v129, v129, s71, v224
	v_pk_mul_f32 v[182:183], v[128:129], v[128:129]
	v_mov_b32_dpp v177, v173 row_shr:2 row_mask:0xf bank_mask:0xf
	v_pk_fma_f32 v[226:227], v[182:183], s[28:29], v[210:211] op_sel_hi:[1,0,0] neg_lo:[1,0,0] neg_hi:[1,0,0]
	v_lshlrev_b32_e32 v176, 16, v177
	v_pk_fma_f32 v[226:227], v[182:183], v[226:227], s[34:35] op_sel_hi:[1,1,0]
	v_and_b32_e32 v177, 0xffff0000, v177
	v_pk_fma_f32 v[226:227], v[182:183], v[226:227], s[36:37] op_sel_hi:[1,1,0]
	v_pk_mul_f32 v[124:125], v[124:125], 0.5 op_sel_hi:[1,0]
	v_pk_fma_f32 v[226:227], v[182:183], v[226:227], s[38:39] op_sel_hi:[1,1,0]
	v_lshlrev_b32_e32 v126, 16, v127
	v_pk_fma_f32 v[226:227], v[182:183], v[226:227], s[40:41] op_sel_hi:[1,1,0]
	v_and_b32_e32 v127, 0xffff0000, v127
	v_pk_fma_f32 v[226:227], v[182:183], v[226:227], s[42:43] op_sel_hi:[1,1,0]
	s_nop 0
	v_pk_fma_f32 v[182:183], v[182:183], v[226:227], s[44:45] op_sel_hi:[1,1,0]
	s_nop 0
	v_pk_mul_f32 v[128:129], v[128:129], v[182:183]
	s_nop 0
	v_pk_fma_f32 v[124:125], v[124:125], v[128:129], v[124:125]
	v_pk_fma_f32 v[128:129], v[150:151], v[176:177], v[162:163]
	v_pk_mul_f32 v[120:121], v[120:121], v[124:125]
	v_lshlrev_b32_e32 v124, 16, v173
	v_and_b32_e32 v125, 0xffff0000, v173
	v_pk_fma_f32 v[126:127], v[154:155], v[126:127], v[128:129]
	v_cvt_pk_bf16_f32 v120, v120, v121
	s_nop 0
	v_pk_fma_f32 v[124:125], v[158:159], v[124:125], v[126:127]
	s_nop 0
	v_pk_mul_f32 v[126:127], v[124:125], s[26:27] op_sel_hi:[1,0]
	v_pk_mul_f32 v[124:125], v[124:125], 0.5 op_sel_hi:[1,0]
	v_med3_f32 v126, v126, s71, v224
	v_med3_f32 v127, v127, s71, v224
	v_pk_mul_f32 v[128:129], v[126:127], v[126:127]
	s_nop 0
	v_pk_fma_f32 v[176:177], v[128:129], s[28:29], v[210:211] op_sel_hi:[1,0,0] neg_lo:[1,0,0] neg_hi:[1,0,0]
	s_nop 0
	v_pk_fma_f32 v[176:177], v[128:129], v[176:177], s[34:35] op_sel_hi:[1,1,0]
	s_nop 0
	v_pk_fma_f32 v[176:177], v[128:129], v[176:177], s[36:37] op_sel_hi:[1,1,0]
	s_nop 0
	v_pk_fma_f32 v[176:177], v[128:129], v[176:177], s[38:39] op_sel_hi:[1,1,0]
	s_nop 0
	v_pk_fma_f32 v[176:177], v[128:129], v[176:177], s[40:41] op_sel_hi:[1,1,0]
; __device__ __forceinline__ unsigned cvt_pk_bf16(float lo, float hi) { unsigned r; asm volatile("v_cvt_pk_bf16_f32 %0, %1, %2" : "=v"(r) : "v"(lo), "v"(hi)); return r; }
;     static __device__ __forceinline__ void unpk4(const u32x2 w, float (&o)[4]) { o[0] = bf_lo(w.x); o[1] = bf_hi(w.x); o[2] = bf_lo(w.y); o[3] = bf_hi(w.y); }
;     template <int N> static __device__ __forceinline__ u32x2 dpp_prev(const u32x2 pv, const u32x2 cur) { u32x2 r; r.x = dpp_prev1<N>(pv.x, cur.x); r.y = dpp_prev1<N>(pv.y, cur.y); return r; }
;     static __device__ __forceinline__ u32x2 finish2(const float (&g0)[4], const float (&g1)[4], const float (&g2)[4], const float (&w0)[4], const float (&w1)[4], const float (&w2)[4], const float (&bb)[4],
;                                                     const f32x4 v, float rs) {
;         float h[4];
; #pragma unroll
;         for (int j = 0; j < 4; j += 2) {
;             const f32x2 gc = (f32x2){bb[j] + w0[j] * g2[j] + w1[j] * g1[j] + w2[j] * g0[j], bb[j + 1] + w0[j + 1] * g2[j + 1] + w1[j + 1] * g1[j + 1] + w2[j + 1] * g0[j + 1]};
;             const f32x2 ge = gelu_pk(gc) * ((f32x2){v[j], v[j + 1]} * rs); h[j] = ge.x; h[j + 1] = ge.y; }
;         u32x2 w; w.x = cvt_pk_bf16(h[0], h[1]); w.y = cvt_pk_bf16(h[2], h[3]); return w;
;     }
;     __device__ __forceinline__ void operator()(const f32x4 (&acc)[2][2][4][2], const Unit& u, int wr, int wc, int fr, int fq) const {
;     ...
; #pragma unroll
;                 for (int m = 0; m < 4; ++m) { const u32x4 cur = gq[m]; u32x4 hw;
; #pragma unroll
;                     for (int hv = 0; hv < 2; ++hv) { const u32x2 c2 = half2(cur, hv), p2 = half2(pv, hv);
;                         const u32x2 q1 = dpp_prev<1>(p2, c2), q2 = dpp_prev<2>(p2, c2);
;                         float g0[4], g1[4], g2[4]; unpk4(c2, g0); unpk4(q1, g1); unpk4(q2, g2);
;                         const u32x2 r = finish2(g0, g1, g2, w0[hv], w1[hv], w2[hv], bb[hv], acc[ai][bj][m][hv], rs8[ai][m]);
;                         if (hv == 0) { hw.x = r.x; hw.y = r.y; } else { hw.z = r.x; hw.w = r.y; } }
;                     *(u32x4*)(H + (size_t)(R0 + fr + 16 * m) * 2816 + col8) = hw;
;                     pv = cur; } }
	s_nop 0
	v_pk_fma_f32 v[176:177], v[128:129], v[176:177], s[42:43] op_sel_hi:[1,1,0]
	s_nop 0
	v_pk_fma_f32 v[128:129], v[128:129], v[176:177], s[44:45] op_sel_hi:[1,1,0]
	v_lshlrev_b32_e32 v176, 16, v174
	v_pk_mul_f32 v[126:127], v[126:127], v[128:129]
	v_and_b32_e32 v177, 0xffff0000, v174
	v_pk_fma_f32 v[124:125], v[124:125], v[126:127], v[124:125]
	v_mov_b32_dpp v127, v178 row_ror:2 row_mask:0xf bank_mask:0xf bound_ctrl:1
	v_pk_mul_f32 v[122:123], v[122:123], v[124:125]
	v_mov_b32_dpp v125, v179 row_ror:1 row_mask:0xf bank_mask:0xf bound_ctrl:1
	v_cvt_pk_bf16_f32 v121, v122, v123
	v_mov_b32_dpp v127, v174 row_shr:2 row_mask:0xf bank_mask:0xf
	v_mov_b32_dpp v123, v178 row_ror:1 row_mask:0xf bank_mask:0xf bound_ctrl:1
	v_lshlrev_b32_e32 v126, 16, v127
	v_and_b32_e32 v127, 0xffff0000, v127
	v_mov_b32_dpp v123, v174 row_shr:1 row_mask:0xf bank_mask:0xf
	v_lshlrev_b32_e32 v122, 16, v123
	v_and_b32_e32 v123, 0xffff0000, v123
	v_pk_fma_f32 v[126:127], v[132:133], v[126:127], v[144:145]
	v_mov_b32_dpp v129, v179 row_ror:2 row_mask:0xf bank_mask:0xf bound_ctrl:1
	v_pk_fma_f32 v[122:123], v[136:137], v[122:123], v[126:127]
	v_mov_b32_dpp v125, v175 row_shr:1 row_mask:0xf bank_mask:0xf
	v_pk_fma_f32 v[122:123], v[140:141], v[176:177], v[122:123]
	v_mov_b32_dpp v129, v175 row_shr:2 row_mask:0xf bank_mask:0xf
	v_pk_mul_f32 v[126:127], v[122:123], s[26:27] op_sel_hi:[1,0]
	v_lshlrev_b32_e32 v128, 16, v129
	v_med3_f32 v126, v126, s71, v224
	v_med3_f32 v127, v127, s71, v224
	v_pk_mul_f32 v[176:177], v[126:127], v[126:127]
	v_and_b32_e32 v129, 0xffff0000, v129
	v_pk_fma_f32 v[178:179], v[176:177], s[28:29], v[210:211] op_sel_hi:[1,0,0] neg_lo:[1,0,0] neg_hi:[1,0,0]
	v_pk_mul_f32 v[122:123], v[122:123], 0.5 op_sel_hi:[1,0]
	v_pk_fma_f32 v[178:179], v[176:177], v[178:179], s[34:35] op_sel_hi:[1,1,0]
	v_lshlrev_b32_e32 v124, 16, v125
	v_pk_fma_f32 v[178:179], v[176:177], v[178:179], s[36:37] op_sel_hi:[1,1,0]
	v_and_b32_e32 v125, 0xffff0000, v125
	v_pk_fma_f32 v[178:179], v[176:177], v[178:179], s[38:39] op_sel_hi:[1,1,0]
	s_nop 0
	v_pk_fma_f32 v[178:179], v[176:177], v[178:179], s[40:41] op_sel_hi:[1,1,0]
	s_nop 0
	v_pk_fma_f32 v[178:179], v[176:177], v[178:179], s[42:43] op_sel_hi:[1,1,0]
	s_nop 0
	v_pk_fma_f32 v[176:177], v[176:177], v[178:179], s[44:45] op_sel_hi:[1,1,0]
	s_nop 0
	v_pk_mul_f32 v[126:127], v[126:127], v[176:177]
	s_nop 0
	v_pk_fma_f32 v[122:123], v[122:123], v[126:127], v[122:123]
	v_pk_fma_f32 v[126:127], v[134:135], v[128:129], v[146:147]
	v_pk_mul_f32 v[116:117], v[116:117], v[122:123]
	v_lshlrev_b32_e32 v122, 16, v175
	v_and_b32_e32 v123, 0xffff0000, v175
	v_pk_fma_f32 v[124:125], v[138:139], v[124:125], v[126:127]
	s_nop 0
	v_pk_fma_f32 v[122:123], v[142:143], v[122:123], v[124:125]
	s_nop 0
	v_pk_mul_f32 v[124:125], v[122:123], s[26:27] op_sel_hi:[1,0]
	v_pk_mul_f32 v[122:123], v[122:123], 0.5 op_sel_hi:[1,0]
	v_med3_f32 v124, v124, s71, v224
	v_med3_f32 v125, v125, s71, v224
	v_pk_mul_f32 v[126:127], v[124:125], v[124:125]
	s_nop 0
	v_pk_fma_f32 v[128:129], v[126:127], s[28:29], v[210:211] op_sel_hi:[1,0,0] neg_lo:[1,0,0] neg_hi:[1,0,0]
	s_nop 0
	v_pk_fma_f32 v[128:129], v[126:127], v[128:129], s[34:35] op_sel_hi:[1,1,0]
	s_nop 0
	v_pk_fma_f32 v[128:129], v[126:127], v[128:129], s[36:37] op_sel_hi:[1,1,0]
	s_nop 0
	v_pk_fma_f32 v[128:129], v[126:127], v[128:129], s[38:39] op_sel_hi:[1,1,0]
	s_nop 0
	v_pk_fma_f32 v[128:129], v[126:127], v[128:129], s[40:41] op_sel_hi:[1,1,0]
	s_nop 0
	v_pk_fma_f32 v[128:129], v[126:127], v[128:129], s[42:43] op_sel_hi:[1,1,0]
	s_nop 0
	v_pk_fma_f32 v[126:127], v[126:127], v[128:129], s[44:45] op_sel_hi:[1,1,0]
	s_nop 0
	v_pk_mul_f32 v[124:125], v[124:125], v[126:127]
	v_lshlrev_b32_e32 v126, 16, v168
	v_pk_fma_f32 v[122:123], v[122:123], v[124:125], v[122:123]
	v_and_b32_e32 v127, 0xffff0000, v168
	v_pk_mul_f32 v[118:119], v[118:119], v[122:123]
	v_cvt_pk_bf16_f32 v122, v116, v117
	v_mov_b64_e32 v[116:117], s[0:1]
	v_mad_i64_i32 v[176:177], s[0:1], v194, s67, v[116:117]
	v_cvt_pk_bf16_f32 v123, v118, v119
	v_lshl_add_u64 v[118:119], v[176:177], 0, v[180:181]
	global_store_dwordx4 v[118:119], v[120:123], off
	v_mov_b32_dpp v125, v173 row_ror:2 row_mask:0xf bank_mask:0xf bound_ctrl:1
	v_mov_b32_dpp v119, v172 row_ror:1 row_mask:0xf bank_mask:0xf bound_ctrl:1
	v_mov_b32_dpp v123, v172 row_ror:2 row_mask:0xf bank_mask:0xf bound_ctrl:1
	v_mov_b32_dpp v121, v173 row_ror:1 row_mask:0xf bank_mask:0xf bound_ctrl:1
	v_mov_b32_dpp v119, v168 row_shr:1 row_mask:0xf bank_mask:0xf
	v_mov_b32_dpp v123, v168 row_shr:2 row_mask:0xf bank_mask:0xf
	v_lshlrev_b32_e32 v122, 16, v123
	v_and_b32_e32 v123, 0xffff0000, v123
	v_lshlrev_b32_e32 v118, 16, v119
	v_and_b32_e32 v119, 0xffff0000, v119
	v_pk_fma_f32 v[122:123], v[148:149], v[122:123], v[160:161]
	v_mov_b32_dpp v125, v169 row_shr:2 row_mask:0xf bank_mask:0xf
	v_pk_fma_f32 v[118:119], v[152:153], v[118:119], v[122:123]
	v_mov_b32_dpp v121, v169 row_shr:1 row_mask:0xf bank_mask:0xf
	v_pk_fma_f32 v[118:119], v[156:157], v[126:127], v[118:119]
	v_lshlrev_b32_e32 v124, 16, v125
	v_pk_mul_f32 v[122:123], v[118:119], s[26:27] op_sel_hi:[1,0]
	v_and_b32_e32 v125, 0xffff0000, v125
	v_med3_f32 v122, v122, s71, v224
	v_med3_f32 v123, v123, s71, v224
	v_pk_mul_f32 v[126:127], v[122:123], v[122:123]
	v_pk_mul_f32 v[118:119], v[118:119], 0.5 op_sel_hi:[1,0]
	v_pk_fma_f32 v[128:129], v[126:127], s[28:29], v[210:211] op_sel_hi:[1,0,0] neg_lo:[1,0,0] neg_hi:[1,0,0]
	v_lshlrev_b32_e32 v120, 16, v121
	v_pk_fma_f32 v[128:129], v[126:127], v[128:129], s[34:35] op_sel_hi:[1,1,0]
	v_and_b32_e32 v121, 0xffff0000, v121
	v_pk_fma_f32 v[128:129], v[126:127], v[128:129], s[36:37] op_sel_hi:[1,1,0]
; __device__ __forceinline__ unsigned cvt_pk_bf16(float lo, float hi) { unsigned r; asm volatile("v_cvt_pk_bf16_f32 %0, %1, %2" : "=v"(r) : "v"(lo), "v"(hi)); return r; }
;     static __device__ __forceinline__ void unpk4(const u32x2 w, float (&o)[4]) { o[0] = bf_lo(w.x); o[1] = bf_hi(w.x); o[2] = bf_lo(w.y); o[3] = bf_hi(w.y); }
;     template <int N> static __device__ __forceinline__ u32x2 dpp_prev(const u32x2 pv, const u32x2 cur) { u32x2 r; r.x = dpp_prev1<N>(pv.x, cur.x); r.y = dpp_prev1<N>(pv.y, cur.y); return r; }
;     static __device__ __forceinline__ u32x2 finish2(const float (&g0)[4], const float (&g1)[4], const float (&g2)[4], const float (&w0)[4], const float (&w1)[4], const float (&w2)[4], const float (&bb)[4],
;                                                     const f32x4 v, float rs) {
;         float h[4];
; #pragma unroll
;         for (int j = 0; j < 4; j += 2) {
;             const f32x2 gc = (f32x2){bb[j] + w0[j] * g2[j] + w1[j] * g1[j] + w2[j] * g0[j], bb[j + 1] + w0[j + 1] * g2[j + 1] + w1[j + 1] * g1[j + 1] + w2[j + 1] * g0[j + 1]};
;             const f32x2 ge = gelu_pk(gc) * ((f32x2){v[j], v[j + 1]} * rs); h[j] = ge.x; h[j + 1] = ge.y; }
;         u32x2 w; w.x = cvt_pk_bf16(h[0], h[1]); w.y = cvt_pk_bf16(h[2], h[3]); return w;
;     }
;     __device__ __forceinline__ void operator()(const f32x4 (&acc)[2][2][4][2], const Unit& u, int wr, int wc, int fr, int fq) const {
;     ...
; #pragma unroll
;                 for (int m = 0; m < 4; ++m) { const u32x4 cur = gq[m]; u32x4 hw;
; #pragma unroll
;                     for (int hv = 0; hv < 2; ++hv) { const u32x2 c2 = half2(cur, hv), p2 = half2(pv, hv);
;                         const u32x2 q1 = dpp_prev<1>(p2, c2), q2 = dpp_prev<2>(p2, c2);
;                         float g0[4], g1[4], g2[4]; unpk4(c2, g0); unpk4(q1, g1); unpk4(q2, g2);
;                         const u32x2 r = finish2(g0, g1, g2, w0[hv], w1[hv], w2[hv], bb[hv], acc[ai][bj][m][hv], rs8[ai][m]);
;                         if (hv == 0) { hw.x = r.x; hw.y = r.y; } else { hw.z = r.x; hw.w = r.y; } }
;                     *(u32x4*)(H + (size_t)(R0 + fr + 16 * m) * 2816 + col8) = hw;
;                     pv = cur; } }
	v_mad_i64_i32 v[172:173], s[0:1], v192, s67, v[116:117]
	v_pk_fma_f32 v[128:129], v[126:127], v[128:129], s[38:39] op_sel_hi:[1,1,0]
	v_readlane_b32 s0, v240, 12
	v_pk_fma_f32 v[128:129], v[126:127], v[128:129], s[40:41] op_sel_hi:[1,1,0]
	v_readlane_b32 s1, v240, 13
	v_pk_fma_f32 v[128:129], v[126:127], v[128:129], s[42:43] op_sel_hi:[1,1,0]
	s_nop 0
	v_pk_fma_f32 v[126:127], v[126:127], v[128:129], s[44:45] op_sel_hi:[1,1,0]
	s_nop 0
	v_pk_mul_f32 v[122:123], v[122:123], v[126:127]
	s_nop 0
	v_pk_fma_f32 v[118:119], v[118:119], v[122:123], v[118:119]
	v_pk_fma_f32 v[122:123], v[150:151], v[124:125], v[162:163]
	v_pk_mul_f32 v[112:113], v[112:113], v[118:119]
	v_lshlrev_b32_e32 v118, 16, v169
	v_and_b32_e32 v119, 0xffff0000, v169
	v_pk_fma_f32 v[120:121], v[154:155], v[120:121], v[122:123]
	v_cvt_pk_bf16_f32 v112, v112, v113
	s_nop 0
	v_pk_fma_f32 v[118:119], v[158:159], v[118:119], v[120:121]
	s_nop 0
	v_pk_mul_f32 v[120:121], v[118:119], s[26:27] op_sel_hi:[1,0]
	v_pk_mul_f32 v[118:119], v[118:119], 0.5 op_sel_hi:[1,0]
	v_med3_f32 v120, v120, s71, v224
	v_med3_f32 v121, v121, s71, v224
	v_pk_mul_f32 v[122:123], v[120:121], v[120:121]
	s_nop 0
	v_pk_fma_f32 v[124:125], v[122:123], s[28:29], v[210:211] op_sel_hi:[1,0,0] neg_lo:[1,0,0] neg_hi:[1,0,0]
	s_nop 0
	v_pk_fma_f32 v[124:125], v[122:123], v[124:125], s[34:35] op_sel_hi:[1,1,0]
	s_nop 0
	v_pk_fma_f32 v[124:125], v[122:123], v[124:125], s[36:37] op_sel_hi:[1,1,0]
	s_nop 0
	v_pk_fma_f32 v[124:125], v[122:123], v[124:125], s[38:39] op_sel_hi:[1,1,0]
	s_nop 0
	v_pk_fma_f32 v[124:125], v[122:123], v[124:125], s[40:41] op_sel_hi:[1,1,0]
	s_nop 0
	v_pk_fma_f32 v[124:125], v[122:123], v[124:125], s[42:43] op_sel_hi:[1,1,0]
	s_nop 0
	v_pk_fma_f32 v[122:123], v[122:123], v[124:125], s[44:45] op_sel_hi:[1,1,0]
	v_lshlrev_b32_e32 v124, 16, v170
	v_pk_mul_f32 v[120:121], v[120:121], v[122:123]
	v_and_b32_e32 v125, 0xffff0000, v170
	v_pk_fma_f32 v[118:119], v[118:119], v[120:121], v[118:119]
	v_mov_b32_dpp v121, v174 row_ror:2 row_mask:0xf bank_mask:0xf bound_ctrl:1
	v_pk_mul_f32 v[114:115], v[114:115], v[118:119]
	v_mov_b32_dpp v123, v175 row_ror:2 row_mask:0xf bank_mask:0xf bound_ctrl:1
	v_cvt_pk_bf16_f32 v113, v114, v115
	v_mov_b32_dpp v121, v170 row_shr:2 row_mask:0xf bank_mask:0xf
	v_mov_b32_dpp v115, v174 row_ror:1 row_mask:0xf bank_mask:0xf bound_ctrl:1
	v_lshlrev_b32_e32 v120, 16, v121
	v_and_b32_e32 v121, 0xffff0000, v121
	v_mov_b32_dpp v115, v170 row_shr:1 row_mask:0xf bank_mask:0xf
	v_lshlrev_b32_e32 v114, 16, v115
	v_and_b32_e32 v115, 0xffff0000, v115
	v_pk_fma_f32 v[120:121], v[132:133], v[120:121], v[144:145]
	v_mov_b32_dpp v119, v175 row_ror:1 row_mask:0xf bank_mask:0xf bound_ctrl:1
	v_pk_fma_f32 v[114:115], v[136:137], v[114:115], v[120:121]
	v_mov_b32_dpp v123, v171 row_shr:2 row_mask:0xf bank_mask:0xf
	v_pk_fma_f32 v[114:115], v[140:141], v[124:125], v[114:115]
	v_mov_b32_dpp v119, v171 row_shr:1 row_mask:0xf bank_mask:0xf
	v_pk_mul_f32 v[120:121], v[114:115], s[26:27] op_sel_hi:[1,0]
	v_lshlrev_b32_e32 v122, 16, v123
	v_med3_f32 v120, v120, s71, v224
	v_med3_f32 v121, v121, s71, v224
	v_pk_mul_f32 v[124:125], v[120:121], v[120:121]
	v_and_b32_e32 v123, 0xffff0000, v123
	v_pk_fma_f32 v[126:127], v[124:125], s[28:29], v[210:211] op_sel_hi:[1,0,0] neg_lo:[1,0,0] neg_hi:[1,0,0]
	v_pk_mul_f32 v[114:115], v[114:115], 0.5 op_sel_hi:[1,0]
	v_pk_fma_f32 v[126:127], v[124:125], v[126:127], s[34:35] op_sel_hi:[1,1,0]
	v_lshlrev_b32_e32 v118, 16, v119
	v_pk_fma_f32 v[126:127], v[124:125], v[126:127], s[36:37] op_sel_hi:[1,1,0]
	v_and_b32_e32 v119, 0xffff0000, v119
	v_pk_fma_f32 v[126:127], v[124:125], v[126:127], s[38:39] op_sel_hi:[1,1,0]
	s_nop 0
	v_pk_fma_f32 v[126:127], v[124:125], v[126:127], s[40:41] op_sel_hi:[1,1,0]
	s_nop 0
	v_pk_fma_f32 v[126:127], v[124:125], v[126:127], s[42:43] op_sel_hi:[1,1,0]
	s_nop 0
	v_pk_fma_f32 v[124:125], v[124:125], v[126:127], s[44:45] op_sel_hi:[1,1,0]
	s_nop 0
	v_pk_mul_f32 v[120:121], v[120:121], v[124:125]
	s_nop 0
	v_pk_fma_f32 v[114:115], v[114:115], v[120:121], v[114:115]
	v_pk_fma_f32 v[120:121], v[134:135], v[122:123], v[146:147]
	v_pk_mul_f32 v[108:109], v[108:109], v[114:115]
	v_lshlrev_b32_e32 v114, 16, v171
	v_and_b32_e32 v115, 0xffff0000, v171
	v_pk_fma_f32 v[118:119], v[138:139], v[118:119], v[120:121]
	s_nop 0
	v_pk_fma_f32 v[114:115], v[142:143], v[114:115], v[118:119]
	s_nop 0
	v_pk_mul_f32 v[118:119], v[114:115], s[26:27] op_sel_hi:[1,0]
	v_pk_mul_f32 v[114:115], v[114:115], 0.5 op_sel_hi:[1,0]
	v_med3_f32 v118, v118, s71, v224
	v_med3_f32 v119, v119, s71, v224
	v_pk_mul_f32 v[120:121], v[118:119], v[118:119]
	s_nop 0
	v_pk_fma_f32 v[122:123], v[120:121], s[28:29], v[210:211] op_sel_hi:[1,0,0] neg_lo:[1,0,0] neg_hi:[1,0,0]
	s_nop 0
	v_pk_fma_f32 v[122:123], v[120:121], v[122:123], s[34:35] op_sel_hi:[1,1,0]
	s_nop 0
	v_pk_fma_f32 v[122:123], v[120:121], v[122:123], s[36:37] op_sel_hi:[1,1,0]
	s_nop 0
	v_pk_fma_f32 v[122:123], v[120:121], v[122:123], s[38:39] op_sel_hi:[1,1,0]
	s_nop 0
	v_pk_fma_f32 v[122:123], v[120:121], v[122:123], s[40:41] op_sel_hi:[1,1,0]
	s_nop 0
	v_pk_fma_f32 v[122:123], v[120:121], v[122:123], s[42:43] op_sel_hi:[1,1,0]
	s_nop 0
	v_pk_fma_f32 v[120:121], v[120:121], v[122:123], s[44:45] op_sel_hi:[1,1,0]
	s_nop 0
	v_pk_mul_f32 v[118:119], v[118:119], v[120:121]
	s_nop 0
	v_pk_fma_f32 v[114:115], v[114:115], v[118:119], v[114:115]
	v_lshlrev_b32_e32 v118, 16, v164
	v_pk_mul_f32 v[110:111], v[110:111], v[114:115]
	v_cvt_pk_bf16_f32 v114, v108, v109
	v_lshl_add_u64 v[108:109], v[172:173], 0, v[180:181]
	v_cvt_pk_bf16_f32 v115, v110, v111
	global_store_dwordx4 v[108:109], v[112:115], off
; __device__ __forceinline__ unsigned cvt_pk_bf16(float lo, float hi) { unsigned r; asm volatile("v_cvt_pk_bf16_f32 %0, %1, %2" : "=v"(r) : "v"(lo), "v"(hi)); return r; }
;     static __device__ __forceinline__ void unpk4(const u32x2 w, float (&o)[4]) { o[0] = bf_lo(w.x); o[1] = bf_hi(w.x); o[2] = bf_lo(w.y); o[3] = bf_hi(w.y); }
;     template <int N> static __device__ __forceinline__ u32x2 dpp_prev(const u32x2 pv, const u32x2 cur) { u32x2 r; r.x = dpp_prev1<N>(pv.x, cur.x); r.y = dpp_prev1<N>(pv.y, cur.y); return r; }
;     static __device__ __forceinline__ u32x2 finish2(const float (&g0)[4], const float (&g1)[4], const float (&g2)[4], const float (&w0)[4], const float (&w1)[4], const float (&w2)[4], const float (&bb)[4],
;                                                     const f32x4 v, float rs) {
;         float h[4];
; #pragma unroll
;         for (int j = 0; j < 4; j += 2) {
;             const f32x2 gc = (f32x2){bb[j] + w0[j] * g2[j] + w1[j] * g1[j] + w2[j] * g0[j], bb[j + 1] + w0[j + 1] * g2[j + 1] + w1[j + 1] * g1[j + 1] + w2[j + 1] * g0[j + 1]};
;             const f32x2 ge = gelu_pk(gc) * ((f32x2){v[j], v[j + 1]} * rs); h[j] = ge.x; h[j + 1] = ge.y; }
;         u32x2 w; w.x = cvt_pk_bf16(h[0], h[1]); w.y = cvt_pk_bf16(h[2], h[3]); return w;
;     }
;     __device__ __forceinline__ void operator()(const f32x4 (&acc)[2][2][4][2], const Unit& u, int wr, int wc, int fr, int fq) const {
;     ...
; #pragma unroll
;                 for (int m = 0; m < 4; ++m) { const u32x4 cur = gq[m]; u32x4 hw;
; #pragma unroll
;                     for (int hv = 0; hv < 2; ++hv) { const u32x2 c2 = half2(cur, hv), p2 = half2(pv, hv);
;                         const u32x2 q1 = dpp_prev<1>(p2, c2), q2 = dpp_prev<2>(p2, c2);
;                         float g0[4], g1[4], g2[4]; unpk4(c2, g0); unpk4(q1, g1); unpk4(q2, g2);
;                         const u32x2 r = finish2(g0, g1, g2, w0[hv], w1[hv], w2[hv], bb[hv], acc[ai][bj][m][hv], rs8[ai][m]);
;                         if (hv == 0) { hw.x = r.x; hw.y = r.y; } else { hw.z = r.x; hw.w = r.y; } }
;                     *(u32x4*)(H + (size_t)(R0 + fr + 16 * m) * 2816 + col8) = hw;
;                     pv = cur; } }
	v_and_b32_e32 v119, 0xffff0000, v164
	v_mov_b32_dpp v109, v168 row_ror:1 row_mask:0xf bank_mask:0xf bound_ctrl:1
	v_mov_b32_dpp v113, v168 row_ror:2 row_mask:0xf bank_mask:0xf bound_ctrl:1
	v_mov_b32_dpp v115, v169 row_ror:2 row_mask:0xf bank_mask:0xf bound_ctrl:1
	v_mov_b32_dpp v109, v164 row_shr:1 row_mask:0xf bank_mask:0xf
	v_mov_b32_dpp v113, v164 row_shr:2 row_mask:0xf bank_mask:0xf
	v_lshlrev_b32_e32 v112, 16, v113
	v_and_b32_e32 v113, 0xffff0000, v113
	v_lshlrev_b32_e32 v108, 16, v109
	v_and_b32_e32 v109, 0xffff0000, v109
	v_pk_fma_f32 v[112:113], v[148:149], v[112:113], v[160:161]
	v_mov_b32_dpp v111, v169 row_ror:1 row_mask:0xf bank_mask:0xf bound_ctrl:1
	v_pk_fma_f32 v[108:109], v[152:153], v[108:109], v[112:113]
	v_mov_b32_dpp v115, v165 row_shr:2 row_mask:0xf bank_mask:0xf
	v_pk_fma_f32 v[108:109], v[156:157], v[118:119], v[108:109]
	v_mov_b32_dpp v111, v165 row_shr:1 row_mask:0xf bank_mask:0xf
	v_pk_mul_f32 v[112:113], v[108:109], s[26:27] op_sel_hi:[1,0]
	v_lshlrev_b32_e32 v114, 16, v115
	v_med3_f32 v112, v112, s71, v224
	v_med3_f32 v113, v113, s71, v224
	v_pk_mul_f32 v[118:119], v[112:113], v[112:113]
	v_and_b32_e32 v115, 0xffff0000, v115
	v_pk_fma_f32 v[120:121], v[118:119], s[28:29], v[210:211] op_sel_hi:[1,0,0] neg_lo:[1,0,0] neg_hi:[1,0,0]
	v_pk_mul_f32 v[108:109], v[108:109], 0.5 op_sel_hi:[1,0]
	v_pk_fma_f32 v[120:121], v[118:119], v[120:121], s[34:35] op_sel_hi:[1,1,0]
	v_lshlrev_b32_e32 v110, 16, v111
	v_pk_fma_f32 v[120:121], v[118:119], v[120:121], s[36:37] op_sel_hi:[1,1,0]
	v_and_b32_e32 v111, 0xffff0000, v111
	v_pk_fma_f32 v[120:121], v[118:119], v[120:121], s[38:39] op_sel_hi:[1,1,0]
	s_nop 0
	v_pk_fma_f32 v[120:121], v[118:119], v[120:121], s[40:41] op_sel_hi:[1,1,0]
	s_nop 0
	v_pk_fma_f32 v[120:121], v[118:119], v[120:121], s[42:43] op_sel_hi:[1,1,0]
	s_nop 0
	v_pk_fma_f32 v[118:119], v[118:119], v[120:121], s[44:45] op_sel_hi:[1,1,0]
	s_nop 0
	v_pk_mul_f32 v[112:113], v[112:113], v[118:119]
	s_nop 0
	v_pk_fma_f32 v[108:109], v[108:109], v[112:113], v[108:109]
	v_pk_fma_f32 v[112:113], v[150:151], v[114:115], v[162:163]
	v_pk_mul_f32 v[104:105], v[104:105], v[108:109]
	v_lshlrev_b32_e32 v108, 16, v165
	v_and_b32_e32 v109, 0xffff0000, v165
	v_pk_fma_f32 v[110:111], v[154:155], v[110:111], v[112:113]
	v_cvt_pk_bf16_f32 v120, v104, v105
	v_mov_b32_dpp v105, v170 row_ror:1 row_mask:0xf bank_mask:0xf bound_ctrl:1
	v_pk_fma_f32 v[108:109], v[158:159], v[108:109], v[110:111]
	s_nop 0
	v_pk_mul_f32 v[110:111], v[108:109], s[26:27] op_sel_hi:[1,0]
	v_pk_mul_f32 v[108:109], v[108:109], 0.5 op_sel_hi:[1,0]
	v_med3_f32 v110, v110, s71, v224
	v_med3_f32 v111, v111, s71, v224
	v_pk_mul_f32 v[112:113], v[110:111], v[110:111]
	v_mov_b32_dpp v105, v166 row_shr:1 row_mask:0xf bank_mask:0xf
	v_pk_fma_f32 v[114:115], v[112:113], s[28:29], v[210:211] op_sel_hi:[1,0,0] neg_lo:[1,0,0] neg_hi:[1,0,0]
	v_lshlrev_b32_e32 v104, 16, v105
	v_pk_fma_f32 v[114:115], v[112:113], v[114:115], s[34:35] op_sel_hi:[1,1,0]
	v_and_b32_e32 v105, 0xffff0000, v105
	v_pk_fma_f32 v[114:115], v[112:113], v[114:115], s[36:37] op_sel_hi:[1,1,0]
	s_nop 0
	v_pk_fma_f32 v[114:115], v[112:113], v[114:115], s[38:39] op_sel_hi:[1,1,0]
	s_nop 0
	v_pk_fma_f32 v[114:115], v[112:113], v[114:115], s[40:41] op_sel_hi:[1,1,0]
	s_nop 0
	v_pk_fma_f32 v[114:115], v[112:113], v[114:115], s[42:43] op_sel_hi:[1,1,0]
	s_nop 0
	v_pk_fma_f32 v[112:113], v[112:113], v[114:115], s[44:45] op_sel_hi:[1,1,0]
	s_nop 0
	v_pk_mul_f32 v[110:111], v[110:111], v[112:113]
	v_lshlrev_b32_e32 v112, 16, v166
	v_pk_fma_f32 v[108:109], v[108:109], v[110:111], v[108:109]
	v_and_b32_e32 v113, 0xffff0000, v166
	v_pk_mul_f32 v[106:107], v[106:107], v[108:109]
	v_mov_b32_dpp v109, v170 row_ror:2 row_mask:0xf bank_mask:0xf bound_ctrl:1
	v_mov_b32_dpp v111, v171 row_ror:2 row_mask:0xf bank_mask:0xf bound_ctrl:1
	v_cvt_pk_bf16_f32 v121, v106, v107
	v_mov_b32_dpp v107, v171 row_ror:1 row_mask:0xf bank_mask:0xf bound_ctrl:1
	v_mov_b32_dpp v109, v166 row_shr:2 row_mask:0xf bank_mask:0xf
;     static __device__ __forceinline__ void unpk4(const u32x2 w, float (&o)[4]) { o[0] = bf_lo(w.x); o[1] = bf_hi(w.x); o[2] = bf_lo(w.y); o[3] = bf_hi(w.y); }
;     template <int N> static __device__ __forceinline__ u32x2 dpp_prev(const u32x2 pv, const u32x2 cur) { u32x2 r; r.x = dpp_prev1<N>(pv.x, cur.x); r.y = dpp_prev1<N>(pv.y, cur.y); return r; }
;     __device__ __forceinline__ void operator()(const f32x4 (&acc)[2][2][4][2], const Unit& u, int wr, int wc, int fr, int fq) const {
;     ...
;             for (int ai = 0; ai < 2; ++ai) { const int R0 = u.rb + ai * HALF + wr * 64; const bf16_t* gp = G + (size_t)(R0 + fr) * 2816 + col8;
;                 u32x4 gq[4], prv = (u32x4){0u, 0u, 0u, 0u};
; #pragma unroll
;                 for (int m = 0; m < 4; ++m) gq[m] = *(const u32x4*)(gp + (size_t)m * 16 * 2816);
;                 if ((R0 & 8191) != 0) prv = *(const u32x4*)(gp - (size_t)16 * 2816);
;                 u32x4 pv = prv;
; #pragma unroll
;                 for (int m = 0; m < 4; ++m) { const u32x4 cur = gq[m]; u32x4 hw;
; #pragma unroll
;                     for (int hv = 0; hv < 2; ++hv) { const u32x2 c2 = half2(cur, hv), p2 = half2(pv, hv);
;                         const u32x2 q1 = dpp_prev<1>(p2, c2), q2 = dpp_prev<2>(p2, c2);
;                         float g0[4], g1[4], g2[4]; unpk4(c2, g0); unpk4(q1, g1); unpk4(q2, g2);
;                         const u32x2 r = finish2(g0, g1, g2, w0[hv], w1[hv], w2[hv], bb[hv], acc[ai][bj][m][hv], rs8[ai][m]);
;                         if (hv == 0) { hw.x = r.x; hw.y = r.y; } else { hw.z = r.x; hw.w = r.y; } }
;                     *(u32x4*)(H + (size_t)(R0 + fr + 16 * m) * 2816 + col8) = hw;
;                     pv = cur; } }
	v_lshlrev_b32_e32 v108, 16, v109
	v_and_b32_e32 v109, 0xffff0000, v109
	v_pk_fma_f32 v[108:109], v[132:133], v[108:109], v[144:145]
	v_mov_b32_dpp v111, v167 row_shr:2 row_mask:0xf bank_mask:0xf
	v_pk_fma_f32 v[104:105], v[136:137], v[104:105], v[108:109]
	v_mov_b32_dpp v107, v167 row_shr:1 row_mask:0xf bank_mask:0xf
	v_pk_fma_f32 v[104:105], v[140:141], v[112:113], v[104:105]
	v_lshlrev_b32_e32 v110, 16, v111
	v_pk_mul_f32 v[108:109], v[104:105], s[26:27] op_sel_hi:[1,0]
	v_and_b32_e32 v111, 0xffff0000, v111
	v_med3_f32 v108, v108, s71, v224
	v_med3_f32 v109, v109, s71, v224
	v_pk_mul_f32 v[112:113], v[108:109], v[108:109]
	v_pk_mul_f32 v[104:105], v[104:105], 0.5 op_sel_hi:[1,0]
	v_pk_fma_f32 v[114:115], v[112:113], s[28:29], v[210:211] op_sel_hi:[1,0,0] neg_lo:[1,0,0] neg_hi:[1,0,0]
	v_lshlrev_b32_e32 v106, 16, v107
	v_pk_fma_f32 v[114:115], v[112:113], v[114:115], s[34:35] op_sel_hi:[1,1,0]
	v_and_b32_e32 v107, 0xffff0000, v107
	v_pk_fma_f32 v[114:115], v[112:113], v[114:115], s[36:37] op_sel_hi:[1,1,0]
	s_nop 0
	v_pk_fma_f32 v[114:115], v[112:113], v[114:115], s[38:39] op_sel_hi:[1,1,0]
	s_nop 0
	v_pk_fma_f32 v[114:115], v[112:113], v[114:115], s[40:41] op_sel_hi:[1,1,0]
	s_nop 0
	v_pk_fma_f32 v[114:115], v[112:113], v[114:115], s[42:43] op_sel_hi:[1,1,0]
	s_nop 0
	v_pk_fma_f32 v[112:113], v[112:113], v[114:115], s[44:45] op_sel_hi:[1,1,0]
	s_nop 0
	v_pk_mul_f32 v[108:109], v[108:109], v[112:113]
	s_nop 0
	v_pk_fma_f32 v[104:105], v[104:105], v[108:109], v[104:105]
	v_pk_fma_f32 v[108:109], v[134:135], v[110:111], v[146:147]
	v_pk_mul_f32 v[100:101], v[100:101], v[104:105]
	v_lshlrev_b32_e32 v104, 16, v167
	v_and_b32_e32 v105, 0xffff0000, v167
	v_pk_fma_f32 v[106:107], v[138:139], v[106:107], v[108:109]
	v_cvt_pk_bf16_f32 v122, v100, v101
	v_mov_b64_e32 v[100:101], s[0:1]
	v_pk_fma_f32 v[104:105], v[142:143], v[104:105], v[106:107]
	v_mad_i64_i32 v[164:165], s[0:1], v1, s67, v[100:101]
	v_pk_mul_f32 v[106:107], v[104:105], s[26:27] op_sel_hi:[1,0]
	v_lshl_add_u64 v[118:119], v[164:165], 0, v[180:181]
	v_med3_f32 v106, v106, s71, v224
	v_med3_f32 v107, v107, s71, v224
	v_pk_mul_f32 v[108:109], v[106:107], v[106:107]
	v_pk_mul_f32 v[104:105], v[104:105], 0.5 op_sel_hi:[1,0]
	v_pk_fma_f32 v[110:111], v[108:109], s[28:29], v[210:211] op_sel_hi:[1,0,0] neg_lo:[1,0,0] neg_hi:[1,0,0]
	v_add_co_u32_e32 v100, vcc, s45, v118
	v_pk_fma_f32 v[110:111], v[108:109], v[110:111], s[34:35] op_sel_hi:[1,1,0]
	s_nop 0
	v_addc_co_u32_e32 v101, vcc, 0, v119, vcc
	v_pk_fma_f32 v[110:111], v[108:109], v[110:111], s[36:37] op_sel_hi:[1,1,0]
	v_mad_i64_i32 v[166:167], s[0:1], v190, s67, v[116:117]
	v_pk_fma_f32 v[110:111], v[108:109], v[110:111], s[38:39] op_sel_hi:[1,1,0]
	s_and_b32 s0, s47, 0x1fff
	v_pk_fma_f32 v[110:111], v[108:109], v[110:111], s[40:41] op_sel_hi:[1,1,0]
	s_cmp_lg_u32 s0, 0
	v_pk_fma_f32 v[110:111], v[108:109], v[110:111], s[42:43] op_sel_hi:[1,1,0]
	v_lshl_add_u64 v[116:117], v[166:167], 0, v[180:181]
	v_pk_fma_f32 v[108:109], v[108:109], v[110:111], s[44:45] op_sel_hi:[1,1,0]
	s_cselect_b64 s[8:9], -1, 0
	v_pk_mul_f32 v[106:107], v[106:107], v[108:109]
	s_cmp_eq_u32 s0, 0
	v_pk_fma_f32 v[104:105], v[104:105], v[106:107], v[104:105]
	s_nop 0
	v_pk_mul_f32 v[102:103], v[102:103], v[104:105]
	s_nop 0
	v_cvt_pk_bf16_f32 v123, v102, v103
	global_load_dwordx4 v[112:115], v[118:119], off nt
	global_load_dwordx4 v[108:111], v[100:101], off nt
	v_add_co_u32_e32 v100, vcc, 0x2c000, v118
	s_nop 1
	v_addc_co_u32_e32 v101, vcc, 0, v119, vcc
	v_add_co_u32_e32 v102, vcc, 0x42000, v118
	s_nop 1
	v_addc_co_u32_e32 v103, vcc, 0, v119, vcc
	global_load_dwordx4 v[104:107], v[100:101], off nt
	s_nop 0
	global_load_dwordx4 v[100:103], v[102:103], off nt
	s_nop 0
	global_store_dwordx4 v[116:117], v[120:123], off
	s_cbranch_scc1 .LBB0_3147
	v_add_co_u32_e32 v116, vcc, 0xfffea000, v118
	s_nop 1
	v_addc_co_u32_e32 v117, vcc, -1, v119, vcc
	global_load_dwordx4 v[116:119], v[116:117], off nt
	s_branch .LBB0_3148

;     static __device__ __forceinline__ void unpk4(const u32x2 w, float (&o)[4]) { o[0] = bf_lo(w.x); o[1] = bf_hi(w.x); o[2] = bf_lo(w.y); o[3] = bf_hi(w.y); }
;     template <int N> static __device__ __forceinline__ u32x2 dpp_prev(const u32x2 pv, const u32x2 cur) { u32x2 r; r.x = dpp_prev1<N>(pv.x, cur.x); r.y = dpp_prev1<N>(pv.y, cur.y); return r; }
;     __device__ __forceinline__ void operator()(const f32x4 (&acc)[2][2][4][2], const Unit& u, int wr, int wc, int fr, int fq) const {
;     ...
;         float rs8[2][4];
; #pragma unroll
;         for (int ai = 0; ai < 2; ++ai)
; #pragma unroll
;             for (int m = 0; m < 4; ++m) rs8[ai][m] = rsqrtf(SS[u.rb + (u.half ? 0 : ai * HALF) + wr * 64 + fr + 16 * m] * (1.f / 1024.f) + 1e-6f);
;     ...
; #pragma unroll
;                 for (int m = 0; m < 4; ++m) { const u32x4 cur = gq[m]; u32x4 hw;
; #pragma unroll
;                     for (int hv = 0; hv < 2; ++hv) { const u32x2 c2 = half2(cur, hv), p2 = half2(pv, hv);
;                         const u32x2 q1 = dpp_prev<1>(p2, c2), q2 = dpp_prev<2>(p2, c2);
;                         float g0[4], g1[4], g2[4]; unpk4(c2, g0); unpk4(q1, g1); unpk4(q2, g2);
;                         const u32x2 r = finish2(g0, g1, g2, w0[hv], w1[hv], w2[hv], bb[hv], acc[ai][bj][m][hv], rs8[ai][m]);
;                         if (hv == 0) { hw.x = r.x; hw.y = r.y; } else { hw.z = r.x; hw.w = r.y; } }
;                     *(u32x4*)(H + (size_t)(R0 + fr + 16 * m) * 2816 + col8) = hw;
;                     pv = cur; } }
.LBB0_3148:
	v_fmamk_f32 v120, v189, 0x3a800000, v223
	v_mul_f32_e32 v121, 0x4b800000, v120
	v_cmp_gt_f32_e32 vcc, s66, v120
	v_fmamk_f32 v3, v3, 0x3a800000, v223
	s_waitcnt vmcnt(0)
	v_mov_b32_dpp v127, v117 row_ror:2 row_mask:0xf bank_mask:0xf bound_ctrl:1
	v_cndmask_b32_e32 v120, v120, v121, vcc
	v_rsq_f32_e32 v122, v120
	v_fmamk_f32 v120, v187, 0x3a800000, v223
	v_mul_f32_e32 v121, 0x4b800000, v120
	v_cmp_gt_f32_e64 s[0:1], s66, v120
	v_mul_f32_e32 v124, 0x45800000, v122
	v_cndmask_b32_e32 v128, v122, v124, vcc
	v_cndmask_b32_e64 v120, v120, v121, s[0:1]
	v_mul_f32_e32 v124, 0x4b800000, v3
	v_cmp_gt_f32_e32 vcc, s66, v3
	v_rsq_f32_e32 v123, v120
	v_mad_i64_i32 v[120:121], s[6:7], v1, s67, 0
	v_cndmask_b32_e32 v3, v3, v124, vcc
	v_fmamk_f32 v124, v185, 0x3a800000, v223
	v_mul_f32_e32 v125, 0x4b800000, v124
	v_cmp_gt_f32_e64 s[6:7], s66, v124
	v_rsq_f32_e32 v3, v3
	v_mul_f32_e32 v122, 0x45800000, v123
	v_cndmask_b32_e64 v124, v124, v125, s[6:7]
	v_rsq_f32_e32 v125, v124
	v_cndmask_b32_e64 v126, v123, v122, s[0:1]
	v_mul_f32_e32 v122, 0x45800000, v3
	v_cndmask_b32_e32 v124, v3, v122, vcc
	v_mul_f32_e32 v3, 0x45800000, v125
	v_cndmask_b32_e64 v122, v125, v3, s[6:7]
	v_mov_b32_dpp v125, v116 row_ror:2 row_mask:0xf bank_mask:0xf bound_ctrl:1
	v_mov_b32_dpp v3, v116 row_ror:1 row_mask:0xf bank_mask:0xf bound_ctrl:1
	v_mov_b32_dpp v123, v117 row_ror:1 row_mask:0xf bank_mask:0xf bound_ctrl:1
	v_mov_b32_dpp v125, v112 row_shr:2 row_mask:0xf bank_mask:0xf
	v_mov_b32_dpp v3, v112 row_shr:1 row_mask:0xf bank_mask:0xf
	v_lshlrev_b32_e32 v170, 16, v125
	v_and_b32_e32 v171, 0xffff0000, v125
	v_lshlrev_b32_e32 v116, 16, v3
	v_and_b32_e32 v117, 0xffff0000, v3
	v_pk_fma_f32 v[170:171], v[148:149], v[170:171], v[160:161]
	v_lshlrev_b32_e32 v178, 16, v112
	v_and_b32_e32 v179, 0xffff0000, v112
	v_pk_fma_f32 v[116:117], v[152:153], v[116:117], v[170:171]
	v_mov_b32_dpp v127, v113 row_shr:2 row_mask:0xf bank_mask:0xf
	v_pk_fma_f32 v[170:171], v[156:157], v[178:179], v[116:117]
	v_mov_b32_dpp v123, v113 row_shr:1 row_mask:0xf bank_mask:0xf
	v_pk_mul_f32 v[116:117], v[170:171], s[26:27] op_sel_hi:[1,0]
	v_lshlrev_b32_e32 v174, 16, v127
	v_med3_f32 v178, v116, s71, v224
	v_med3_f32 v179, v117, s71, v224
	v_pk_mul_f32 v[182:183], v[178:179], v[178:179]
	v_mov_b64_e32 v[116:117], s[30:31]
	v_pk_fma_f32 v[190:191], v[182:183], s[28:29], v[116:117] op_sel_hi:[1,0,0] neg_lo:[1,0,0] neg_hi:[1,0,0]
	v_and_b32_e32 v175, 0xffff0000, v127
	v_pk_fma_f32 v[190:191], v[182:183], v[190:191], s[34:35] op_sel_hi:[1,1,0]
	v_pk_mul_f32 v[170:171], v[170:171], 0.5 op_sel_hi:[1,0]
	v_pk_fma_f32 v[190:191], v[182:183], v[190:191], s[36:37] op_sel_hi:[1,1,0]
	v_lshlrev_b32_e32 v168, 16, v123
	v_pk_fma_f32 v[190:191], v[182:183], v[190:191], s[38:39] op_sel_hi:[1,1,0]
	v_and_b32_e32 v169, 0xffff0000, v123
	v_pk_fma_f32 v[190:191], v[182:183], v[190:191], s[40:41] op_sel_hi:[1,1,0]
	v_pk_mul_f32 v[96:97], v[96:97], v[128:129] op_sel_hi:[1,0]
	v_pk_fma_f32 v[190:191], v[182:183], v[190:191], s[42:43] op_sel_hi:[1,1,0]
	v_pk_fma_f32 v[174:175], v[150:151], v[174:175], v[162:163]
	v_pk_fma_f32 v[182:183], v[182:183], v[190:191], s[44:45] op_sel_hi:[1,1,0]
	v_pk_fma_f32 v[168:169], v[154:155], v[168:169], v[174:175]
	v_pk_mul_f32 v[178:179], v[178:179], v[182:183]
	v_mov_b32_dpp v125, v118 row_ror:2 row_mask:0xf bank_mask:0xf bound_ctrl:1
	v_pk_fma_f32 v[170:171], v[170:171], v[178:179], v[170:171]
	v_pk_mul_f32 v[98:99], v[98:99], v[128:129] op_sel_hi:[1,0]
	v_pk_mul_f32 v[96:97], v[96:97], v[170:171]
	v_lshlrev_b32_e32 v170, 16, v113
	v_and_b32_e32 v171, 0xffff0000, v113
	v_pk_fma_f32 v[168:169], v[158:159], v[170:171], v[168:169]
	v_mov_b32_dpp v3, v118 row_ror:1 row_mask:0xf bank_mask:0xf bound_ctrl:1
	v_pk_mul_f32 v[170:171], v[168:169], s[26:27] op_sel_hi:[1,0]
	v_pk_mul_f32 v[168:169], v[168:169], 0.5 op_sel_hi:[1,0]
	v_med3_f32 v170, v170, s71, v224
	v_med3_f32 v171, v171, s71, v224
	v_pk_mul_f32 v[174:175], v[170:171], v[170:171]
	v_mov_b32_dpp v125, v114 row_shr:2 row_mask:0xf bank_mask:0xf
	v_pk_fma_f32 v[178:179], v[174:175], s[28:29], v[116:117] op_sel_hi:[1,0,0] neg_lo:[1,0,0] neg_hi:[1,0,0]
	v_mov_b32_dpp v3, v114 row_shr:1 row_mask:0xf bank_mask:0xf
	v_pk_fma_f32 v[178:179], v[174:175], v[178:179], s[34:35] op_sel_hi:[1,1,0]
	v_cvt_pk_bf16_f32 v96, v96, v97
	v_mov_b32_dpp v127, v119 row_ror:2 row_mask:0xf bank_mask:0xf bound_ctrl:1
	v_pk_fma_f32 v[178:179], v[174:175], v[178:179], s[36:37] op_sel_hi:[1,1,0]
	v_mov_b32_dpp v123, v119 row_ror:1 row_mask:0xf bank_mask:0xf bound_ctrl:1
	v_pk_fma_f32 v[178:179], v[174:175], v[178:179], s[38:39] op_sel_hi:[1,1,0]
	v_mov_b32_dpp v127, v115 row_shr:2 row_mask:0xf bank_mask:0xf
	v_pk_fma_f32 v[178:179], v[174:175], v[178:179], s[40:41] op_sel_hi:[1,1,0]
	v_mov_b32_dpp v123, v115 row_shr:1 row_mask:0xf bank_mask:0xf
	v_pk_fma_f32 v[178:179], v[174:175], v[178:179], s[42:43] op_sel_hi:[1,1,0]
	v_lshlrev_b32_e32 v118, 16, v123
	v_pk_fma_f32 v[174:175], v[174:175], v[178:179], s[44:45] op_sel_hi:[1,1,0]
	v_and_b32_e32 v119, 0xffff0000, v123
	v_pk_mul_f32 v[170:171], v[170:171], v[174:175]
	v_lshlrev_b32_e32 v174, 16, v114
	v_pk_fma_f32 v[168:169], v[168:169], v[170:171], v[168:169]
	v_and_b32_e32 v175, 0xffff0000, v114
	v_pk_mul_f32 v[98:99], v[98:99], v[168:169]
	v_lshlrev_b32_e32 v168, 16, v125
	v_and_b32_e32 v169, 0xffff0000, v125
	v_cvt_pk_bf16_f32 v97, v98, v99
	v_lshlrev_b32_e32 v98, 16, v3
	v_and_b32_e32 v99, 0xffff0000, v3
	v_pk_fma_f32 v[168:169], v[132:133], v[168:169], v[144:145]
	v_lshlrev_b32_e32 v170, 16, v127
	v_pk_fma_f32 v[98:99], v[136:137], v[98:99], v[168:169]
	v_and_b32_e32 v171, 0xffff0000, v127
; __device__ __forceinline__ unsigned cvt_pk_bf16(float lo, float hi) { unsigned r; asm volatile("v_cvt_pk_bf16_f32 %0, %1, %2" : "=v"(r) : "v"(lo), "v"(hi)); return r; }
;     static __device__ __forceinline__ void unpk4(const u32x2 w, float (&o)[4]) { o[0] = bf_lo(w.x); o[1] = bf_hi(w.x); o[2] = bf_lo(w.y); o[3] = bf_hi(w.y); }
;     template <int N> static __device__ __forceinline__ u32x2 dpp_prev(const u32x2 pv, const u32x2 cur) { u32x2 r; r.x = dpp_prev1<N>(pv.x, cur.x); r.y = dpp_prev1<N>(pv.y, cur.y); return r; }
;     static __device__ __forceinline__ u32x2 finish2(const float (&g0)[4], const float (&g1)[4], const float (&g2)[4], const float (&w0)[4], const float (&w1)[4], const float (&w2)[4], const float (&bb)[4],
;                                                     const f32x4 v, float rs) {
;         float h[4];
; #pragma unroll
;         for (int j = 0; j < 4; j += 2) {
;             const f32x2 gc = (f32x2){bb[j] + w0[j] * g2[j] + w1[j] * g1[j] + w2[j] * g0[j], bb[j + 1] + w0[j + 1] * g2[j + 1] + w1[j + 1] * g1[j + 1] + w2[j + 1] * g0[j + 1]};
;             const f32x2 ge = gelu_pk(gc) * ((f32x2){v[j], v[j + 1]} * rs); h[j] = ge.x; h[j + 1] = ge.y; }
;         u32x2 w; w.x = cvt_pk_bf16(h[0], h[1]); w.y = cvt_pk_bf16(h[2], h[3]); return w;
;     }
;     __device__ __forceinline__ void operator()(const f32x4 (&acc)[2][2][4][2], const Unit& u, int wr, int wc, int fr, int fq) const {
;     ...
; #pragma unroll
;                 for (int m = 0; m < 4; ++m) { const u32x4 cur = gq[m]; u32x4 hw;
; #pragma unroll
;                     for (int hv = 0; hv < 2; ++hv) { const u32x2 c2 = half2(cur, hv), p2 = half2(pv, hv);
;                         const u32x2 q1 = dpp_prev<1>(p2, c2), q2 = dpp_prev<2>(p2, c2);
;                         float g0[4], g1[4], g2[4]; unpk4(c2, g0); unpk4(q1, g1); unpk4(q2, g2);
;                         const u32x2 r = finish2(g0, g1, g2, w0[hv], w1[hv], w2[hv], bb[hv], acc[ai][bj][m][hv], rs8[ai][m]);
;                         if (hv == 0) { hw.x = r.x; hw.y = r.y; } else { hw.z = r.x; hw.w = r.y; } }
;                     *(u32x4*)(H + (size_t)(R0 + fr + 16 * m) * 2816 + col8) = hw;
;                     pv = cur; } }
	v_pk_fma_f32 v[98:99], v[140:141], v[174:175], v[98:99]
	v_pk_mul_f32 v[92:93], v[92:93], v[128:129] op_sel_hi:[1,0]
	v_pk_mul_f32 v[168:169], v[98:99], s[26:27] op_sel_hi:[1,0]
	v_pk_mul_f32 v[98:99], v[98:99], 0.5 op_sel_hi:[1,0]
	v_med3_f32 v168, v168, s71, v224
	v_med3_f32 v169, v169, s71, v224
	v_pk_mul_f32 v[174:175], v[168:169], v[168:169]
	v_readlane_b32 s0, v240, 58
	v_pk_fma_f32 v[178:179], v[174:175], s[28:29], v[116:117] op_sel_hi:[1,0,0] neg_lo:[1,0,0] neg_hi:[1,0,0]
	v_readlane_b32 s1, v240, 59
	v_pk_fma_f32 v[178:179], v[174:175], v[178:179], s[34:35] op_sel_hi:[1,1,0]
	v_pk_mul_f32 v[94:95], v[94:95], v[128:129] op_sel_hi:[1,0]
	v_pk_fma_f32 v[178:179], v[174:175], v[178:179], s[36:37] op_sel_hi:[1,1,0]
	v_mov_b32_dpp v3, v112 row_ror:1 row_mask:0xf bank_mask:0xf bound_ctrl:1
	v_pk_fma_f32 v[178:179], v[174:175], v[178:179], s[38:39] op_sel_hi:[1,1,0]
	v_pk_mul_f32 v[88:89], v[88:89], v[126:127] op_sel_hi:[1,0]
	v_pk_fma_f32 v[178:179], v[174:175], v[178:179], s[40:41] op_sel_hi:[1,1,0]
	v_mov_b32_dpp v3, v108 row_shr:1 row_mask:0xf bank_mask:0xf
	v_pk_fma_f32 v[178:179], v[174:175], v[178:179], s[42:43] op_sel_hi:[1,1,0]
	v_pk_mul_f32 v[90:91], v[90:91], v[126:127] op_sel_hi:[1,0]
	v_pk_fma_f32 v[174:175], v[174:175], v[178:179], s[44:45] op_sel_hi:[1,1,0]
	v_pk_mul_f32 v[84:85], v[84:85], v[126:127] op_sel_hi:[1,0]
	v_pk_mul_f32 v[168:169], v[168:169], v[174:175]
	v_pk_mul_f32 v[86:87], v[86:87], v[126:127] op_sel_hi:[1,0]
	v_pk_fma_f32 v[98:99], v[98:99], v[168:169], v[98:99]
	v_pk_fma_f32 v[168:169], v[134:135], v[170:171], v[146:147]
	v_pk_mul_f32 v[92:93], v[92:93], v[98:99]
	v_lshlrev_b32_e32 v98, 16, v115
	v_and_b32_e32 v99, 0xffff0000, v115
	v_pk_fma_f32 v[118:119], v[138:139], v[118:119], v[168:169]
	v_pk_mul_f32 v[80:81], v[80:81], v[124:125] op_sel_hi:[1,0]
	v_pk_fma_f32 v[98:99], v[142:143], v[98:99], v[118:119]
	v_pk_mul_f32 v[82:83], v[82:83], v[124:125] op_sel_hi:[1,0]
	v_pk_mul_f32 v[118:119], v[98:99], s[26:27] op_sel_hi:[1,0]
	v_pk_mul_f32 v[98:99], v[98:99], 0.5 op_sel_hi:[1,0]
	v_med3_f32 v118, v118, s71, v224
	v_med3_f32 v119, v119, s71, v224
	v_pk_mul_f32 v[168:169], v[118:119], v[118:119]
	v_pk_mul_f32 v[76:77], v[76:77], v[124:125] op_sel_hi:[1,0]
	v_pk_fma_f32 v[170:171], v[168:169], s[28:29], v[116:117] op_sel_hi:[1,0,0] neg_lo:[1,0,0] neg_hi:[1,0,0]
	v_pk_mul_f32 v[78:79], v[78:79], v[124:125] op_sel_hi:[1,0]
	v_pk_fma_f32 v[170:171], v[168:169], v[170:171], s[34:35] op_sel_hi:[1,1,0]
	v_pk_mul_f32 v[72:73], v[72:73], v[122:123] op_sel_hi:[1,0]
	v_pk_fma_f32 v[170:171], v[168:169], v[170:171], s[36:37] op_sel_hi:[1,1,0]
	v_pk_mul_f32 v[74:75], v[74:75], v[122:123] op_sel_hi:[1,0]
	v_pk_fma_f32 v[170:171], v[168:169], v[170:171], s[38:39] op_sel_hi:[1,1,0]
	v_pk_mul_f32 v[64:65], v[64:65], v[122:123] op_sel_hi:[1,0]
	v_pk_fma_f32 v[170:171], v[168:169], v[170:171], s[40:41] op_sel_hi:[1,1,0]
	v_pk_mul_f32 v[66:67], v[66:67], v[122:123] op_sel_hi:[1,0]
	v_pk_fma_f32 v[170:171], v[168:169], v[170:171], s[42:43] op_sel_hi:[1,1,0]
	s_nop 0
	v_pk_fma_f32 v[168:169], v[168:169], v[170:171], s[44:45] op_sel_hi:[1,1,0]
	s_nop 0
	v_pk_mul_f32 v[118:119], v[118:119], v[168:169]
	v_lshl_add_u64 v[168:169], s[0:1], 0, v[120:121]
	v_pk_fma_f32 v[98:99], v[98:99], v[118:119], v[98:99]
	v_mov_b32_e32 v120, 0
	v_pk_mul_f32 v[94:95], v[94:95], v[98:99]
	v_cvt_pk_bf16_f32 v98, v92, v93
	v_lshl_add_u64 v[92:93], v[168:169], 0, v[180:181]
	v_cvt_pk_bf16_f32 v99, v94, v95
	global_store_dwordx4 v[92:93], v[96:99], off
	v_lshlrev_b32_e32 v92, 16, v3
	v_and_b32_e32 v93, 0xffff0000, v3
	v_mov_b32_dpp v97, v112 row_ror:2 row_mask:0xf bank_mask:0xf bound_ctrl:1
	v_mov_b32_dpp v95, v113 row_ror:1 row_mask:0xf bank_mask:0xf bound_ctrl:1
	v_mov_b32_dpp v99, v113 row_ror:2 row_mask:0xf bank_mask:0xf bound_ctrl:1
	v_mov_b32_dpp v97, v108 row_shr:2 row_mask:0xf bank_mask:0xf
	v_lshlrev_b32_e32 v96, 16, v97
	v_and_b32_e32 v97, 0xffff0000, v97
	v_pk_fma_f32 v[96:97], v[148:149], v[96:97], v[160:161]
	v_lshlrev_b32_e32 v112, 16, v108
	v_and_b32_e32 v113, 0xffff0000, v108
	v_pk_fma_f32 v[92:93], v[152:153], v[92:93], v[96:97]
	v_mov_b32_dpp v99, v109 row_shr:2 row_mask:0xf bank_mask:0xf
	v_pk_fma_f32 v[92:93], v[156:157], v[112:113], v[92:93]
	v_mov_b32_dpp v95, v109 row_shr:1 row_mask:0xf bank_mask:0xf
	v_pk_mul_f32 v[96:97], v[92:93], s[26:27] op_sel_hi:[1,0]
	v_lshlrev_b32_e32 v98, 16, v99
	v_med3_f32 v96, v96, s71, v224
	v_med3_f32 v97, v97, s71, v224
	v_pk_mul_f32 v[112:113], v[96:97], v[96:97]
	v_and_b32_e32 v99, 0xffff0000, v99
	v_pk_fma_f32 v[118:119], v[112:113], s[28:29], v[116:117] op_sel_hi:[1,0,0] neg_lo:[1,0,0] neg_hi:[1,0,0]
	v_pk_mul_f32 v[92:93], v[92:93], 0.5 op_sel_hi:[1,0]
	v_pk_fma_f32 v[118:119], v[112:113], v[118:119], s[34:35] op_sel_hi:[1,1,0]
	v_lshlrev_b32_e32 v94, 16, v95
	v_pk_fma_f32 v[118:119], v[112:113], v[118:119], s[36:37] op_sel_hi:[1,1,0]
	v_and_b32_e32 v95, 0xffff0000, v95
	v_pk_fma_f32 v[118:119], v[112:113], v[118:119], s[38:39] op_sel_hi:[1,1,0]
	v_mov_b32_dpp v3, v114 row_ror:1 row_mask:0xf bank_mask:0xf bound_ctrl:1
	v_pk_fma_f32 v[118:119], v[112:113], v[118:119], s[40:41] op_sel_hi:[1,1,0]
	v_mov_b32_e32 v121, 0
	v_pk_fma_f32 v[118:119], v[112:113], v[118:119], s[42:43] op_sel_hi:[1,1,0]
	v_mov_b32_dpp v3, v110 row_shr:1 row_mask:0xf bank_mask:0xf
	v_pk_fma_f32 v[112:113], v[112:113], v[118:119], s[44:45] op_sel_hi:[1,1,0]
	v_mov_b32_e32 v118, 0
	v_pk_mul_f32 v[96:97], v[96:97], v[112:113]
	v_mov_b32_e32 v119, 0
	v_pk_fma_f32 v[92:93], v[92:93], v[96:97], v[92:93]
	v_pk_fma_f32 v[96:97], v[150:151], v[98:99], v[162:163]
	v_pk_mul_f32 v[88:89], v[88:89], v[92:93]
	v_lshlrev_b32_e32 v92, 16, v109
; __device__ __forceinline__ unsigned cvt_pk_bf16(float lo, float hi) { unsigned r; asm volatile("v_cvt_pk_bf16_f32 %0, %1, %2" : "=v"(r) : "v"(lo), "v"(hi)); return r; }
;     static __device__ __forceinline__ void unpk4(const u32x2 w, float (&o)[4]) { o[0] = bf_lo(w.x); o[1] = bf_hi(w.x); o[2] = bf_lo(w.y); o[3] = bf_hi(w.y); }
;     template <int N> static __device__ __forceinline__ u32x2 dpp_prev(const u32x2 pv, const u32x2 cur) { u32x2 r; r.x = dpp_prev1<N>(pv.x, cur.x); r.y = dpp_prev1<N>(pv.y, cur.y); return r; }
;     static __device__ __forceinline__ u32x2 finish2(const float (&g0)[4], const float (&g1)[4], const float (&g2)[4], const float (&w0)[4], const float (&w1)[4], const float (&w2)[4], const float (&bb)[4],
;                                                     const f32x4 v, float rs) {
;         float h[4];
; #pragma unroll
;         for (int j = 0; j < 4; j += 2) {
;             const f32x2 gc = (f32x2){bb[j] + w0[j] * g2[j] + w1[j] * g1[j] + w2[j] * g0[j], bb[j + 1] + w0[j + 1] * g2[j + 1] + w1[j + 1] * g1[j + 1] + w2[j + 1] * g0[j + 1]};
;             const f32x2 ge = gelu_pk(gc) * ((f32x2){v[j], v[j + 1]} * rs); h[j] = ge.x; h[j + 1] = ge.y; }
;         u32x2 w; w.x = cvt_pk_bf16(h[0], h[1]); w.y = cvt_pk_bf16(h[2], h[3]); return w;
;     }
;     __device__ __forceinline__ void operator()(const f32x4 (&acc)[2][2][4][2], const Unit& u, int wr, int wc, int fr, int fq) const {
;     ...
; #pragma unroll
;                 for (int m = 0; m < 4; ++m) { const u32x4 cur = gq[m]; u32x4 hw;
; #pragma unroll
;                     for (int hv = 0; hv < 2; ++hv) { const u32x2 c2 = half2(cur, hv), p2 = half2(pv, hv);
;                         const u32x2 q1 = dpp_prev<1>(p2, c2), q2 = dpp_prev<2>(p2, c2);
;                         float g0[4], g1[4], g2[4]; unpk4(c2, g0); unpk4(q1, g1); unpk4(q2, g2);
;                         const u32x2 r = finish2(g0, g1, g2, w0[hv], w1[hv], w2[hv], bb[hv], acc[ai][bj][m][hv], rs8[ai][m]);
;                         if (hv == 0) { hw.x = r.x; hw.y = r.y; } else { hw.z = r.x; hw.w = r.y; } }
;                     *(u32x4*)(H + (size_t)(R0 + fr + 16 * m) * 2816 + col8) = hw;
;                     pv = cur; } }
	v_and_b32_e32 v93, 0xffff0000, v109
	v_pk_fma_f32 v[94:95], v[154:155], v[94:95], v[96:97]
	v_cvt_pk_bf16_f32 v88, v88, v89
	s_nop 0
	v_pk_fma_f32 v[92:93], v[158:159], v[92:93], v[94:95]
	s_nop 0
	v_pk_mul_f32 v[94:95], v[92:93], s[26:27] op_sel_hi:[1,0]
	v_pk_mul_f32 v[92:93], v[92:93], 0.5 op_sel_hi:[1,0]
	v_med3_f32 v94, v94, s71, v224
	v_med3_f32 v95, v95, s71, v224
	v_pk_mul_f32 v[96:97], v[94:95], v[94:95]
	s_nop 0
	v_pk_fma_f32 v[98:99], v[96:97], s[28:29], v[116:117] op_sel_hi:[1,0,0] neg_lo:[1,0,0] neg_hi:[1,0,0]
	s_nop 0
	v_pk_fma_f32 v[98:99], v[96:97], v[98:99], s[34:35] op_sel_hi:[1,1,0]
	s_nop 0
	v_pk_fma_f32 v[98:99], v[96:97], v[98:99], s[36:37] op_sel_hi:[1,1,0]
	s_nop 0
	v_pk_fma_f32 v[98:99], v[96:97], v[98:99], s[38:39] op_sel_hi:[1,1,0]
	s_nop 0
	v_pk_fma_f32 v[98:99], v[96:97], v[98:99], s[40:41] op_sel_hi:[1,1,0]
	s_nop 0
	v_pk_fma_f32 v[98:99], v[96:97], v[98:99], s[42:43] op_sel_hi:[1,1,0]
	s_nop 0
	v_pk_fma_f32 v[96:97], v[96:97], v[98:99], s[44:45] op_sel_hi:[1,1,0]
	v_lshlrev_b32_e32 v98, 16, v110
	v_pk_mul_f32 v[94:95], v[94:95], v[96:97]
	v_and_b32_e32 v99, 0xffff0000, v110
	v_pk_fma_f32 v[92:93], v[92:93], v[94:95], v[92:93]
	v_mov_b32_dpp v95, v114 row_ror:2 row_mask:0xf bank_mask:0xf bound_ctrl:1
	v_pk_mul_f32 v[90:91], v[90:91], v[92:93]
	v_mov_b32_dpp v97, v115 row_ror:2 row_mask:0xf bank_mask:0xf bound_ctrl:1
	v_mov_b32_dpp v95, v110 row_shr:2 row_mask:0xf bank_mask:0xf
	v_lshlrev_b32_e32 v94, 16, v95
	v_and_b32_e32 v95, 0xffff0000, v95
	v_cvt_pk_bf16_f32 v89, v90, v91
	v_lshlrev_b32_e32 v90, 16, v3
	v_and_b32_e32 v91, 0xffff0000, v3
	v_pk_fma_f32 v[94:95], v[132:133], v[94:95], v[144:145]
	v_mov_b32_dpp v93, v115 row_ror:1 row_mask:0xf bank_mask:0xf bound_ctrl:1
	v_pk_fma_f32 v[90:91], v[136:137], v[90:91], v[94:95]
	v_mov_b32_dpp v97, v111 row_shr:2 row_mask:0xf bank_mask:0xf
	v_pk_fma_f32 v[90:91], v[140:141], v[98:99], v[90:91]
	v_mov_b32_dpp v93, v111 row_shr:1 row_mask:0xf bank_mask:0xf
	v_pk_mul_f32 v[94:95], v[90:91], s[26:27] op_sel_hi:[1,0]
	v_lshlrev_b32_e32 v96, 16, v97
	v_med3_f32 v94, v94, s71, v224
	v_med3_f32 v95, v95, s71, v224
	v_pk_mul_f32 v[98:99], v[94:95], v[94:95]
	v_and_b32_e32 v97, 0xffff0000, v97
	v_pk_fma_f32 v[112:113], v[98:99], s[28:29], v[116:117] op_sel_hi:[1,0,0] neg_lo:[1,0,0] neg_hi:[1,0,0]
	v_pk_mul_f32 v[90:91], v[90:91], 0.5 op_sel_hi:[1,0]
	v_pk_fma_f32 v[112:113], v[98:99], v[112:113], s[34:35] op_sel_hi:[1,1,0]
	v_lshlrev_b32_e32 v92, 16, v93
	v_pk_fma_f32 v[112:113], v[98:99], v[112:113], s[36:37] op_sel_hi:[1,1,0]
	v_and_b32_e32 v93, 0xffff0000, v93
	v_pk_fma_f32 v[112:113], v[98:99], v[112:113], s[38:39] op_sel_hi:[1,1,0]
	v_add_u32_e32 v3, 16, v1
	v_pk_fma_f32 v[112:113], v[98:99], v[112:113], s[40:41] op_sel_hi:[1,1,0]
	s_nop 0
	v_pk_fma_f32 v[112:113], v[98:99], v[112:113], s[42:43] op_sel_hi:[1,1,0]
	s_nop 0
	v_pk_fma_f32 v[98:99], v[98:99], v[112:113], s[44:45] op_sel_hi:[1,1,0]
	s_nop 0
	v_pk_mul_f32 v[94:95], v[94:95], v[98:99]
	s_nop 0
	v_pk_fma_f32 v[90:91], v[90:91], v[94:95], v[90:91]
	v_pk_fma_f32 v[94:95], v[134:135], v[96:97], v[146:147]
	v_pk_mul_f32 v[84:85], v[84:85], v[90:91]
	v_lshlrev_b32_e32 v90, 16, v111
	v_and_b32_e32 v91, 0xffff0000, v111
	v_pk_fma_f32 v[92:93], v[138:139], v[92:93], v[94:95]
	s_nop 0
	v_pk_fma_f32 v[90:91], v[142:143], v[90:91], v[92:93]
	s_nop 0
	v_pk_mul_f32 v[92:93], v[90:91], s[26:27] op_sel_hi:[1,0]
	v_pk_mul_f32 v[90:91], v[90:91], 0.5 op_sel_hi:[1,0]
	v_med3_f32 v92, v92, s71, v224
	v_med3_f32 v93, v93, s71, v224
	v_pk_mul_f32 v[94:95], v[92:93], v[92:93]
	s_nop 0
	v_pk_fma_f32 v[96:97], v[94:95], s[28:29], v[116:117] op_sel_hi:[1,0,0] neg_lo:[1,0,0] neg_hi:[1,0,0]
	s_nop 0
	v_pk_fma_f32 v[96:97], v[94:95], v[96:97], s[34:35] op_sel_hi:[1,1,0]
	s_nop 0
	v_pk_fma_f32 v[96:97], v[94:95], v[96:97], s[36:37] op_sel_hi:[1,1,0]
	s_nop 0
	v_pk_fma_f32 v[96:97], v[94:95], v[96:97], s[38:39] op_sel_hi:[1,1,0]
	s_nop 0
	v_pk_fma_f32 v[96:97], v[94:95], v[96:97], s[40:41] op_sel_hi:[1,1,0]
	s_nop 0
	v_pk_fma_f32 v[96:97], v[94:95], v[96:97], s[42:43] op_sel_hi:[1,1,0]
	s_nop 0
	v_pk_fma_f32 v[94:95], v[94:95], v[96:97], s[44:45] op_sel_hi:[1,1,0]
	s_nop 0
	v_pk_mul_f32 v[92:93], v[92:93], v[94:95]
	v_lshlrev_b32_e32 v94, 16, v104
	v_pk_fma_f32 v[90:91], v[90:91], v[92:93], v[90:91]
	v_and_b32_e32 v95, 0xffff0000, v104
	v_pk_mul_f32 v[86:87], v[86:87], v[90:91]
	v_cvt_pk_bf16_f32 v90, v84, v85
	v_mov_b64_e32 v[84:85], s[0:1]
	v_mad_i64_i32 v[170:171], s[0:1], v3, s67, v[84:85]
	v_cvt_pk_bf16_f32 v91, v86, v87
	v_lshl_add_u64 v[86:87], v[170:171], 0, v[180:181]
	global_store_dwordx4 v[86:87], v[88:91], off
	v_mov_b32_dpp v3, v108 row_ror:1 row_mask:0xf bank_mask:0xf bound_ctrl:1
	v_mov_b32_dpp v93, v109 row_ror:2 row_mask:0xf bank_mask:0xf bound_ctrl:1
	v_mov_b32_dpp v91, v108 row_ror:2 row_mask:0xf bank_mask:0xf bound_ctrl:1
	v_mov_b32_dpp v3, v104 row_shr:1 row_mask:0xf bank_mask:0xf
	v_lshlrev_b32_e32 v86, 16, v3
	v_mov_b32_dpp v91, v104 row_shr:2 row_mask:0xf bank_mask:0xf
	v_lshlrev_b32_e32 v90, 16, v91
	v_and_b32_e32 v91, 0xffff0000, v91
	v_and_b32_e32 v87, 0xffff0000, v3
	v_pk_fma_f32 v[90:91], v[148:149], v[90:91], v[160:161]
	v_mov_b32_dpp v89, v109 row_ror:1 row_mask:0xf bank_mask:0xf bound_ctrl:1
	v_pk_fma_f32 v[86:87], v[152:153], v[86:87], v[90:91]
	v_mov_b32_dpp v93, v105 row_shr:2 row_mask:0xf bank_mask:0xf
	v_pk_fma_f32 v[86:87], v[156:157], v[94:95], v[86:87]
	v_mov_b32_dpp v89, v105 row_shr:1 row_mask:0xf bank_mask:0xf
	v_pk_mul_f32 v[90:91], v[86:87], s[26:27] op_sel_hi:[1,0]
	v_lshlrev_b32_e32 v92, 16, v93
	v_med3_f32 v90, v90, s71, v224
	v_med3_f32 v91, v91, s71, v224
	v_pk_mul_f32 v[94:95], v[90:91], v[90:91]
; __device__ __forceinline__ unsigned cvt_pk_bf16(float lo, float hi) { unsigned r; asm volatile("v_cvt_pk_bf16_f32 %0, %1, %2" : "=v"(r) : "v"(lo), "v"(hi)); return r; }
;     static __device__ __forceinline__ void unpk4(const u32x2 w, float (&o)[4]) { o[0] = bf_lo(w.x); o[1] = bf_hi(w.x); o[2] = bf_lo(w.y); o[3] = bf_hi(w.y); }
;     template <int N> static __device__ __forceinline__ u32x2 dpp_prev(const u32x2 pv, const u32x2 cur) { u32x2 r; r.x = dpp_prev1<N>(pv.x, cur.x); r.y = dpp_prev1<N>(pv.y, cur.y); return r; }
;     static __device__ __forceinline__ u32x2 finish2(const float (&g0)[4], const float (&g1)[4], const float (&g2)[4], const float (&w0)[4], const float (&w1)[4], const float (&w2)[4], const float (&bb)[4],
;                                                     const f32x4 v, float rs) {
;         float h[4];
; #pragma unroll
;         for (int j = 0; j < 4; j += 2) {
;             const f32x2 gc = (f32x2){bb[j] + w0[j] * g2[j] + w1[j] * g1[j] + w2[j] * g0[j], bb[j + 1] + w0[j + 1] * g2[j + 1] + w1[j + 1] * g1[j + 1] + w2[j + 1] * g0[j + 1]};
;             const f32x2 ge = gelu_pk(gc) * ((f32x2){v[j], v[j + 1]} * rs); h[j] = ge.x; h[j + 1] = ge.y; }
;         u32x2 w; w.x = cvt_pk_bf16(h[0], h[1]); w.y = cvt_pk_bf16(h[2], h[3]); return w;
;     }
;     __device__ __forceinline__ void operator()(const f32x4 (&acc)[2][2][4][2], const Unit& u, int wr, int wc, int fr, int fq) const {
;     ...
; #pragma unroll
;                 for (int m = 0; m < 4; ++m) { const u32x4 cur = gq[m]; u32x4 hw;
; #pragma unroll
;                     for (int hv = 0; hv < 2; ++hv) { const u32x2 c2 = half2(cur, hv), p2 = half2(pv, hv);
;                         const u32x2 q1 = dpp_prev<1>(p2, c2), q2 = dpp_prev<2>(p2, c2);
;                         float g0[4], g1[4], g2[4]; unpk4(c2, g0); unpk4(q1, g1); unpk4(q2, g2);
;                         const u32x2 r = finish2(g0, g1, g2, w0[hv], w1[hv], w2[hv], bb[hv], acc[ai][bj][m][hv], rs8[ai][m]);
;                         if (hv == 0) { hw.x = r.x; hw.y = r.y; } else { hw.z = r.x; hw.w = r.y; } }
;                     *(u32x4*)(H + (size_t)(R0 + fr + 16 * m) * 2816 + col8) = hw;
;                     pv = cur; } }
	v_and_b32_e32 v93, 0xffff0000, v93
	v_pk_fma_f32 v[96:97], v[94:95], s[28:29], v[116:117] op_sel_hi:[1,0,0] neg_lo:[1,0,0] neg_hi:[1,0,0]
	v_pk_mul_f32 v[86:87], v[86:87], 0.5 op_sel_hi:[1,0]
	v_pk_fma_f32 v[96:97], v[94:95], v[96:97], s[34:35] op_sel_hi:[1,1,0]
	v_lshlrev_b32_e32 v88, 16, v89
	v_pk_fma_f32 v[96:97], v[94:95], v[96:97], s[36:37] op_sel_hi:[1,1,0]
	v_and_b32_e32 v89, 0xffff0000, v89
	v_pk_fma_f32 v[96:97], v[94:95], v[96:97], s[38:39] op_sel_hi:[1,1,0]
	v_mov_b32_dpp v3, v110 row_ror:1 row_mask:0xf bank_mask:0xf bound_ctrl:1
	v_pk_fma_f32 v[96:97], v[94:95], v[96:97], s[40:41] op_sel_hi:[1,1,0]
	s_nop 0
	v_pk_fma_f32 v[96:97], v[94:95], v[96:97], s[42:43] op_sel_hi:[1,1,0]
	v_mov_b32_dpp v3, v106 row_shr:1 row_mask:0xf bank_mask:0xf
	v_pk_fma_f32 v[94:95], v[94:95], v[96:97], s[44:45] op_sel_hi:[1,1,0]
	s_nop 0
	v_pk_mul_f32 v[90:91], v[90:91], v[94:95]
	s_nop 0
	v_pk_fma_f32 v[86:87], v[86:87], v[90:91], v[86:87]
	v_pk_fma_f32 v[90:91], v[150:151], v[92:93], v[162:163]
	v_pk_mul_f32 v[80:81], v[80:81], v[86:87]
	v_lshlrev_b32_e32 v86, 16, v105
	v_and_b32_e32 v87, 0xffff0000, v105
	v_pk_fma_f32 v[88:89], v[154:155], v[88:89], v[90:91]
	v_cvt_pk_bf16_f32 v80, v80, v81
	s_nop 0
	v_pk_fma_f32 v[86:87], v[158:159], v[86:87], v[88:89]
	s_nop 0
	v_pk_mul_f32 v[88:89], v[86:87], s[26:27] op_sel_hi:[1,0]
	v_pk_mul_f32 v[86:87], v[86:87], 0.5 op_sel_hi:[1,0]
	v_med3_f32 v88, v88, s71, v224
	v_med3_f32 v89, v89, s71, v224
	v_pk_mul_f32 v[90:91], v[88:89], v[88:89]
	s_nop 0
	v_pk_fma_f32 v[92:93], v[90:91], s[28:29], v[116:117] op_sel_hi:[1,0,0] neg_lo:[1,0,0] neg_hi:[1,0,0]
	s_nop 0
	v_pk_fma_f32 v[92:93], v[90:91], v[92:93], s[34:35] op_sel_hi:[1,1,0]
	s_nop 0
	v_pk_fma_f32 v[92:93], v[90:91], v[92:93], s[36:37] op_sel_hi:[1,1,0]
	s_nop 0
	v_pk_fma_f32 v[92:93], v[90:91], v[92:93], s[38:39] op_sel_hi:[1,1,0]
	s_nop 0
	v_pk_fma_f32 v[92:93], v[90:91], v[92:93], s[40:41] op_sel_hi:[1,1,0]
	s_nop 0
	v_pk_fma_f32 v[92:93], v[90:91], v[92:93], s[42:43] op_sel_hi:[1,1,0]
	s_nop 0
	v_pk_fma_f32 v[90:91], v[90:91], v[92:93], s[44:45] op_sel_hi:[1,1,0]
	v_lshlrev_b32_e32 v92, 16, v106
	v_pk_mul_f32 v[88:89], v[88:89], v[90:91]
	v_and_b32_e32 v93, 0xffff0000, v106
	v_pk_fma_f32 v[86:87], v[86:87], v[88:89], v[86:87]
	v_mov_b32_dpp v89, v110 row_ror:2 row_mask:0xf bank_mask:0xf bound_ctrl:1
	v_pk_mul_f32 v[82:83], v[82:83], v[86:87]
	v_mov_b32_dpp v91, v111 row_ror:2 row_mask:0xf bank_mask:0xf bound_ctrl:1
	v_mov_b32_dpp v89, v106 row_shr:2 row_mask:0xf bank_mask:0xf
	v_lshlrev_b32_e32 v88, 16, v89
	v_and_b32_e32 v89, 0xffff0000, v89
	v_cvt_pk_bf16_f32 v81, v82, v83
	v_lshlrev_b32_e32 v82, 16, v3
	v_and_b32_e32 v83, 0xffff0000, v3
	v_pk_fma_f32 v[88:89], v[132:133], v[88:89], v[144:145]
	v_mov_b32_dpp v87, v111 row_ror:1 row_mask:0xf bank_mask:0xf bound_ctrl:1
	v_pk_fma_f32 v[82:83], v[136:137], v[82:83], v[88:89]
	v_mov_b32_dpp v91, v107 row_shr:2 row_mask:0xf bank_mask:0xf
	v_pk_fma_f32 v[82:83], v[140:141], v[92:93], v[82:83]
	v_mov_b32_dpp v87, v107 row_shr:1 row_mask:0xf bank_mask:0xf
	v_pk_mul_f32 v[88:89], v[82:83], s[26:27] op_sel_hi:[1,0]
	v_lshlrev_b32_e32 v90, 16, v91
	v_med3_f32 v88, v88, s71, v224
	v_med3_f32 v89, v89, s71, v224
	v_pk_mul_f32 v[92:93], v[88:89], v[88:89]
	v_and_b32_e32 v91, 0xffff0000, v91
	v_pk_fma_f32 v[94:95], v[92:93], s[28:29], v[116:117] op_sel_hi:[1,0,0] neg_lo:[1,0,0] neg_hi:[1,0,0]
	v_pk_mul_f32 v[82:83], v[82:83], 0.5 op_sel_hi:[1,0]
	v_pk_fma_f32 v[94:95], v[92:93], v[94:95], s[34:35] op_sel_hi:[1,1,0]
	v_lshlrev_b32_e32 v86, 16, v87
	v_pk_fma_f32 v[94:95], v[92:93], v[94:95], s[36:37] op_sel_hi:[1,1,0]
	v_and_b32_e32 v87, 0xffff0000, v87
	v_pk_fma_f32 v[94:95], v[92:93], v[94:95], s[38:39] op_sel_hi:[1,1,0]
	v_add_u32_e32 v3, 32, v1
	v_pk_fma_f32 v[94:95], v[92:93], v[94:95], s[40:41] op_sel_hi:[1,1,0]
	v_mad_i64_i32 v[174:175], s[0:1], v3, s67, v[84:85]
	v_pk_fma_f32 v[94:95], v[92:93], v[94:95], s[42:43] op_sel_hi:[1,1,0]
	v_mov_b32_dpp v3, v104 row_ror:1 row_mask:0xf bank_mask:0xf bound_ctrl:1
	v_pk_fma_f32 v[92:93], v[92:93], v[94:95], s[44:45] op_sel_hi:[1,1,0]
	v_add_u32_e32 v1, 48, v1
	v_pk_mul_f32 v[88:89], v[88:89], v[92:93]
	v_mov_b32_dpp v3, v100 row_shr:1 row_mask:0xf bank_mask:0xf
	v_pk_fma_f32 v[82:83], v[82:83], v[88:89], v[82:83]
	v_pk_fma_f32 v[88:89], v[134:135], v[90:91], v[146:147]
	v_pk_mul_f32 v[76:77], v[76:77], v[82:83]
	v_lshlrev_b32_e32 v82, 16, v107
	v_and_b32_e32 v83, 0xffff0000, v107
	v_pk_fma_f32 v[86:87], v[138:139], v[86:87], v[88:89]
	s_nop 0
	v_pk_fma_f32 v[82:83], v[142:143], v[82:83], v[86:87]
	s_nop 0
	v_pk_mul_f32 v[86:87], v[82:83], s[26:27] op_sel_hi:[1,0]
	v_pk_mul_f32 v[82:83], v[82:83], 0.5 op_sel_hi:[1,0]
	v_med3_f32 v86, v86, s71, v224
	v_med3_f32 v87, v87, s71, v224
	v_pk_mul_f32 v[88:89], v[86:87], v[86:87]
	s_nop 0
	v_pk_fma_f32 v[90:91], v[88:89], s[28:29], v[116:117] op_sel_hi:[1,0,0] neg_lo:[1,0,0] neg_hi:[1,0,0]
	s_nop 0
	v_pk_fma_f32 v[90:91], v[88:89], v[90:91], s[34:35] op_sel_hi:[1,1,0]
	s_nop 0
	v_pk_fma_f32 v[90:91], v[88:89], v[90:91], s[36:37] op_sel_hi:[1,1,0]
	s_nop 0
	v_pk_fma_f32 v[90:91], v[88:89], v[90:91], s[38:39] op_sel_hi:[1,1,0]
	s_nop 0
	v_pk_fma_f32 v[90:91], v[88:89], v[90:91], s[40:41] op_sel_hi:[1,1,0]
	s_nop 0
	v_pk_fma_f32 v[90:91], v[88:89], v[90:91], s[42:43] op_sel_hi:[1,1,0]
	s_nop 0
	v_pk_fma_f32 v[88:89], v[88:89], v[90:91], s[44:45] op_sel_hi:[1,1,0]
	s_nop 0
	v_pk_mul_f32 v[86:87], v[86:87], v[88:89]
	s_nop 0
	v_pk_fma_f32 v[82:83], v[82:83], v[86:87], v[82:83]
	v_lshlrev_b32_e32 v86, 16, v100
	v_pk_mul_f32 v[78:79], v[78:79], v[82:83]
	v_cvt_pk_bf16_f32 v82, v76, v77
	v_lshl_add_u64 v[76:77], v[174:175], 0, v[180:181]
; __device__ __forceinline__ unsigned cvt_pk_bf16(float lo, float hi) { unsigned r; asm volatile("v_cvt_pk_bf16_f32 %0, %1, %2" : "=v"(r) : "v"(lo), "v"(hi)); return r; }
;     static __device__ __forceinline__ void unpk4(const u32x2 w, float (&o)[4]) { o[0] = bf_lo(w.x); o[1] = bf_hi(w.x); o[2] = bf_lo(w.y); o[3] = bf_hi(w.y); }
;     template <int N> static __device__ __forceinline__ u32x2 dpp_prev(const u32x2 pv, const u32x2 cur) { u32x2 r; r.x = dpp_prev1<N>(pv.x, cur.x); r.y = dpp_prev1<N>(pv.y, cur.y); return r; }
;     static __device__ __forceinline__ u32x2 finish2(const float (&g0)[4], const float (&g1)[4], const float (&g2)[4], const float (&w0)[4], const float (&w1)[4], const float (&w2)[4], const float (&bb)[4],
;                                                     const f32x4 v, float rs) {
;         float h[4];
; #pragma unroll
;         for (int j = 0; j < 4; j += 2) {
;             const f32x2 gc = (f32x2){bb[j] + w0[j] * g2[j] + w1[j] * g1[j] + w2[j] * g0[j], bb[j + 1] + w0[j + 1] * g2[j + 1] + w1[j + 1] * g1[j + 1] + w2[j + 1] * g0[j + 1]};
;             const f32x2 ge = gelu_pk(gc) * ((f32x2){v[j], v[j + 1]} * rs); h[j] = ge.x; h[j + 1] = ge.y; }
;         u32x2 w; w.x = cvt_pk_bf16(h[0], h[1]); w.y = cvt_pk_bf16(h[2], h[3]); return w;
;     }
;     __device__ __forceinline__ void operator()(const f32x4 (&acc)[2][2][4][2], const Unit& u, int wr, int wc, int fr, int fq) const {
;     ...
;             const int col8 = u.pn * BM + bj * HALF + wc * 32 + 8 * fq;
;     ...
; #pragma unroll
;                 for (int m = 0; m < 4; ++m) { const u32x4 cur = gq[m]; u32x4 hw;
; #pragma unroll
;                     for (int hv = 0; hv < 2; ++hv) { const u32x2 c2 = half2(cur, hv), p2 = half2(pv, hv);
;                         const u32x2 q1 = dpp_prev<1>(p2, c2), q2 = dpp_prev<2>(p2, c2);
;                         float g0[4], g1[4], g2[4]; unpk4(c2, g0); unpk4(q1, g1); unpk4(q2, g2);
;                         const u32x2 r = finish2(g0, g1, g2, w0[hv], w1[hv], w2[hv], bb[hv], acc[ai][bj][m][hv], rs8[ai][m]);
;                         if (hv == 0) { hw.x = r.x; hw.y = r.y; } else { hw.z = r.x; hw.w = r.y; } }
;                     *(u32x4*)(H + (size_t)(R0 + fr + 16 * m) * 2816 + col8) = hw;
;                     pv = cur; } }
	v_cvt_pk_bf16_f32 v83, v78, v79
	global_store_dwordx4 v[76:77], v[80:83], off
	v_lshlrev_b32_e32 v76, 16, v3
	v_and_b32_e32 v77, 0xffff0000, v3
	v_mov_b32_dpp v81, v104 row_ror:2 row_mask:0xf bank_mask:0xf bound_ctrl:1
	v_and_b32_e32 v87, 0xffff0000, v100
	v_mov_b32_dpp v83, v105 row_ror:2 row_mask:0xf bank_mask:0xf bound_ctrl:1
	v_mov_b32_dpp v81, v100 row_shr:2 row_mask:0xf bank_mask:0xf
	v_lshlrev_b32_e32 v80, 16, v81
	v_and_b32_e32 v81, 0xffff0000, v81
	v_pk_fma_f32 v[80:81], v[148:149], v[80:81], v[160:161]
	v_mov_b32_dpp v79, v105 row_ror:1 row_mask:0xf bank_mask:0xf bound_ctrl:1
	v_pk_fma_f32 v[76:77], v[152:153], v[76:77], v[80:81]
	v_mov_b32_dpp v83, v101 row_shr:2 row_mask:0xf bank_mask:0xf
	v_pk_fma_f32 v[76:77], v[156:157], v[86:87], v[76:77]
	v_mov_b32_dpp v79, v101 row_shr:1 row_mask:0xf bank_mask:0xf
	v_pk_mul_f32 v[80:81], v[76:77], s[26:27] op_sel_hi:[1,0]
	v_lshlrev_b32_e32 v82, 16, v83
	v_med3_f32 v80, v80, s71, v224
	v_med3_f32 v81, v81, s71, v224
	v_pk_mul_f32 v[86:87], v[80:81], v[80:81]
	v_and_b32_e32 v83, 0xffff0000, v83
	v_pk_fma_f32 v[88:89], v[86:87], s[28:29], v[116:117] op_sel_hi:[1,0,0] neg_lo:[1,0,0] neg_hi:[1,0,0]
	v_pk_mul_f32 v[76:77], v[76:77], 0.5 op_sel_hi:[1,0]
	v_pk_fma_f32 v[88:89], v[86:87], v[88:89], s[34:35] op_sel_hi:[1,1,0]
	v_lshlrev_b32_e32 v78, 16, v79
	v_pk_fma_f32 v[88:89], v[86:87], v[88:89], s[36:37] op_sel_hi:[1,1,0]
	v_and_b32_e32 v79, 0xffff0000, v79
	v_pk_fma_f32 v[88:89], v[86:87], v[88:89], s[38:39] op_sel_hi:[1,1,0]
	v_mov_b32_dpp v3, v106 row_ror:1 row_mask:0xf bank_mask:0xf bound_ctrl:1
	v_pk_fma_f32 v[88:89], v[86:87], v[88:89], s[40:41] op_sel_hi:[1,1,0]
	s_nop 0
	v_pk_fma_f32 v[88:89], v[86:87], v[88:89], s[42:43] op_sel_hi:[1,1,0]
	v_mov_b32_dpp v3, v102 row_shr:1 row_mask:0xf bank_mask:0xf
	v_pk_fma_f32 v[86:87], v[86:87], v[88:89], s[44:45] op_sel_hi:[1,1,0]
	s_nop 0
	v_pk_mul_f32 v[80:81], v[80:81], v[86:87]
	s_nop 0
	v_pk_fma_f32 v[76:77], v[76:77], v[80:81], v[76:77]
	v_pk_fma_f32 v[80:81], v[150:151], v[82:83], v[162:163]
	v_pk_mul_f32 v[72:73], v[72:73], v[76:77]
	v_lshlrev_b32_e32 v76, 16, v101
	v_and_b32_e32 v77, 0xffff0000, v101
	v_pk_fma_f32 v[78:79], v[154:155], v[78:79], v[80:81]
	v_cvt_pk_bf16_f32 v72, v72, v73
	s_nop 0
	v_pk_fma_f32 v[76:77], v[158:159], v[76:77], v[78:79]
	s_nop 0
	v_pk_mul_f32 v[78:79], v[76:77], s[26:27] op_sel_hi:[1,0]
	v_pk_mul_f32 v[76:77], v[76:77], 0.5 op_sel_hi:[1,0]
	v_med3_f32 v78, v78, s71, v224
	v_med3_f32 v79, v79, s71, v224
	v_pk_mul_f32 v[80:81], v[78:79], v[78:79]
	s_nop 0
	v_pk_fma_f32 v[82:83], v[80:81], s[28:29], v[116:117] op_sel_hi:[1,0,0] neg_lo:[1,0,0] neg_hi:[1,0,0]
	s_nop 0
	v_pk_fma_f32 v[82:83], v[80:81], v[82:83], s[34:35] op_sel_hi:[1,1,0]
	s_nop 0
	v_pk_fma_f32 v[82:83], v[80:81], v[82:83], s[36:37] op_sel_hi:[1,1,0]
	s_nop 0
	v_pk_fma_f32 v[82:83], v[80:81], v[82:83], s[38:39] op_sel_hi:[1,1,0]
	s_nop 0
	v_pk_fma_f32 v[82:83], v[80:81], v[82:83], s[40:41] op_sel_hi:[1,1,0]
	s_nop 0
	v_pk_fma_f32 v[82:83], v[80:81], v[82:83], s[42:43] op_sel_hi:[1,1,0]
	s_nop 0
	v_pk_fma_f32 v[80:81], v[80:81], v[82:83], s[44:45] op_sel_hi:[1,1,0]
	v_lshlrev_b32_e32 v82, 16, v102
	v_pk_mul_f32 v[78:79], v[78:79], v[80:81]
	v_and_b32_e32 v83, 0xffff0000, v102
	v_pk_fma_f32 v[76:77], v[76:77], v[78:79], v[76:77]
	v_mov_b32_dpp v79, v106 row_ror:2 row_mask:0xf bank_mask:0xf bound_ctrl:1
	v_pk_mul_f32 v[74:75], v[74:75], v[76:77]
	v_mov_b32_dpp v81, v107 row_ror:2 row_mask:0xf bank_mask:0xf bound_ctrl:1
	v_mov_b32_dpp v79, v102 row_shr:2 row_mask:0xf bank_mask:0xf
	v_lshlrev_b32_e32 v78, 16, v79
	v_and_b32_e32 v79, 0xffff0000, v79
	v_cvt_pk_bf16_f32 v73, v74, v75
	v_lshlrev_b32_e32 v74, 16, v3
	v_and_b32_e32 v75, 0xffff0000, v3
	v_pk_fma_f32 v[78:79], v[132:133], v[78:79], v[144:145]
	v_mov_b32_dpp v77, v107 row_ror:1 row_mask:0xf bank_mask:0xf bound_ctrl:1
	v_pk_fma_f32 v[74:75], v[136:137], v[74:75], v[78:79]
	v_mov_b32_dpp v81, v103 row_shr:2 row_mask:0xf bank_mask:0xf
	v_pk_fma_f32 v[74:75], v[140:141], v[82:83], v[74:75]
	v_mov_b32_dpp v77, v103 row_shr:1 row_mask:0xf bank_mask:0xf
	v_pk_mul_f32 v[78:79], v[74:75], s[26:27] op_sel_hi:[1,0]
	v_lshlrev_b32_e32 v80, 16, v81
	v_med3_f32 v78, v78, s71, v224
	v_med3_f32 v79, v79, s71, v224
	v_pk_mul_f32 v[82:83], v[78:79], v[78:79]
	v_and_b32_e32 v81, 0xffff0000, v81
	v_pk_fma_f32 v[86:87], v[82:83], s[28:29], v[116:117] op_sel_hi:[1,0,0] neg_lo:[1,0,0] neg_hi:[1,0,0]
	v_pk_mul_f32 v[74:75], v[74:75], 0.5 op_sel_hi:[1,0]
	v_pk_fma_f32 v[86:87], v[82:83], v[86:87], s[34:35] op_sel_hi:[1,1,0]
	v_lshlrev_b32_e32 v76, 16, v77
	v_pk_fma_f32 v[86:87], v[82:83], v[86:87], s[36:37] op_sel_hi:[1,1,0]
	v_and_b32_e32 v77, 0xffff0000, v77
	v_pk_fma_f32 v[86:87], v[82:83], v[86:87], s[38:39] op_sel_hi:[1,1,0]
	v_mad_i64_i32 v[132:133], s[0:1], v1, s67, v[84:85]
	v_pk_fma_f32 v[86:87], v[82:83], v[86:87], s[40:41] op_sel_hi:[1,1,0]
	s_nop 0
	v_pk_fma_f32 v[86:87], v[82:83], v[86:87], s[42:43] op_sel_hi:[1,1,0]
	s_nop 0
	v_pk_fma_f32 v[82:83], v[82:83], v[86:87], s[44:45] op_sel_hi:[1,1,0]
	s_nop 0
	v_pk_mul_f32 v[78:79], v[78:79], v[82:83]
	s_nop 0
	v_pk_fma_f32 v[74:75], v[74:75], v[78:79], v[74:75]
	v_pk_fma_f32 v[78:79], v[134:135], v[80:81], v[146:147]
	v_pk_mul_f32 v[64:65], v[64:65], v[74:75]
	v_lshlrev_b32_e32 v74, 16, v103
	v_and_b32_e32 v75, 0xffff0000, v103
	v_pk_fma_f32 v[76:77], v[138:139], v[76:77], v[78:79]
	v_add_u32_e32 v134, 0x80, v212
	v_pk_fma_f32 v[74:75], v[142:143], v[74:75], v[76:77]
	v_ashrrev_i32_e32 v135, 31, v134
	v_pk_mul_f32 v[76:77], v[74:75], s[26:27] op_sel_hi:[1,0]
	v_pk_mul_f32 v[74:75], v[74:75], 0.5 op_sel_hi:[1,0]
	v_med3_f32 v76, v76, s71, v224
;     static __device__ __forceinline__ void unpk4(const u32x2 w, float (&o)[4]) { o[0] = bf_lo(w.x); o[1] = bf_hi(w.x); o[2] = bf_lo(w.y); o[3] = bf_hi(w.y); }
;     template <int N> static __device__ __forceinline__ u32x2 dpp_prev(const u32x2 pv, const u32x2 cur) { u32x2 r; r.x = dpp_prev1<N>(pv.x, cur.x); r.y = dpp_prev1<N>(pv.y, cur.y); return r; }
;     __device__ __forceinline__ void operator()(const f32x4 (&acc)[2][2][4][2], const Unit& u, int wr, int wc, int fr, int fq) const {
;     ...
;             const int col8 = u.pn * BM + bj * HALF + wc * 32 + 8 * fq;
;             float w0[2][4], w1[2][4], w2[2][4], bb[2][4];
; #pragma unroll
;             for (int hv = 0; hv < 2; ++hv) { ld4f(cw + col8 + 4 * hv, w0[hv]); ld4f(cw + 2816 + col8 + 4 * hv, w1[hv]); ld4f(cw + 2 * 2816 + col8 + 4 * hv, w2[hv]); ld4f(cb + col8 + 4 * hv, bb[hv]); }
; #pragma unroll
;             for (int ai = 0; ai < 2; ++ai) { const int R0 = u.rb + ai * HALF + wr * 64; const bf16_t* gp = G + (size_t)(R0 + fr) * 2816 + col8;
;                 u32x4 gq[4], prv = (u32x4){0u, 0u, 0u, 0u};
; #pragma unroll
;                 for (int m = 0; m < 4; ++m) gq[m] = *(const u32x4*)(gp + (size_t)m * 16 * 2816);
;                 if ((R0 & 8191) != 0) prv = *(const u32x4*)(gp - (size_t)16 * 2816);
;                 u32x4 pv = prv;
; #pragma unroll
;                 for (int m = 0; m < 4; ++m) { const u32x4 cur = gq[m]; u32x4 hw;
; #pragma unroll
;                     for (int hv = 0; hv < 2; ++hv) { const u32x2 c2 = half2(cur, hv), p2 = half2(pv, hv);
;                         const u32x2 q1 = dpp_prev<1>(p2, c2), q2 = dpp_prev<2>(p2, c2);
;                         float g0[4], g1[4], g2[4]; unpk4(c2, g0); unpk4(q1, g1); unpk4(q2, g2);
;                         const u32x2 r = finish2(g0, g1, g2, w0[hv], w1[hv], w2[hv], bb[hv], acc[ai][bj][m][hv], rs8[ai][m]);
;                         if (hv == 0) { hw.x = r.x; hw.y = r.y; } else { hw.z = r.x; hw.w = r.y; } }
;                     *(u32x4*)(H + (size_t)(R0 + fr + 16 * m) * 2816 + col8) = hw;
;                     pv = cur; } }
	v_med3_f32 v77, v77, s71, v224
	v_pk_mul_f32 v[78:79], v[76:77], v[76:77]
	v_lshl_add_u64 v[136:137], v[134:135], 1, v[214:215]
	v_pk_fma_f32 v[80:81], v[78:79], s[28:29], v[116:117] op_sel_hi:[1,0,0] neg_lo:[1,0,0] neg_hi:[1,0,0]
	v_add_co_u32_e32 v100, vcc, s45, v136
	v_pk_fma_f32 v[80:81], v[78:79], v[80:81], s[34:35] op_sel_hi:[1,1,0]
	s_nop 0
	v_addc_co_u32_e32 v101, vcc, 0, v137, vcc
	v_pk_fma_f32 v[80:81], v[78:79], v[80:81], s[36:37] op_sel_hi:[1,1,0]
	v_add_co_u32_e32 v102, vcc, 0x2c000, v136
	v_pk_fma_f32 v[80:81], v[78:79], v[80:81], s[38:39] op_sel_hi:[1,1,0]
	s_nop 0
	v_addc_co_u32_e32 v103, vcc, 0, v137, vcc
	v_pk_fma_f32 v[80:81], v[78:79], v[80:81], s[40:41] op_sel_hi:[1,1,0]
	s_nop 0
	v_pk_fma_f32 v[80:81], v[78:79], v[80:81], s[42:43] op_sel_hi:[1,1,0]
	s_nop 0
	v_pk_fma_f32 v[78:79], v[78:79], v[80:81], s[44:45] op_sel_hi:[1,1,0]
	s_nop 0
	v_pk_mul_f32 v[76:77], v[76:77], v[78:79]
	s_nop 0
	v_pk_fma_f32 v[74:75], v[74:75], v[76:77], v[74:75]
	s_nop 0
	v_pk_mul_f32 v[66:67], v[66:67], v[74:75]
	v_cvt_pk_bf16_f32 v74, v64, v65
	v_lshl_add_u64 v[64:65], v[132:133], 0, v[180:181]
	v_cvt_pk_bf16_f32 v75, v66, v67
	global_store_dwordx4 v[64:65], v[72:75], off
	v_lshlrev_b64 v[64:65], 2, v[134:135]
	v_lshl_add_u64 v[76:77], s[18:19], 0, v[64:65]
	v_lshl_add_u64 v[72:73], s[12:13], 0, v[64:65]
	v_lshl_add_u64 v[80:81], s[20:21], 0, v[64:65]
	v_lshl_add_u64 v[96:97], s[14:15], 0, v[64:65]
	global_load_dwordx4 v[64:67], v[72:73], off offset:16
	global_load_dwordx4 v[84:87], v[72:73], off
	s_nop 0
	global_load_dwordx4 v[72:75], v[76:77], off offset:16
	global_load_dwordx4 v[88:91], v[76:77], off
	s_nop 0
	global_load_dwordx4 v[76:79], v[80:81], off offset:16
	global_load_dwordx4 v[92:95], v[80:81], off
	s_nop 0
	global_load_dwordx4 v[80:83], v[96:97], off offset:16
	s_nop 0
	global_load_dwordx4 v[96:99], v[96:97], off
	s_nop 0
	global_load_dwordx4 v[114:117], v[136:137], off nt
	global_load_dwordx4 v[110:113], v[100:101], off nt
	global_load_dwordx4 v[106:109], v[102:103], off nt
	v_add_co_u32_e32 v100, vcc, 0x42000, v136
	s_nop 1
	v_addc_co_u32_e32 v101, vcc, 0, v137, vcc
	global_load_dwordx4 v[102:105], v[100:101], off nt
	v_mov_b32_e32 v100, 0
	s_andn2_b64 vcc, exec, s[2:3]
	s_cbranch_vccnz .LBB0_3150
	v_add_co_u32_e32 v118, vcc, 0xfffea000, v136
	s_nop 1
	v_addc_co_u32_e32 v119, vcc, -1, v137, vcc
	global_load_dwordx4 v[118:121], v[118:119], off nt
.LBB0_3150:
	s_waitcnt vmcnt(0)
	s_nop 0
	v_mov_b32_dpp v123, v118 row_ror:2 row_mask:0xf bank_mask:0xf bound_ctrl:1
	v_mov_b32_dpp v1, v118 row_ror:1 row_mask:0xf bank_mask:0xf bound_ctrl:1
	v_mov_b32_dpp v101, v119 row_ror:1 row_mask:0xf bank_mask:0xf bound_ctrl:1
	v_mov_b32_dpp v123, v114 row_shr:2 row_mask:0xf bank_mask:0xf
	v_mov_b32_dpp v1, v114 row_shr:1 row_mask:0xf bank_mask:0xf
	v_lshlrev_b32_e32 v138, 16, v123
	v_and_b32_e32 v139, 0xffff0000, v123
	v_mov_b32_dpp v125, v119 row_ror:2 row_mask:0xf bank_mask:0xf bound_ctrl:1
	v_lshlrev_b32_e32 v118, 16, v1
	v_and_b32_e32 v119, 0xffff0000, v1
	v_pk_fma_f32 v[138:139], v[84:85], v[138:139], v[96:97]
	v_lshlrev_b32_e32 v142, 16, v114
	v_and_b32_e32 v143, 0xffff0000, v114
	v_pk_fma_f32 v[118:119], v[88:89], v[118:119], v[138:139]
	v_mov_b32_dpp v125, v115 row_shr:2 row_mask:0xf bank_mask:0xf
	v_pk_fma_f32 v[138:139], v[92:93], v[142:143], v[118:119]
	v_mov_b32_e32 v189, v188
	v_pk_mul_f32 v[118:119], v[138:139], s[26:27] op_sel_hi:[1,0]
	v_mov_b32_dpp v101, v115 row_shr:1 row_mask:0xf bank_mask:0xf
	v_med3_f32 v142, v118, s71, v224
	v_med3_f32 v143, v119, s71, v224
	v_pk_mul_f32 v[144:145], v[142:143], v[142:143]
	v_mov_b64_e32 v[118:119], s[30:31]
	v_pk_fma_f32 v[146:147], v[144:145], s[28:29], v[118:119] op_sel_hi:[1,0,0] neg_lo:[1,0,0] neg_hi:[1,0,0]
	v_lshlrev_b32_e32 v140, 16, v125
	v_pk_fma_f32 v[146:147], v[144:145], v[146:147], s[34:35] op_sel_hi:[1,1,0]
	v_and_b32_e32 v141, 0xffff0000, v125
	v_pk_fma_f32 v[146:147], v[144:145], v[146:147], s[36:37] op_sel_hi:[1,1,0]
	v_pk_mul_f32 v[138:139], v[138:139], 0.5 op_sel_hi:[1,0]
	v_pk_fma_f32 v[146:147], v[144:145], v[146:147], s[38:39] op_sel_hi:[1,1,0]
	v_lshlrev_b32_e32 v136, 16, v101
	v_pk_fma_f32 v[146:147], v[144:145], v[146:147], s[40:41] op_sel_hi:[1,1,0]
	v_and_b32_e32 v137, 0xffff0000, v101
	v_pk_fma_f32 v[146:147], v[144:145], v[146:147], s[42:43] op_sel_hi:[1,1,0]
	v_pk_mul_f32 v[68:69], v[68:69], v[188:189]
	v_pk_fma_f32 v[144:145], v[144:145], v[146:147], s[44:45] op_sel_hi:[1,1,0]
	v_pk_fma_f32 v[140:141], v[86:87], v[140:141], v[98:99]
	v_pk_mul_f32 v[142:143], v[142:143], v[144:145]
	v_pk_fma_f32 v[136:137], v[90:91], v[136:137], v[140:141]
	v_pk_fma_f32 v[138:139], v[138:139], v[142:143], v[138:139]
	v_mov_b32_dpp v123, v120 row_ror:2 row_mask:0xf bank_mask:0xf bound_ctrl:1
	v_pk_mul_f32 v[68:69], v[68:69], v[138:139]
	v_lshlrev_b32_e32 v138, 16, v115
	v_and_b32_e32 v139, 0xffff0000, v115
	v_pk_fma_f32 v[136:137], v[94:95], v[138:139], v[136:137]
	v_pk_mul_f32 v[70:71], v[70:71], v[188:189]
	v_pk_mul_f32 v[138:139], v[136:137], s[26:27] op_sel_hi:[1,0]
	v_pk_mul_f32 v[136:137], v[136:137], 0.5 op_sel_hi:[1,0]
	v_med3_f32 v138, v138, s71, v224
	v_med3_f32 v139, v139, s71, v224
	v_pk_mul_f32 v[140:141], v[138:139], v[138:139]
	v_mov_b32_dpp v1, v120 row_ror:1 row_mask:0xf bank_mask:0xf bound_ctrl:1
	v_pk_fma_f32 v[142:143], v[140:141], s[28:29], v[118:119] op_sel_hi:[1,0,0] neg_lo:[1,0,0] neg_hi:[1,0,0]
	v_mov_b32_dpp v123, v116 row_shr:2 row_mask:0xf bank_mask:0xf
	v_pk_fma_f32 v[142:143], v[140:141], v[142:143], s[34:35] op_sel_hi:[1,1,0]
	v_mov_b32_dpp v1, v116 row_shr:1 row_mask:0xf bank_mask:0xf
	v_pk_fma_f32 v[142:143], v[140:141], v[142:143], s[36:37] op_sel_hi:[1,1,0]
; __device__ __forceinline__ unsigned cvt_pk_bf16(float lo, float hi) { unsigned r; asm volatile("v_cvt_pk_bf16_f32 %0, %1, %2" : "=v"(r) : "v"(lo), "v"(hi)); return r; }
;     static __device__ __forceinline__ void unpk4(const u32x2 w, float (&o)[4]) { o[0] = bf_lo(w.x); o[1] = bf_hi(w.x); o[2] = bf_lo(w.y); o[3] = bf_hi(w.y); }
;     template <int N> static __device__ __forceinline__ u32x2 dpp_prev(const u32x2 pv, const u32x2 cur) { u32x2 r; r.x = dpp_prev1<N>(pv.x, cur.x); r.y = dpp_prev1<N>(pv.y, cur.y); return r; }
;     static __device__ __forceinline__ u32x2 finish2(const float (&g0)[4], const float (&g1)[4], const float (&g2)[4], const float (&w0)[4], const float (&w1)[4], const float (&w2)[4], const float (&bb)[4],
;                                                     const f32x4 v, float rs) {
;         float h[4];
; #pragma unroll
;         for (int j = 0; j < 4; j += 2) {
;             const f32x2 gc = (f32x2){bb[j] + w0[j] * g2[j] + w1[j] * g1[j] + w2[j] * g0[j], bb[j + 1] + w0[j + 1] * g2[j + 1] + w1[j + 1] * g1[j + 1] + w2[j + 1] * g0[j + 1]};
;             const f32x2 ge = gelu_pk(gc) * ((f32x2){v[j], v[j + 1]} * rs); h[j] = ge.x; h[j + 1] = ge.y; }
;         u32x2 w; w.x = cvt_pk_bf16(h[0], h[1]); w.y = cvt_pk_bf16(h[2], h[3]); return w;
;     }
;     __device__ __forceinline__ void operator()(const f32x4 (&acc)[2][2][4][2], const Unit& u, int wr, int wc, int fr, int fq) const {
;     ...
; #pragma unroll
;                 for (int m = 0; m < 4; ++m) { const u32x4 cur = gq[m]; u32x4 hw;
; #pragma unroll
;                     for (int hv = 0; hv < 2; ++hv) { const u32x2 c2 = half2(cur, hv), p2 = half2(pv, hv);
;                         const u32x2 q1 = dpp_prev<1>(p2, c2), q2 = dpp_prev<2>(p2, c2);
;                         float g0[4], g1[4], g2[4]; unpk4(c2, g0); unpk4(q1, g1); unpk4(q2, g2);
;                         const u32x2 r = finish2(g0, g1, g2, w0[hv], w1[hv], w2[hv], bb[hv], acc[ai][bj][m][hv], rs8[ai][m]);
;                         if (hv == 0) { hw.x = r.x; hw.y = r.y; } else { hw.z = r.x; hw.w = r.y; } }
;                     *(u32x4*)(H + (size_t)(R0 + fr + 16 * m) * 2816 + col8) = hw;
;                     pv = cur; } }
	v_cvt_pk_bf16_f32 v68, v68, v69
	v_mov_b32_dpp v125, v121 row_ror:2 row_mask:0xf bank_mask:0xf bound_ctrl:1
	v_pk_fma_f32 v[142:143], v[140:141], v[142:143], s[38:39] op_sel_hi:[1,1,0]
	v_mov_b32_dpp v101, v121 row_ror:1 row_mask:0xf bank_mask:0xf bound_ctrl:1
	v_pk_fma_f32 v[142:143], v[140:141], v[142:143], s[40:41] op_sel_hi:[1,1,0]
	v_mov_b32_dpp v125, v117 row_shr:2 row_mask:0xf bank_mask:0xf
	v_pk_fma_f32 v[142:143], v[140:141], v[142:143], s[42:43] op_sel_hi:[1,1,0]
	v_mov_b32_dpp v101, v117 row_shr:1 row_mask:0xf bank_mask:0xf
	v_pk_fma_f32 v[140:141], v[140:141], v[142:143], s[44:45] op_sel_hi:[1,1,0]
	v_lshlrev_b32_e32 v120, 16, v101
	v_pk_mul_f32 v[138:139], v[138:139], v[140:141]
	v_lshlrev_b32_e32 v140, 16, v116
	v_pk_fma_f32 v[136:137], v[136:137], v[138:139], v[136:137]
	v_and_b32_e32 v141, 0xffff0000, v116
	v_pk_mul_f32 v[70:71], v[70:71], v[136:137]
	v_lshlrev_b32_e32 v136, 16, v123
	v_and_b32_e32 v137, 0xffff0000, v123
	v_cvt_pk_bf16_f32 v69, v70, v71
	v_lshlrev_b32_e32 v70, 16, v1
	v_and_b32_e32 v71, 0xffff0000, v1
	v_pk_fma_f32 v[136:137], v[64:65], v[136:137], v[80:81]
	v_lshlrev_b32_e32 v138, 16, v125
	v_pk_fma_f32 v[70:71], v[72:73], v[70:71], v[136:137]
	v_and_b32_e32 v139, 0xffff0000, v125
	v_pk_fma_f32 v[70:71], v[76:77], v[140:141], v[70:71]
	v_and_b32_e32 v121, 0xffff0000, v101
	v_pk_mul_f32 v[136:137], v[70:71], s[26:27] op_sel_hi:[1,0]
	v_pk_mul_f32 v[70:71], v[70:71], 0.5 op_sel_hi:[1,0]
	v_med3_f32 v136, v136, s71, v224
	v_med3_f32 v137, v137, s71, v224
	v_pk_mul_f32 v[140:141], v[136:137], v[136:137]
	v_pk_mul_f32 v[60:61], v[60:61], v[188:189]
	v_pk_fma_f32 v[142:143], v[140:141], s[28:29], v[118:119] op_sel_hi:[1,0,0] neg_lo:[1,0,0] neg_hi:[1,0,0]
	v_pk_mul_f32 v[62:63], v[62:63], v[188:189]
	v_pk_fma_f32 v[142:143], v[140:141], v[142:143], s[34:35] op_sel_hi:[1,1,0]
	v_mov_b32_dpp v1, v114 row_ror:1 row_mask:0xf bank_mask:0xf bound_ctrl:1
	v_pk_fma_f32 v[142:143], v[140:141], v[142:143], s[36:37] op_sel_hi:[1,1,0]
	v_mov_b32_dpp v101, v115 row_ror:2 row_mask:0xf bank_mask:0xf bound_ctrl:1
	v_pk_fma_f32 v[142:143], v[140:141], v[142:143], s[38:39] op_sel_hi:[1,1,0]
	v_mov_b32_dpp v1, v110 row_shr:1 row_mask:0xf bank_mask:0xf
	v_pk_fma_f32 v[142:143], v[140:141], v[142:143], s[40:41] op_sel_hi:[1,1,0]
	v_mov_b32_dpp v101, v111 row_shr:2 row_mask:0xf bank_mask:0xf
	v_pk_fma_f32 v[142:143], v[140:141], v[142:143], s[42:43] op_sel_hi:[1,1,0]
	v_mov_b32_e32 v187, v186
	v_pk_fma_f32 v[140:141], v[140:141], v[142:143], s[44:45] op_sel_hi:[1,1,0]
	v_pk_mul_f32 v[56:57], v[56:57], v[186:187]
	v_pk_mul_f32 v[136:137], v[136:137], v[140:141]
	v_pk_mul_f32 v[58:59], v[58:59], v[186:187]
	v_pk_fma_f32 v[70:71], v[70:71], v[136:137], v[70:71]
	v_pk_fma_f32 v[136:137], v[66:67], v[138:139], v[82:83]
	v_pk_mul_f32 v[60:61], v[60:61], v[70:71]
	v_lshlrev_b32_e32 v70, 16, v117
	v_and_b32_e32 v71, 0xffff0000, v117
	v_pk_fma_f32 v[120:121], v[74:75], v[120:121], v[136:137]
	v_pk_mul_f32 v[52:53], v[52:53], v[186:187]
	v_pk_fma_f32 v[70:71], v[78:79], v[70:71], v[120:121]
	v_pk_mul_f32 v[54:55], v[54:55], v[186:187]
	v_pk_mul_f32 v[120:121], v[70:71], s[26:27] op_sel_hi:[1,0]
	v_pk_mul_f32 v[70:71], v[70:71], 0.5 op_sel_hi:[1,0]
	v_med3_f32 v120, v120, s71, v224
	v_med3_f32 v121, v121, s71, v224
	v_pk_mul_f32 v[136:137], v[120:121], v[120:121]
	v_mov_b32_e32 v185, v184
	v_pk_fma_f32 v[138:139], v[136:137], s[28:29], v[118:119] op_sel_hi:[1,0,0] neg_lo:[1,0,0] neg_hi:[1,0,0]
	v_pk_mul_f32 v[48:49], v[48:49], v[184:185]
	v_pk_fma_f32 v[138:139], v[136:137], v[138:139], s[34:35] op_sel_hi:[1,1,0]
	v_pk_mul_f32 v[50:51], v[50:51], v[184:185]
	v_pk_fma_f32 v[138:139], v[136:137], v[138:139], s[36:37] op_sel_hi:[1,1,0]
	v_pk_mul_f32 v[44:45], v[44:45], v[184:185]
	v_pk_fma_f32 v[138:139], v[136:137], v[138:139], s[38:39] op_sel_hi:[1,1,0]
	v_pk_mul_f32 v[46:47], v[46:47], v[184:185]
	v_pk_fma_f32 v[138:139], v[136:137], v[138:139], s[40:41] op_sel_hi:[1,1,0]
	v_mov_b32_e32 v3, v2
	v_pk_fma_f32 v[138:139], v[136:137], v[138:139], s[42:43] op_sel_hi:[1,1,0]
	v_pk_mul_f32 v[40:41], v[40:41], v[2:3]
	v_pk_fma_f32 v[136:137], v[136:137], v[138:139], s[44:45] op_sel_hi:[1,1,0]
	v_pk_mul_f32 v[42:43], v[42:43], v[2:3]
	v_pk_mul_f32 v[120:121], v[120:121], v[136:137]
	v_pk_mul_f32 v[36:37], v[36:37], v[2:3]
	v_pk_fma_f32 v[70:71], v[70:71], v[120:121], v[70:71]
	v_lshlrev_b32_e32 v120, 16, v110
	v_pk_mul_f32 v[62:63], v[62:63], v[70:71]
	v_cvt_pk_bf16_f32 v70, v60, v61
	v_lshlrev_b64 v[60:61], 1, v[134:135]
	v_cvt_pk_bf16_f32 v71, v62, v63
	v_lshl_add_u64 v[62:63], v[130:131], 0, v[60:61]
	global_store_dwordx4 v[62:63], v[68:71], off
	v_lshlrev_b32_e32 v62, 16, v1
	v_and_b32_e32 v63, 0xffff0000, v1
	v_mov_b32_dpp v71, v114 row_ror:2 row_mask:0xf bank_mask:0xf bound_ctrl:1
	v_and_b32_e32 v121, 0xffff0000, v110
	v_mov_b32_dpp v69, v115 row_ror:1 row_mask:0xf bank_mask:0xf bound_ctrl:1
	v_mov_b32_dpp v71, v110 row_shr:2 row_mask:0xf bank_mask:0xf
	v_lshlrev_b32_e32 v70, 16, v71
	v_and_b32_e32 v71, 0xffff0000, v71
	v_pk_fma_f32 v[70:71], v[84:85], v[70:71], v[96:97]
	v_mov_b32_dpp v69, v111 row_shr:1 row_mask:0xf bank_mask:0xf
	v_pk_fma_f32 v[62:63], v[88:89], v[62:63], v[70:71]
	v_lshlrev_b32_e32 v114, 16, v101
	v_pk_fma_f32 v[62:63], v[92:93], v[120:121], v[62:63]
	v_and_b32_e32 v115, 0xffff0000, v101
	v_pk_mul_f32 v[70:71], v[62:63], s[26:27] op_sel_hi:[1,0]
	v_pk_mul_f32 v[62:63], v[62:63], 0.5 op_sel_hi:[1,0]
	v_med3_f32 v70, v70, s71, v224
	v_med3_f32 v71, v71, s71, v224
	v_pk_mul_f32 v[120:121], v[70:71], v[70:71]
	v_lshlrev_b32_e32 v68, 16, v69
	v_pk_fma_f32 v[130:131], v[120:121], s[28:29], v[118:119] op_sel_hi:[1,0,0] neg_lo:[1,0,0] neg_hi:[1,0,0]
; __device__ __forceinline__ unsigned cvt_pk_bf16(float lo, float hi) { unsigned r; asm volatile("v_cvt_pk_bf16_f32 %0, %1, %2" : "=v"(r) : "v"(lo), "v"(hi)); return r; }
;     static __device__ __forceinline__ void unpk4(const u32x2 w, float (&o)[4]) { o[0] = bf_lo(w.x); o[1] = bf_hi(w.x); o[2] = bf_lo(w.y); o[3] = bf_hi(w.y); }
;     template <int N> static __device__ __forceinline__ u32x2 dpp_prev(const u32x2 pv, const u32x2 cur) { u32x2 r; r.x = dpp_prev1<N>(pv.x, cur.x); r.y = dpp_prev1<N>(pv.y, cur.y); return r; }
;     static __device__ __forceinline__ u32x2 finish2(const float (&g0)[4], const float (&g1)[4], const float (&g2)[4], const float (&w0)[4], const float (&w1)[4], const float (&w2)[4], const float (&bb)[4],
;                                                     const f32x4 v, float rs) {
;         float h[4];
; #pragma unroll
;         for (int j = 0; j < 4; j += 2) {
;             const f32x2 gc = (f32x2){bb[j] + w0[j] * g2[j] + w1[j] * g1[j] + w2[j] * g0[j], bb[j + 1] + w0[j + 1] * g2[j + 1] + w1[j + 1] * g1[j + 1] + w2[j + 1] * g0[j + 1]};
;             const f32x2 ge = gelu_pk(gc) * ((f32x2){v[j], v[j + 1]} * rs); h[j] = ge.x; h[j + 1] = ge.y; }
;         u32x2 w; w.x = cvt_pk_bf16(h[0], h[1]); w.y = cvt_pk_bf16(h[2], h[3]); return w;
;     }
;     __device__ __forceinline__ void operator()(const f32x4 (&acc)[2][2][4][2], const Unit& u, int wr, int wc, int fr, int fq) const {
;     ...
; #pragma unroll
;                 for (int m = 0; m < 4; ++m) { const u32x4 cur = gq[m]; u32x4 hw;
; #pragma unroll
;                     for (int hv = 0; hv < 2; ++hv) { const u32x2 c2 = half2(cur, hv), p2 = half2(pv, hv);
;                         const u32x2 q1 = dpp_prev<1>(p2, c2), q2 = dpp_prev<2>(p2, c2);
;                         float g0[4], g1[4], g2[4]; unpk4(c2, g0); unpk4(q1, g1); unpk4(q2, g2);
;                         const u32x2 r = finish2(g0, g1, g2, w0[hv], w1[hv], w2[hv], bb[hv], acc[ai][bj][m][hv], rs8[ai][m]);
;                         if (hv == 0) { hw.x = r.x; hw.y = r.y; } else { hw.z = r.x; hw.w = r.y; } }
;                     *(u32x4*)(H + (size_t)(R0 + fr + 16 * m) * 2816 + col8) = hw;
;                     pv = cur; } }
	v_and_b32_e32 v69, 0xffff0000, v69
	v_pk_fma_f32 v[130:131], v[120:121], v[130:131], s[34:35] op_sel_hi:[1,1,0]
	v_mov_b32_dpp v1, v116 row_ror:1 row_mask:0xf bank_mask:0xf bound_ctrl:1
	v_pk_fma_f32 v[130:131], v[120:121], v[130:131], s[36:37] op_sel_hi:[1,1,0]
	v_pk_mul_f32 v[2:3], v[38:39], v[2:3]
	v_pk_fma_f32 v[130:131], v[120:121], v[130:131], s[38:39] op_sel_hi:[1,1,0]
	v_mov_b32_dpp v1, v112 row_shr:1 row_mask:0xf bank_mask:0xf
	v_pk_fma_f32 v[130:131], v[120:121], v[130:131], s[40:41] op_sel_hi:[1,1,0]
	v_mov_b32_e32 v101, 0
	v_pk_fma_f32 v[130:131], v[120:121], v[130:131], s[42:43] op_sel_hi:[1,1,0]
	s_nop 0
	v_pk_fma_f32 v[120:121], v[120:121], v[130:131], s[44:45] op_sel_hi:[1,1,0]
	s_nop 0
	v_pk_mul_f32 v[70:71], v[70:71], v[120:121]
	s_nop 0
	v_pk_fma_f32 v[62:63], v[62:63], v[70:71], v[62:63]
	v_pk_fma_f32 v[70:71], v[86:87], v[114:115], v[98:99]
	v_pk_mul_f32 v[56:57], v[56:57], v[62:63]
	v_lshlrev_b32_e32 v62, 16, v111
	v_and_b32_e32 v63, 0xffff0000, v111
	v_pk_fma_f32 v[68:69], v[90:91], v[68:69], v[70:71]
	v_cvt_pk_bf16_f32 v56, v56, v57
	s_nop 0
	v_pk_fma_f32 v[62:63], v[94:95], v[62:63], v[68:69]
	s_nop 0
	v_pk_mul_f32 v[68:69], v[62:63], s[26:27] op_sel_hi:[1,0]
	v_pk_mul_f32 v[62:63], v[62:63], 0.5 op_sel_hi:[1,0]
	v_med3_f32 v68, v68, s71, v224
	v_med3_f32 v69, v69, s71, v224
	v_pk_mul_f32 v[70:71], v[68:69], v[68:69]
	s_nop 0
	v_pk_fma_f32 v[114:115], v[70:71], s[28:29], v[118:119] op_sel_hi:[1,0,0] neg_lo:[1,0,0] neg_hi:[1,0,0]
	s_nop 0
	v_pk_fma_f32 v[114:115], v[70:71], v[114:115], s[34:35] op_sel_hi:[1,1,0]
	s_nop 0
	v_pk_fma_f32 v[114:115], v[70:71], v[114:115], s[36:37] op_sel_hi:[1,1,0]
	s_nop 0
	v_pk_fma_f32 v[114:115], v[70:71], v[114:115], s[38:39] op_sel_hi:[1,1,0]
	s_nop 0
	v_pk_fma_f32 v[114:115], v[70:71], v[114:115], s[40:41] op_sel_hi:[1,1,0]
	s_nop 0
	v_pk_fma_f32 v[114:115], v[70:71], v[114:115], s[42:43] op_sel_hi:[1,1,0]
	s_nop 0
	v_pk_fma_f32 v[70:71], v[70:71], v[114:115], s[44:45] op_sel_hi:[1,1,0]
	v_lshlrev_b32_e32 v114, 16, v112
	v_pk_mul_f32 v[68:69], v[68:69], v[70:71]
	v_and_b32_e32 v115, 0xffff0000, v112
	v_pk_fma_f32 v[62:63], v[62:63], v[68:69], v[62:63]
	v_mov_b32_dpp v69, v116 row_ror:2 row_mask:0xf bank_mask:0xf bound_ctrl:1
	v_pk_mul_f32 v[58:59], v[58:59], v[62:63]
	v_mov_b32_dpp v63, v117 row_ror:1 row_mask:0xf bank_mask:0xf bound_ctrl:1
	v_mov_b32_dpp v69, v112 row_shr:2 row_mask:0xf bank_mask:0xf
	v_lshlrev_b32_e32 v68, 16, v69
	v_and_b32_e32 v69, 0xffff0000, v69
	v_cvt_pk_bf16_f32 v57, v58, v59
	v_lshlrev_b32_e32 v58, 16, v1
	v_and_b32_e32 v59, 0xffff0000, v1
	v_pk_fma_f32 v[68:69], v[64:65], v[68:69], v[80:81]
	v_mov_b32_dpp v71, v117 row_ror:2 row_mask:0xf bank_mask:0xf bound_ctrl:1
	v_pk_fma_f32 v[58:59], v[72:73], v[58:59], v[68:69]
	v_mov_b32_dpp v63, v113 row_shr:1 row_mask:0xf bank_mask:0xf
	v_pk_fma_f32 v[58:59], v[76:77], v[114:115], v[58:59]
	v_mov_b32_dpp v71, v113 row_shr:2 row_mask:0xf bank_mask:0xf
	v_pk_mul_f32 v[68:69], v[58:59], s[26:27] op_sel_hi:[1,0]
	v_lshlrev_b32_e32 v70, 16, v71
	v_med3_f32 v68, v68, s71, v224
	v_med3_f32 v69, v69, s71, v224
	v_pk_mul_f32 v[114:115], v[68:69], v[68:69]
	v_and_b32_e32 v71, 0xffff0000, v71
	v_pk_fma_f32 v[116:117], v[114:115], s[28:29], v[118:119] op_sel_hi:[1,0,0] neg_lo:[1,0,0] neg_hi:[1,0,0]
	v_pk_mul_f32 v[58:59], v[58:59], 0.5 op_sel_hi:[1,0]
	v_pk_fma_f32 v[116:117], v[114:115], v[116:117], s[34:35] op_sel_hi:[1,1,0]
	v_lshlrev_b32_e32 v62, 16, v63
	v_pk_fma_f32 v[116:117], v[114:115], v[116:117], s[36:37] op_sel_hi:[1,1,0]
	v_and_b32_e32 v63, 0xffff0000, v63
	v_pk_fma_f32 v[116:117], v[114:115], v[116:117], s[38:39] op_sel_hi:[1,1,0]
	v_mov_b32_dpp v1, v110 row_ror:1 row_mask:0xf bank_mask:0xf bound_ctrl:1
	v_pk_fma_f32 v[116:117], v[114:115], v[116:117], s[40:41] op_sel_hi:[1,1,0]
	s_nop 0
	v_pk_fma_f32 v[116:117], v[114:115], v[116:117], s[42:43] op_sel_hi:[1,1,0]
	v_mov_b32_dpp v1, v106 row_shr:1 row_mask:0xf bank_mask:0xf
	v_pk_fma_f32 v[114:115], v[114:115], v[116:117], s[44:45] op_sel_hi:[1,1,0]
	s_nop 0
	v_pk_mul_f32 v[68:69], v[68:69], v[114:115]
	s_nop 0
	v_pk_fma_f32 v[58:59], v[58:59], v[68:69], v[58:59]
	v_pk_fma_f32 v[68:69], v[66:67], v[70:71], v[82:83]
	v_pk_mul_f32 v[52:53], v[52:53], v[58:59]
	v_lshlrev_b32_e32 v58, 16, v113
	v_and_b32_e32 v59, 0xffff0000, v113
	v_pk_fma_f32 v[62:63], v[74:75], v[62:63], v[68:69]
	s_nop 0
	v_pk_fma_f32 v[58:59], v[78:79], v[58:59], v[62:63]
	s_nop 0
	v_pk_mul_f32 v[62:63], v[58:59], s[26:27] op_sel_hi:[1,0]
	v_pk_mul_f32 v[58:59], v[58:59], 0.5 op_sel_hi:[1,0]
	v_med3_f32 v62, v62, s71, v224
	v_med3_f32 v63, v63, s71, v224
	v_pk_mul_f32 v[68:69], v[62:63], v[62:63]
	s_nop 0
	v_pk_fma_f32 v[70:71], v[68:69], s[28:29], v[118:119] op_sel_hi:[1,0,0] neg_lo:[1,0,0] neg_hi:[1,0,0]
	s_nop 0
	v_pk_fma_f32 v[70:71], v[68:69], v[70:71], s[34:35] op_sel_hi:[1,1,0]
	s_nop 0
	v_pk_fma_f32 v[70:71], v[68:69], v[70:71], s[36:37] op_sel_hi:[1,1,0]
	s_nop 0
	v_pk_fma_f32 v[70:71], v[68:69], v[70:71], s[38:39] op_sel_hi:[1,1,0]
	s_nop 0
	v_pk_fma_f32 v[70:71], v[68:69], v[70:71], s[40:41] op_sel_hi:[1,1,0]
	s_nop 0
	v_pk_fma_f32 v[70:71], v[68:69], v[70:71], s[42:43] op_sel_hi:[1,1,0]
	s_nop 0
	v_pk_fma_f32 v[68:69], v[68:69], v[70:71], s[44:45] op_sel_hi:[1,1,0]
	s_nop 0
	v_pk_mul_f32 v[62:63], v[62:63], v[68:69]
	s_nop 0
	v_pk_fma_f32 v[58:59], v[58:59], v[62:63], v[58:59]
	v_lshlrev_b32_e32 v62, 16, v106
	v_pk_mul_f32 v[54:55], v[54:55], v[58:59]
	v_cvt_pk_bf16_f32 v58, v52, v53
	v_lshl_add_u64 v[52:53], v[176:177], 0, v[60:61]
	v_cvt_pk_bf16_f32 v59, v54, v55
	global_store_dwordx4 v[52:53], v[56:59], off
	v_lshlrev_b32_e32 v52, 16, v1
	v_and_b32_e32 v53, 0xffff0000, v1
; __device__ __forceinline__ unsigned cvt_pk_bf16(float lo, float hi) { unsigned r; asm volatile("v_cvt_pk_bf16_f32 %0, %1, %2" : "=v"(r) : "v"(lo), "v"(hi)); return r; }
;     static __device__ __forceinline__ void unpk4(const u32x2 w, float (&o)[4]) { o[0] = bf_lo(w.x); o[1] = bf_hi(w.x); o[2] = bf_lo(w.y); o[3] = bf_hi(w.y); }
;     template <int N> static __device__ __forceinline__ u32x2 dpp_prev(const u32x2 pv, const u32x2 cur) { u32x2 r; r.x = dpp_prev1<N>(pv.x, cur.x); r.y = dpp_prev1<N>(pv.y, cur.y); return r; }
;     static __device__ __forceinline__ u32x2 finish2(const float (&g0)[4], const float (&g1)[4], const float (&g2)[4], const float (&w0)[4], const float (&w1)[4], const float (&w2)[4], const float (&bb)[4],
;                                                     const f32x4 v, float rs) {
;         float h[4];
; #pragma unroll
;         for (int j = 0; j < 4; j += 2) {
;             const f32x2 gc = (f32x2){bb[j] + w0[j] * g2[j] + w1[j] * g1[j] + w2[j] * g0[j], bb[j + 1] + w0[j + 1] * g2[j + 1] + w1[j + 1] * g1[j + 1] + w2[j + 1] * g0[j + 1]};
;             const f32x2 ge = gelu_pk(gc) * ((f32x2){v[j], v[j + 1]} * rs); h[j] = ge.x; h[j + 1] = ge.y; }
;         u32x2 w; w.x = cvt_pk_bf16(h[0], h[1]); w.y = cvt_pk_bf16(h[2], h[3]); return w;
;     }
;     __device__ __forceinline__ void operator()(const f32x4 (&acc)[2][2][4][2], const Unit& u, int wr, int wc, int fr, int fq) const {
;     ...
; #pragma unroll
;                 for (int m = 0; m < 4; ++m) { const u32x4 cur = gq[m]; u32x4 hw;
; #pragma unroll
;                     for (int hv = 0; hv < 2; ++hv) { const u32x2 c2 = half2(cur, hv), p2 = half2(pv, hv);
;                         const u32x2 q1 = dpp_prev<1>(p2, c2), q2 = dpp_prev<2>(p2, c2);
;                         float g0[4], g1[4], g2[4]; unpk4(c2, g0); unpk4(q1, g1); unpk4(q2, g2);
;                         const u32x2 r = finish2(g0, g1, g2, w0[hv], w1[hv], w2[hv], bb[hv], acc[ai][bj][m][hv], rs8[ai][m]);
;                         if (hv == 0) { hw.x = r.x; hw.y = r.y; } else { hw.z = r.x; hw.w = r.y; } }
;                     *(u32x4*)(H + (size_t)(R0 + fr + 16 * m) * 2816 + col8) = hw;
;                     pv = cur; } }
	v_mov_b32_dpp v57, v110 row_ror:2 row_mask:0xf bank_mask:0xf bound_ctrl:1
	v_and_b32_e32 v63, 0xffff0000, v106
	v_mov_b32_dpp v59, v111 row_ror:2 row_mask:0xf bank_mask:0xf bound_ctrl:1
	v_mov_b32_dpp v57, v106 row_shr:2 row_mask:0xf bank_mask:0xf
	v_lshlrev_b32_e32 v56, 16, v57
	v_and_b32_e32 v57, 0xffff0000, v57
	v_pk_fma_f32 v[56:57], v[84:85], v[56:57], v[96:97]
	v_mov_b32_dpp v55, v111 row_ror:1 row_mask:0xf bank_mask:0xf bound_ctrl:1
	v_pk_fma_f32 v[52:53], v[88:89], v[52:53], v[56:57]
	v_mov_b32_dpp v59, v107 row_shr:2 row_mask:0xf bank_mask:0xf
	v_pk_fma_f32 v[52:53], v[92:93], v[62:63], v[52:53]
	v_mov_b32_dpp v55, v107 row_shr:1 row_mask:0xf bank_mask:0xf
	v_pk_mul_f32 v[56:57], v[52:53], s[26:27] op_sel_hi:[1,0]
	v_lshlrev_b32_e32 v58, 16, v59
	v_med3_f32 v56, v56, s71, v224
	v_med3_f32 v57, v57, s71, v224
	v_pk_mul_f32 v[62:63], v[56:57], v[56:57]
	v_and_b32_e32 v59, 0xffff0000, v59
	v_pk_fma_f32 v[68:69], v[62:63], s[28:29], v[118:119] op_sel_hi:[1,0,0] neg_lo:[1,0,0] neg_hi:[1,0,0]
	v_pk_mul_f32 v[52:53], v[52:53], 0.5 op_sel_hi:[1,0]
	v_pk_fma_f32 v[68:69], v[62:63], v[68:69], s[34:35] op_sel_hi:[1,1,0]
	v_lshlrev_b32_e32 v54, 16, v55
	v_pk_fma_f32 v[68:69], v[62:63], v[68:69], s[36:37] op_sel_hi:[1,1,0]
	v_and_b32_e32 v55, 0xffff0000, v55
	v_pk_fma_f32 v[68:69], v[62:63], v[68:69], s[38:39] op_sel_hi:[1,1,0]
	v_mov_b32_dpp v1, v112 row_ror:1 row_mask:0xf bank_mask:0xf bound_ctrl:1
	v_pk_fma_f32 v[68:69], v[62:63], v[68:69], s[40:41] op_sel_hi:[1,1,0]
	s_nop 0
	v_pk_fma_f32 v[68:69], v[62:63], v[68:69], s[42:43] op_sel_hi:[1,1,0]
	v_mov_b32_dpp v1, v108 row_shr:1 row_mask:0xf bank_mask:0xf
	v_pk_fma_f32 v[62:63], v[62:63], v[68:69], s[44:45] op_sel_hi:[1,1,0]
	s_nop 0
	v_pk_mul_f32 v[56:57], v[56:57], v[62:63]
	s_nop 0
	v_pk_fma_f32 v[52:53], v[52:53], v[56:57], v[52:53]
	v_pk_fma_f32 v[56:57], v[86:87], v[58:59], v[98:99]
	v_pk_mul_f32 v[48:49], v[48:49], v[52:53]
	v_lshlrev_b32_e32 v52, 16, v107
	v_and_b32_e32 v53, 0xffff0000, v107
	v_pk_fma_f32 v[54:55], v[90:91], v[54:55], v[56:57]
	v_cvt_pk_bf16_f32 v48, v48, v49
	s_nop 0
	v_pk_fma_f32 v[52:53], v[94:95], v[52:53], v[54:55]
	s_nop 0
	v_pk_mul_f32 v[54:55], v[52:53], s[26:27] op_sel_hi:[1,0]
	v_pk_mul_f32 v[52:53], v[52:53], 0.5 op_sel_hi:[1,0]
	v_med3_f32 v54, v54, s71, v224
	v_med3_f32 v55, v55, s71, v224
	v_pk_mul_f32 v[56:57], v[54:55], v[54:55]
	s_nop 0
	v_pk_fma_f32 v[58:59], v[56:57], s[28:29], v[118:119] op_sel_hi:[1,0,0] neg_lo:[1,0,0] neg_hi:[1,0,0]
	s_nop 0
	v_pk_fma_f32 v[58:59], v[56:57], v[58:59], s[34:35] op_sel_hi:[1,1,0]
	s_nop 0
	v_pk_fma_f32 v[58:59], v[56:57], v[58:59], s[36:37] op_sel_hi:[1,1,0]
	s_nop 0
	v_pk_fma_f32 v[58:59], v[56:57], v[58:59], s[38:39] op_sel_hi:[1,1,0]
	s_nop 0
	v_pk_fma_f32 v[58:59], v[56:57], v[58:59], s[40:41] op_sel_hi:[1,1,0]
	s_nop 0
	v_pk_fma_f32 v[58:59], v[56:57], v[58:59], s[42:43] op_sel_hi:[1,1,0]
	s_nop 0
	v_pk_fma_f32 v[56:57], v[56:57], v[58:59], s[44:45] op_sel_hi:[1,1,0]
	v_lshlrev_b32_e32 v58, 16, v108
	v_pk_mul_f32 v[54:55], v[54:55], v[56:57]
	v_and_b32_e32 v59, 0xffff0000, v108
	v_pk_fma_f32 v[52:53], v[52:53], v[54:55], v[52:53]
	v_mov_b32_dpp v55, v112 row_ror:2 row_mask:0xf bank_mask:0xf bound_ctrl:1
	v_pk_mul_f32 v[50:51], v[50:51], v[52:53]
	v_mov_b32_dpp v57, v113 row_ror:2 row_mask:0xf bank_mask:0xf bound_ctrl:1
	v_mov_b32_dpp v55, v108 row_shr:2 row_mask:0xf bank_mask:0xf
	v_lshlrev_b32_e32 v54, 16, v55
	v_and_b32_e32 v55, 0xffff0000, v55
	v_cvt_pk_bf16_f32 v49, v50, v51
	v_lshlrev_b32_e32 v50, 16, v1
	v_and_b32_e32 v51, 0xffff0000, v1
	v_pk_fma_f32 v[54:55], v[64:65], v[54:55], v[80:81]
	v_mov_b32_dpp v53, v113 row_ror:1 row_mask:0xf bank_mask:0xf bound_ctrl:1
	v_pk_fma_f32 v[50:51], v[72:73], v[50:51], v[54:55]
	v_mov_b32_dpp v57, v109 row_shr:2 row_mask:0xf bank_mask:0xf
	v_pk_fma_f32 v[50:51], v[76:77], v[58:59], v[50:51]
	v_mov_b32_dpp v53, v109 row_shr:1 row_mask:0xf bank_mask:0xf
	v_pk_mul_f32 v[54:55], v[50:51], s[26:27] op_sel_hi:[1,0]
	v_lshlrev_b32_e32 v56, 16, v57
	v_med3_f32 v54, v54, s71, v224
	v_med3_f32 v55, v55, s71, v224
	v_pk_mul_f32 v[58:59], v[54:55], v[54:55]
	v_and_b32_e32 v57, 0xffff0000, v57
	v_pk_fma_f32 v[62:63], v[58:59], s[28:29], v[118:119] op_sel_hi:[1,0,0] neg_lo:[1,0,0] neg_hi:[1,0,0]
	v_pk_mul_f32 v[50:51], v[50:51], 0.5 op_sel_hi:[1,0]
	v_pk_fma_f32 v[62:63], v[58:59], v[62:63], s[34:35] op_sel_hi:[1,1,0]
	v_lshlrev_b32_e32 v52, 16, v53
	v_pk_fma_f32 v[62:63], v[58:59], v[62:63], s[36:37] op_sel_hi:[1,1,0]
	v_and_b32_e32 v53, 0xffff0000, v53
	v_pk_fma_f32 v[62:63], v[58:59], v[62:63], s[38:39] op_sel_hi:[1,1,0]
	v_mov_b32_dpp v1, v106 row_ror:1 row_mask:0xf bank_mask:0xf bound_ctrl:1
	v_pk_fma_f32 v[62:63], v[58:59], v[62:63], s[40:41] op_sel_hi:[1,1,0]
	s_nop 0
	v_pk_fma_f32 v[62:63], v[58:59], v[62:63], s[42:43] op_sel_hi:[1,1,0]
	v_mov_b32_dpp v1, v102 row_shr:1 row_mask:0xf bank_mask:0xf
	v_pk_fma_f32 v[58:59], v[58:59], v[62:63], s[44:45] op_sel_hi:[1,1,0]
	s_nop 0
	v_pk_mul_f32 v[54:55], v[54:55], v[58:59]
	s_nop 0
	v_pk_fma_f32 v[50:51], v[50:51], v[54:55], v[50:51]
	v_pk_fma_f32 v[54:55], v[66:67], v[56:57], v[82:83]
	v_pk_mul_f32 v[44:45], v[44:45], v[50:51]
	v_lshlrev_b32_e32 v50, 16, v109
	v_and_b32_e32 v51, 0xffff0000, v109
	v_pk_fma_f32 v[52:53], v[74:75], v[52:53], v[54:55]
	s_nop 0
	v_pk_fma_f32 v[50:51], v[78:79], v[50:51], v[52:53]
	s_nop 0
	v_pk_mul_f32 v[52:53], v[50:51], s[26:27] op_sel_hi:[1,0]
	v_pk_mul_f32 v[50:51], v[50:51], 0.5 op_sel_hi:[1,0]
	v_med3_f32 v52, v52, s71, v224
	v_med3_f32 v53, v53, s71, v224
	v_pk_mul_f32 v[54:55], v[52:53], v[52:53]
	s_nop 0
	v_pk_fma_f32 v[56:57], v[54:55], s[28:29], v[118:119] op_sel_hi:[1,0,0] neg_lo:[1,0,0] neg_hi:[1,0,0]
; __device__ __forceinline__ unsigned cvt_pk_bf16(float lo, float hi) { unsigned r; asm volatile("v_cvt_pk_bf16_f32 %0, %1, %2" : "=v"(r) : "v"(lo), "v"(hi)); return r; }
;     static __device__ __forceinline__ void unpk4(const u32x2 w, float (&o)[4]) { o[0] = bf_lo(w.x); o[1] = bf_hi(w.x); o[2] = bf_lo(w.y); o[3] = bf_hi(w.y); }
;     template <int N> static __device__ __forceinline__ u32x2 dpp_prev(const u32x2 pv, const u32x2 cur) { u32x2 r; r.x = dpp_prev1<N>(pv.x, cur.x); r.y = dpp_prev1<N>(pv.y, cur.y); return r; }
;     static __device__ __forceinline__ u32x2 finish2(const float (&g0)[4], const float (&g1)[4], const float (&g2)[4], const float (&w0)[4], const float (&w1)[4], const float (&w2)[4], const float (&bb)[4],
;                                                     const f32x4 v, float rs) {
;         float h[4];
; #pragma unroll
;         for (int j = 0; j < 4; j += 2) {
;             const f32x2 gc = (f32x2){bb[j] + w0[j] * g2[j] + w1[j] * g1[j] + w2[j] * g0[j], bb[j + 1] + w0[j + 1] * g2[j + 1] + w1[j + 1] * g1[j + 1] + w2[j + 1] * g0[j + 1]};
;             const f32x2 ge = gelu_pk(gc) * ((f32x2){v[j], v[j + 1]} * rs); h[j] = ge.x; h[j + 1] = ge.y; }
;         u32x2 w; w.x = cvt_pk_bf16(h[0], h[1]); w.y = cvt_pk_bf16(h[2], h[3]); return w;
;     }
;     __device__ __forceinline__ void operator()(const f32x4 (&acc)[2][2][4][2], const Unit& u, int wr, int wc, int fr, int fq) const {
;     ...
; #pragma unroll
;                 for (int m = 0; m < 4; ++m) { const u32x4 cur = gq[m]; u32x4 hw;
; #pragma unroll
;                     for (int hv = 0; hv < 2; ++hv) { const u32x2 c2 = half2(cur, hv), p2 = half2(pv, hv);
;                         const u32x2 q1 = dpp_prev<1>(p2, c2), q2 = dpp_prev<2>(p2, c2);
;                         float g0[4], g1[4], g2[4]; unpk4(c2, g0); unpk4(q1, g1); unpk4(q2, g2);
;                         const u32x2 r = finish2(g0, g1, g2, w0[hv], w1[hv], w2[hv], bb[hv], acc[ai][bj][m][hv], rs8[ai][m]);
;                         if (hv == 0) { hw.x = r.x; hw.y = r.y; } else { hw.z = r.x; hw.w = r.y; } }
;                     *(u32x4*)(H + (size_t)(R0 + fr + 16 * m) * 2816 + col8) = hw;
;                     pv = cur; } }
	s_nop 0
	v_pk_fma_f32 v[56:57], v[54:55], v[56:57], s[34:35] op_sel_hi:[1,1,0]
	s_nop 0
	v_pk_fma_f32 v[56:57], v[54:55], v[56:57], s[36:37] op_sel_hi:[1,1,0]
	s_nop 0
	v_pk_fma_f32 v[56:57], v[54:55], v[56:57], s[38:39] op_sel_hi:[1,1,0]
	s_nop 0
	v_pk_fma_f32 v[56:57], v[54:55], v[56:57], s[40:41] op_sel_hi:[1,1,0]
	s_nop 0
	v_pk_fma_f32 v[56:57], v[54:55], v[56:57], s[42:43] op_sel_hi:[1,1,0]
	s_nop 0
	v_pk_fma_f32 v[54:55], v[54:55], v[56:57], s[44:45] op_sel_hi:[1,1,0]
	v_lshl_add_u64 v[56:57], v[166:167], 0, v[60:61]
	v_pk_mul_f32 v[52:53], v[52:53], v[54:55]
	s_nop 0
	v_pk_fma_f32 v[50:51], v[50:51], v[52:53], v[50:51]
	v_lshlrev_b32_e32 v52, 16, v102
	v_pk_mul_f32 v[46:47], v[46:47], v[50:51]
	v_cvt_pk_bf16_f32 v50, v44, v45
	v_lshl_add_u64 v[44:45], v[172:173], 0, v[60:61]
	v_cvt_pk_bf16_f32 v51, v46, v47
	global_store_dwordx4 v[44:45], v[48:51], off
	v_lshlrev_b32_e32 v44, 16, v1
	v_and_b32_e32 v45, 0xffff0000, v1
	v_mov_b32_dpp v49, v106 row_ror:2 row_mask:0xf bank_mask:0xf bound_ctrl:1
	v_and_b32_e32 v53, 0xffff0000, v102
	v_mov_b32_dpp v51, v107 row_ror:2 row_mask:0xf bank_mask:0xf bound_ctrl:1
	v_mov_b32_dpp v49, v102 row_shr:2 row_mask:0xf bank_mask:0xf
	v_lshlrev_b32_e32 v48, 16, v49
	v_and_b32_e32 v49, 0xffff0000, v49
	v_pk_fma_f32 v[48:49], v[84:85], v[48:49], v[96:97]
	v_mov_b32_dpp v47, v107 row_ror:1 row_mask:0xf bank_mask:0xf bound_ctrl:1
	v_pk_fma_f32 v[44:45], v[88:89], v[44:45], v[48:49]
	v_mov_b32_dpp v51, v103 row_shr:2 row_mask:0xf bank_mask:0xf
	v_pk_fma_f32 v[44:45], v[92:93], v[52:53], v[44:45]
	v_mov_b32_dpp v47, v103 row_shr:1 row_mask:0xf bank_mask:0xf
	v_pk_mul_f32 v[48:49], v[44:45], s[26:27] op_sel_hi:[1,0]
	v_lshlrev_b32_e32 v50, 16, v51
	v_med3_f32 v48, v48, s71, v224
	v_med3_f32 v49, v49, s71, v224
	v_pk_mul_f32 v[52:53], v[48:49], v[48:49]
	v_and_b32_e32 v51, 0xffff0000, v51
	v_pk_fma_f32 v[54:55], v[52:53], s[28:29], v[118:119] op_sel_hi:[1,0,0] neg_lo:[1,0,0] neg_hi:[1,0,0]
	v_pk_mul_f32 v[44:45], v[44:45], 0.5 op_sel_hi:[1,0]
	v_pk_fma_f32 v[54:55], v[52:53], v[54:55], s[34:35] op_sel_hi:[1,1,0]
	v_lshlrev_b32_e32 v46, 16, v47
	v_pk_fma_f32 v[54:55], v[52:53], v[54:55], s[36:37] op_sel_hi:[1,1,0]
	v_and_b32_e32 v47, 0xffff0000, v47
	v_pk_fma_f32 v[54:55], v[52:53], v[54:55], s[38:39] op_sel_hi:[1,1,0]
	v_mov_b32_dpp v1, v108 row_ror:1 row_mask:0xf bank_mask:0xf bound_ctrl:1
	v_pk_fma_f32 v[54:55], v[52:53], v[54:55], s[40:41] op_sel_hi:[1,1,0]
	v_mov_b32_e32 v102, 0
	v_pk_fma_f32 v[54:55], v[52:53], v[54:55], s[42:43] op_sel_hi:[1,1,0]
	v_mov_b32_dpp v1, v104 row_shr:1 row_mask:0xf bank_mask:0xf
	v_pk_fma_f32 v[52:53], v[52:53], v[54:55], s[44:45] op_sel_hi:[1,1,0]
	s_nop 0
	v_pk_mul_f32 v[48:49], v[48:49], v[52:53]
	s_nop 0
	v_pk_fma_f32 v[44:45], v[44:45], v[48:49], v[44:45]
	v_pk_fma_f32 v[48:49], v[86:87], v[50:51], v[98:99]
	v_pk_mul_f32 v[40:41], v[40:41], v[44:45]
	v_lshlrev_b32_e32 v44, 16, v103
	v_and_b32_e32 v45, 0xffff0000, v103
	v_pk_fma_f32 v[46:47], v[90:91], v[46:47], v[48:49]
	v_cvt_pk_bf16_f32 v52, v40, v41
	v_lshlrev_b32_e32 v40, 16, v1
	v_pk_fma_f32 v[44:45], v[94:95], v[44:45], v[46:47]
	v_and_b32_e32 v41, 0xffff0000, v1
	v_pk_mul_f32 v[46:47], v[44:45], s[26:27] op_sel_hi:[1,0]
	v_pk_mul_f32 v[44:45], v[44:45], 0.5 op_sel_hi:[1,0]
	v_med3_f32 v46, v46, s71, v224
	v_med3_f32 v47, v47, s71, v224
	v_pk_mul_f32 v[48:49], v[46:47], v[46:47]
	v_mov_b32_e32 v103, 0
	v_pk_fma_f32 v[50:51], v[48:49], s[28:29], v[118:119] op_sel_hi:[1,0,0] neg_lo:[1,0,0] neg_hi:[1,0,0]
	s_nop 0
	v_pk_fma_f32 v[50:51], v[48:49], v[50:51], s[34:35] op_sel_hi:[1,1,0]
	s_nop 0
	v_pk_fma_f32 v[50:51], v[48:49], v[50:51], s[36:37] op_sel_hi:[1,1,0]
	s_nop 0
	v_pk_fma_f32 v[50:51], v[48:49], v[50:51], s[38:39] op_sel_hi:[1,1,0]
	s_nop 0
	v_pk_fma_f32 v[50:51], v[48:49], v[50:51], s[40:41] op_sel_hi:[1,1,0]
	s_nop 0
	v_pk_fma_f32 v[50:51], v[48:49], v[50:51], s[42:43] op_sel_hi:[1,1,0]
	s_nop 0
	v_pk_fma_f32 v[48:49], v[48:49], v[50:51], s[44:45] op_sel_hi:[1,1,0]
	s_nop 0
;     static __device__ __forceinline__ void unpk4(const u32x2 w, float (&o)[4]) { o[0] = bf_lo(w.x); o[1] = bf_hi(w.x); o[2] = bf_lo(w.y); o[3] = bf_hi(w.y); }
;     template <int N> static __device__ __forceinline__ u32x2 dpp_prev(const u32x2 pv, const u32x2 cur) { u32x2 r; r.x = dpp_prev1<N>(pv.x, cur.x); r.y = dpp_prev1<N>(pv.y, cur.y); return r; }
;     __device__ __forceinline__ void operator()(const f32x4 (&acc)[2][2][4][2], const Unit& u, int wr, int wc, int fr, int fq) const {
;     ...
;             for (int ai = 0; ai < 2; ++ai) { const int R0 = u.rb + ai * HALF + wr * 64; const bf16_t* gp = G + (size_t)(R0 + fr) * 2816 + col8;
;                 u32x4 gq[4], prv = (u32x4){0u, 0u, 0u, 0u};
; #pragma unroll
;                 for (int m = 0; m < 4; ++m) gq[m] = *(const u32x4*)(gp + (size_t)m * 16 * 2816);
;                 if ((R0 & 8191) != 0) prv = *(const u32x4*)(gp - (size_t)16 * 2816);
;                 u32x4 pv = prv;
; #pragma unroll
;                 for (int m = 0; m < 4; ++m) { const u32x4 cur = gq[m]; u32x4 hw;
; #pragma unroll
;                     for (int hv = 0; hv < 2; ++hv) { const u32x2 c2 = half2(cur, hv), p2 = half2(pv, hv);
;                         const u32x2 q1 = dpp_prev<1>(p2, c2), q2 = dpp_prev<2>(p2, c2);
;                         float g0[4], g1[4], g2[4]; unpk4(c2, g0); unpk4(q1, g1); unpk4(q2, g2);
;                         const u32x2 r = finish2(g0, g1, g2, w0[hv], w1[hv], w2[hv], bb[hv], acc[ai][bj][m][hv], rs8[ai][m]);
;                         if (hv == 0) { hw.x = r.x; hw.y = r.y; } else { hw.z = r.x; hw.w = r.y; } }
;                     *(u32x4*)(H + (size_t)(R0 + fr + 16 * m) * 2816 + col8) = hw;
;                     pv = cur; } }
	v_pk_mul_f32 v[46:47], v[46:47], v[48:49]
	v_lshlrev_b32_e32 v48, 16, v104
	v_pk_fma_f32 v[44:45], v[44:45], v[46:47], v[44:45]
	v_and_b32_e32 v49, 0xffff0000, v104
	v_pk_mul_f32 v[42:43], v[42:43], v[44:45]
	v_mov_b32_dpp v45, v108 row_ror:2 row_mask:0xf bank_mask:0xf bound_ctrl:1
	v_mov_b32_dpp v47, v109 row_ror:2 row_mask:0xf bank_mask:0xf bound_ctrl:1
	v_cvt_pk_bf16_f32 v53, v42, v43
	v_mov_b32_dpp v43, v109 row_ror:1 row_mask:0xf bank_mask:0xf bound_ctrl:1
	v_mov_b32_dpp v45, v104 row_shr:2 row_mask:0xf bank_mask:0xf
	v_lshlrev_b32_e32 v44, 16, v45
	v_and_b32_e32 v45, 0xffff0000, v45
	v_pk_fma_f32 v[44:45], v[64:65], v[44:45], v[80:81]
	v_mov_b32_dpp v47, v105 row_shr:2 row_mask:0xf bank_mask:0xf
	v_pk_fma_f32 v[40:41], v[72:73], v[40:41], v[44:45]
	v_mov_b32_dpp v43, v105 row_shr:1 row_mask:0xf bank_mask:0xf
	v_pk_fma_f32 v[40:41], v[76:77], v[48:49], v[40:41]
	v_lshlrev_b32_e32 v46, 16, v47
	v_pk_mul_f32 v[44:45], v[40:41], s[26:27] op_sel_hi:[1,0]
	v_and_b32_e32 v47, 0xffff0000, v47
	v_med3_f32 v44, v44, s71, v224
	v_med3_f32 v45, v45, s71, v224
	v_pk_mul_f32 v[48:49], v[44:45], v[44:45]
	v_pk_mul_f32 v[40:41], v[40:41], 0.5 op_sel_hi:[1,0]
	v_pk_fma_f32 v[50:51], v[48:49], s[28:29], v[118:119] op_sel_hi:[1,0,0] neg_lo:[1,0,0] neg_hi:[1,0,0]
	v_lshlrev_b32_e32 v42, 16, v43
	v_pk_fma_f32 v[50:51], v[48:49], v[50:51], s[34:35] op_sel_hi:[1,1,0]
	v_and_b32_e32 v43, 0xffff0000, v43
	v_pk_fma_f32 v[50:51], v[48:49], v[50:51], s[36:37] op_sel_hi:[1,1,0]
	s_nop 0
	v_pk_fma_f32 v[50:51], v[48:49], v[50:51], s[38:39] op_sel_hi:[1,1,0]
	s_nop 0
	v_pk_fma_f32 v[50:51], v[48:49], v[50:51], s[40:41] op_sel_hi:[1,1,0]
	s_nop 0
	v_pk_fma_f32 v[50:51], v[48:49], v[50:51], s[42:43] op_sel_hi:[1,1,0]
	s_nop 0
	v_pk_fma_f32 v[48:49], v[48:49], v[50:51], s[44:45] op_sel_hi:[1,1,0]
	s_nop 0
	v_pk_mul_f32 v[44:45], v[44:45], v[48:49]
	s_nop 0
	v_pk_fma_f32 v[40:41], v[40:41], v[44:45], v[40:41]
	v_pk_fma_f32 v[44:45], v[66:67], v[46:47], v[82:83]
	v_pk_mul_f32 v[36:37], v[36:37], v[40:41]
	v_lshlrev_b32_e32 v40, 16, v105
	v_and_b32_e32 v41, 0xffff0000, v105
	v_pk_fma_f32 v[42:43], v[74:75], v[42:43], v[44:45]
	v_cvt_pk_bf16_f32 v54, v36, v37
	s_nop 0
	v_pk_fma_f32 v[40:41], v[78:79], v[40:41], v[42:43]
	s_nop 0
	v_pk_mul_f32 v[42:43], v[40:41], s[26:27] op_sel_hi:[1,0]
	v_pk_mul_f32 v[40:41], v[40:41], 0.5 op_sel_hi:[1,0]
	v_med3_f32 v42, v42, s71, v224
	v_med3_f32 v43, v43, s71, v224
	v_pk_mul_f32 v[44:45], v[42:43], v[42:43]
	s_nop 0
	v_pk_fma_f32 v[46:47], v[44:45], s[28:29], v[118:119] op_sel_hi:[1,0,0] neg_lo:[1,0,0] neg_hi:[1,0,0]
	s_nop 0
	v_pk_fma_f32 v[46:47], v[44:45], v[46:47], s[34:35] op_sel_hi:[1,1,0]
	s_nop 0
	v_pk_fma_f32 v[46:47], v[44:45], v[46:47], s[36:37] op_sel_hi:[1,1,0]
	s_nop 0
	v_pk_fma_f32 v[46:47], v[44:45], v[46:47], s[38:39] op_sel_hi:[1,1,0]
	s_nop 0
	v_pk_fma_f32 v[46:47], v[44:45], v[46:47], s[40:41] op_sel_hi:[1,1,0]
	s_nop 0
	v_pk_fma_f32 v[46:47], v[44:45], v[46:47], s[42:43] op_sel_hi:[1,1,0]
	s_nop 0
	v_pk_fma_f32 v[44:45], v[44:45], v[46:47], s[44:45] op_sel_hi:[1,1,0]
	s_nop 0
	v_pk_mul_f32 v[42:43], v[42:43], v[44:45]
	s_nop 0
	v_pk_fma_f32 v[40:41], v[40:41], v[42:43], v[40:41]
	s_nop 0
	v_pk_mul_f32 v[2:3], v[2:3], v[40:41]
	s_nop 0
	v_cvt_pk_bf16_f32 v55, v2, v3
	v_lshl_add_u64 v[2:3], v[164:165], 0, v[60:61]
	v_add_co_u32_e32 v36, vcc, s45, v2
	s_nop 1
	v_addc_co_u32_e32 v37, vcc, 0, v3, vcc
	global_load_dwordx4 v[48:51], v[2:3], off nt
	global_load_dwordx4 v[44:47], v[36:37], off nt
	v_add_co_u32_e32 v36, vcc, 0x2c000, v2
	s_nop 1
	v_addc_co_u32_e32 v37, vcc, 0, v3, vcc
	v_add_co_u32_e32 v38, vcc, 0x42000, v2
	s_nop 1
	v_addc_co_u32_e32 v39, vcc, 0, v3, vcc
	global_load_dwordx4 v[40:43], v[36:37], off nt
	s_nop 0
	global_load_dwordx4 v[36:39], v[38:39], off nt
	s_andn2_b64 vcc, exec, s[8:9]
	global_store_dwordx4 v[56:57], v[52:55], off
	s_cbranch_vccnz .LBB0_3152
	v_add_co_u32_e32 v2, vcc, 0xfffea000, v2
	s_nop 1
	v_addc_co_u32_e32 v3, vcc, -1, v3, vcc
	global_load_dwordx4 v[100:103], v[2:3], off nt
